# placement trial: NA, FFN-out and FFN-in loops moved to a byte phase equal to the baseline's modulo 8
# baseline (speedup 1.0000x reference)
; #define LAS __attribute__((address_space(3)))
; template <int KIND> ...
;     ...
;         int base1 = b * 4096, n1 = 64, kr_lo = 0, rs_w = 0, qr = 0, qc = 0, cs = 0;
;         if (KIND == 0) { const int r0 = qb * 4; kr_lo = min(max(r0 - 4, 0), 56); const int kr_hi = min(max(r0 - 1, 0), 56) + 8; base1 += kr_lo * 64; n1 = kr_hi - kr_lo;
;             qr = r0 + (wid >> 1); rs_w = min(max(qr - 4, 0), 56); qc = 32 * (wid & 1) + l32; cs = min(max(qc - 8, 0), 48); }
;         if (isctx) n1 = 0;
;         const int base2 = M_LAT + b * 256, nt = n1 + 4;
;         bf16x8 qf[4];
;         { const bf16_t* qp = qkv + (size_t)(qrow0 + qoff + l32) * N + hq * 64 + 8 * hi;
; #pragma unroll
;           for (int t = 0; t < 4; ++t) qf[t] = *(const bf16x8*)(qp + 16 * t); }
;         if (KIND == 0 && !isctx) { LAS float* bt = (LAS float*)(lds + OFF_BIAS); for (int i = tid; i < 465; i += NTHREADS) bt[i] = rpb[h * 465 + i] * LOG2E; }
;         u32x4 kreg[NK], vreg[NVC];
;         const int krow_l = tid >> 3, kpart = tid & 7;
;     ...
;         float m_ref = 0.f; int first = 1;
;         f32x16 o[NDT], lacc, mneg;
; #pragma unroll
;         for (int dt = 0; dt < NDT; ++dt)
; #pragma unroll
;             for (int j = 0; j < 16; ++j) o[dt][j] = 0.f;
; #pragma unroll
;         for (int j = 0; j < 16; ++j) { lacc[j] = 0.f; mneg[j] = 0.f; }
;         const bf16x8 ones = {(short)0x3F80, (short)0x3F80, (short)0x3F80, (short)0x3F80, (short)0x3F80, (short)0x3F80, (short)0x3F80, (short)0x3F80};
;         ATT_LOAD(0); ATT_STORE(0); __syncthreads();
;         const int koff = kidx * KT + l32 * KSTR + 16 * hi;
;         const int voff = OFF_V + (4 * hi + ((lane & 15) >> 2)) * VSTR + (16 * ((lane >> 4) & 1) + 4 * (lane & 3)) * 2;
;         const int wb = 4 * hi - cs;
;         const int boff0 = OFF_BIAS + 4 * (cs - qc + 15 + wb);
;         for (int t = 0; t < nt; ++t) {
.LBB0_143:
	s_or_b64 exec, exec, s[82:83]
	s_lshl_b32 s75, s81, 2
	v_sub_u32_e64 v0, s75, 1 clamp
	s_max_u32 s90, s75, 4
	v_readfirstlane_b32 s10, v0
	s_min_u32 s10, s10, 56
	s_lshl_b32 s8, s74, 6
	s_lshl_b32 s2, s2, 8
	s_sub_i32 s10, s10, s90
	s_add_i32 s9, s8, 0x800
	s_add_i32 s2, s2, 0x8000
	s_add_i32 s10, s10, 12
	s_and_b64 s[76:77], exec, s[78:79]
	s_cselect_b32 s80, 0, s10
	s_lshl_b32 s10, s80, 6
	v_sub_u32_e64 v4, s75, 4 clamp
	s_sub_i32 s10, s2, s10
	v_lshlrev_b32_e32 v0, 6, v4
	s_cmp_gt_i32 s80, 0
	v_add_u32_e32 v0, s5, v0
	v_mov_b32_e32 v1, s10
	s_cselect_b64 vcc, -1, 0
	v_readlane_b32 s10, v255, 5
	v_cndmask_b32_e32 v5, v1, v0, vcc
	v_readlane_b32 s11, v255, 6
	v_add_u32_e32 v2, v5, v208
	v_add_u32_e32 v5, v5, v209
	v_mov_b64_e32 v[0:1], s[10:11]
	s_movk_i32 s10, 0x1800
	v_mad_i64_i32 v[2:3], s[76:77], v2, s10, v[0:1]
	s_lshl_b32 s96, s8, 1
	v_mad_i64_i32 v[0:1], s[76:77], v5, s10, v[0:1]
	v_lshl_add_u64 v[2:3], v[2:3], 0, s[96:97]
	s_lshl_b32 s76, s9, 1
	s_mov_b32 s77, s97
	v_lshl_add_u64 v[2:3], v[2:3], 0, v[192:193]
	v_lshl_add_u64 v[0:1], v[0:1], 0, s[76:77]
	v_lshl_add_u64 v[0:1], v[154:155], 1, v[0:1]
	global_load_dwordx4 v[128:131], v[2:3], off offset:2048
	global_load_dwordx4 v[132:135], v[0:1], off
	v_readfirstlane_b32 s74, v4
	s_cmp_lt_i32 s80, -3
	s_mov_b32 s83, 0
	s_waitcnt vmcnt(1)
	ds_write_b128 v210, v[128:131]
	s_waitcnt vmcnt(0)
	ds_write_b128 v211, v[132:135] offset:18432
	s_waitcnt lgkmcnt(0)
	s_barrier
	s_cbranch_scc1 .LBB0_166
	v_readlane_b32 s8, v255, 41
	s_add_i32 s75, s75, s8
	s_max_i32 s8, s75, 4
	s_add_i32 s8, s8, -4
	s_min_u32 s75, s8, 56
	s_mulk_i32 s90, 0x7c
	s_mul_i32 s8, s81, 0x1f0
	v_mov_b32_e32 v46, v193
	v_mov_b32_e32 v47, v193
	s_sub_i32 s8, s90, s8
	v_mov_b32_e32 v32, v193
	v_mov_b32_e32 v33, v193
	v_mov_b32_e32 v34, v193
	v_mov_b32_e32 v35, v193
	v_mov_b32_e32 v36, v193
	v_mov_b32_e32 v37, v193
	v_mov_b32_e32 v38, v193
	v_mov_b32_e32 v39, v193
	v_mov_b32_e32 v40, v193
	v_mov_b32_e32 v41, v193
	v_mov_b32_e32 v42, v193
	v_mov_b32_e32 v43, v193
	v_mov_b32_e32 v44, v193
	v_mov_b32_e32 v45, v193
	v_mov_b32_e32 v16, 0
	v_mov_b64_e32 v[62:63], v[46:47]
	s_add_i32 s95, s80, 4
	s_mov_b32 s82, 1
	v_lshl_add_u64 v[202:203], v[156:157], 0, s[96:97]
	v_lshl_add_u64 v[204:205], v[158:159], 0, s[76:77]
	s_add_i32 s76, s75, 8
	s_sub_i32 s77, 0, s80
	v_add_u32_e32 v237, s8, v235
	v_mov_b64_e32 v[60:61], v[44:45]
	v_mov_b64_e32 v[58:59], v[42:43]
	v_mov_b64_e32 v[56:57], v[40:41]
	v_mov_b64_e32 v[54:55], v[38:39]
	v_mov_b64_e32 v[52:53], v[36:37]
	v_mov_b64_e32 v[50:51], v[34:35]
	v_mov_b64_e32 v[48:49], v[32:33]
	v_mov_b32_e32 v17, v16
	v_mov_b32_e32 v18, v16
	v_mov_b32_e32 v19, v16
	v_mov_b32_e32 v20, v16
	v_mov_b32_e32 v21, v16
	v_mov_b32_e32 v22, v16
	v_mov_b32_e32 v23, v16
	v_mov_b32_e32 v24, v16
	v_mov_b32_e32 v25, v16
	v_mov_b32_e32 v26, v16
	v_mov_b32_e32 v27, v16
	v_mov_b32_e32 v28, v16
	v_mov_b32_e32 v29, v16
	v_mov_b32_e32 v30, v16
	v_mov_b32_e32 v31, v16
	v_mov_b32_e32 v0, v16
	v_mov_b32_e32 v1, v16
	v_mov_b32_e32 v2, v16
	v_mov_b32_e32 v3, v16
	v_mov_b32_e32 v4, v16
	v_mov_b32_e32 v5, v16
	v_mov_b32_e32 v6, v16
	v_mov_b32_e32 v7, v16
	v_mov_b32_e32 v8, v16
	v_mov_b32_e32 v9, v16
	v_mov_b32_e32 v10, v16
	v_mov_b32_e32 v11, v16
	v_mov_b32_e32 v12, v16
	v_mov_b32_e32 v13, v16
	v_mov_b32_e32 v14, v16
	v_mov_b32_e32 v15, v16
	v_readlane_b32 s8, v255, 22
	s_nop 0
	s_nop 0
	s_bitcmp1_b32 s8, 0
	s_cbranch_scc1 nap1_145

; template <int KIND> ...
;     ...
;         f32x16 o[NDT], lacc, mneg;
; #pragma unroll
;         for (int dt = 0; dt < NDT; ++dt)
; #pragma unroll
;             for (int j = 0; j < 16; ++j) o[dt][j] = 0.f;
; #pragma unroll
;         for (int j = 0; j < 16; ++j) { lacc[j] = 0.f; mneg[j] = 0.f; }
;     ...
;         for (int t = 0; t < nt; ++t) {
nap1_164:
	s_cmp_eq_u32 s95, s81
	v_add_u32_e32 v237, 0x7c, v237
	s_waitcnt lgkmcnt(0)
	s_barrier
	s_cbranch_scc1 .LBB0_125
	s_mov_b32 s83, s81
	s_branch nap1_145
	s_nop 0
	s_nop 0
	s_nop 0
	s_nop 0
	s_nop 0
	s_nop 0
	s_nop 0
	s_nop 0
	s_nop 0
	s_nop 0
	s_nop 0
	s_nop 0
	s_nop 0
	s_nop 0
	s_nop 0
	s_nop 0
	s_nop 0
	s_nop 0
	s_nop 0
	s_nop 0
	s_nop 0
	s_nop 0
	s_nop 0
	s_nop 0
	s_nop 0
	s_nop 0
	s_nop 0
	s_nop 0
	s_nop 0
	s_nop 0
	s_nop 0
	s_nop 0
	s_nop 0
	s_nop 0
	s_nop 0
	s_nop 0
	s_nop 0
	s_nop 0
	s_nop 0
	s_nop 0
	s_nop 0
	s_nop 0
	s_nop 0
	s_nop 0
	s_nop 0
	s_nop 0
	s_nop 0
	s_nop 0
	s_nop 0
	s_nop 0
	s_nop 0
	s_nop 0
	s_nop 0
	s_nop 0
	s_nop 0
	s_nop 0
	s_nop 0
	s_nop 0
	s_nop 0
	s_nop 0
	s_nop 0
	s_nop 0
	s_nop 0
	s_nop 0
	s_nop 0
	s_nop 0
	s_nop 0
	s_nop 0
	s_nop 0
	s_nop 0
	s_nop 0
	s_nop 0
	s_nop 0
	s_nop 0
	s_nop 0
	s_nop 0
	s_nop 0
	s_nop 0
	s_nop 0
	s_nop 0
	s_nop 0
	s_nop 0
	s_nop 0
	s_nop 0
	s_nop 0
	s_nop 0
	s_nop 0
	s_nop 0
	s_nop 0
	s_nop 0
	s_nop 0
	s_nop 0
	s_nop 0
	s_nop 0
	s_nop 0
	s_nop 0
	s_nop 0
	s_nop 0
	s_nop 0
	s_nop 0
	s_nop 0
	s_nop 0
	s_nop 0
	s_nop 0
	s_nop 0
	s_nop 0
	s_nop 0
	s_nop 0
	s_nop 0
	s_nop 0
	s_nop 0
	s_nop 0
	s_nop 0
	s_nop 0
	s_nop 0
	s_nop 0
	s_nop 0
	s_nop 0
	s_nop 0
	s_nop 0
	s_nop 0
	s_nop 0
	s_nop 0
	s_nop 0
	s_nop 0
	s_nop 0
	s_nop 0
	s_nop 0
	s_nop 0
	s_nop 0
	s_nop 0
	s_nop 0
	s_nop 0
	s_nop 0
	s_nop 0
	s_nop 0
	s_nop 0
	s_nop 0
	s_nop 0
	s_nop 0
	s_nop 0
	s_nop 0
	s_nop 0
	s_nop 0
	s_nop 0
	s_nop 0
	s_nop 0
	s_nop 0
	s_nop 0
	s_nop 0
	s_nop 0
	s_nop 0
	s_nop 0
	s_nop 0
	s_nop 0
	s_nop 0
	s_nop 0
	s_nop 0
	s_nop 0
	s_nop 0
	s_nop 0
	s_nop 0
	s_nop 0
	s_nop 0
	s_nop 0
	s_nop 0
	s_nop 0
	s_nop 0
	s_nop 0
	s_nop 0
	s_nop 0
	s_nop 0
	s_nop 0
	s_nop 0
	s_nop 0
	s_nop 0
	s_nop 0
	s_nop 0
	s_nop 0
	s_nop 0
	s_nop 0
	s_nop 0
	s_nop 0
	s_nop 0
	s_nop 0
	s_nop 0
	s_nop 0
	s_nop 0
	s_nop 0
	s_nop 0
	s_nop 0
	s_nop 0
	s_nop 0
	s_nop 0
	s_nop 0
	s_nop 0
	s_nop 0
	s_nop 0
	s_nop 0
	s_nop 0
	s_nop 0
	s_nop 0
	s_nop 0
	s_nop 0
	s_nop 0
	s_nop 0
	s_nop 0
	s_nop 0
	s_nop 0
	s_nop 0
	s_nop 0
	s_nop 0
	s_nop 0
	s_nop 0
	s_nop 0
	s_nop 0
	s_nop 0
	s_nop 0
	s_nop 0
	s_nop 0
	s_nop 0
	s_nop 0
	s_nop 0
	s_nop 0
	s_nop 0
	s_nop 0
	s_nop 0
	s_nop 0
	s_nop 0
	s_nop 0
	s_nop 0
	s_nop 0
	s_nop 0
	s_nop 0
	s_nop 0
	s_nop 0
	s_nop 0
	s_nop 0
	s_nop 0
	s_nop 0
	s_nop 0
	s_nop 0
	s_nop 0
	s_nop 0
	s_nop 0
	s_nop 0
	s_nop 0
	s_nop 0
	s_nop 0
	s_nop 0
	s_nop 0
	s_nop 0
	s_nop 0
	s_nop 0
	s_nop 0
	s_nop 0
	s_nop 0
	s_nop 0
	s_nop 0
	s_nop 0
	s_nop 0
	s_nop 0
	s_nop 0
	s_nop 0
	s_nop 0
	s_nop 0
	s_nop 0
	s_nop 0
	s_nop 0
	s_nop 0
	s_nop 0
	s_nop 0
	s_nop 0
	s_nop 0
	s_nop 0
	s_nop 0
	s_nop 0
	s_nop 0
	s_nop 0
	s_nop 0
	s_nop 0
	s_nop 0
	s_nop 0
	s_nop 0
	s_nop 0
	s_nop 0
	s_nop 0
	s_nop 0
	s_nop 0
	s_nop 0
	s_nop 0
	s_nop 0
	s_nop 0
	s_nop 0
	s_nop 0
	s_nop 0
	s_nop 0
	s_nop 0
	s_nop 0
	s_nop 0
	s_nop 0
	s_nop 0
	s_nop 0
	s_nop 0
	s_nop 0
	s_nop 0
	s_nop 0
	s_nop 0
	s_nop 0
	s_nop 0
	s_nop 0
	s_nop 0
	s_nop 0
	s_nop 0
	s_nop 0
	s_nop 0
	s_nop 0
	s_nop 0
	s_nop 0
	s_nop 0
	s_nop 0
	s_nop 0
	s_nop 0
	s_nop 0
	s_nop 0
	s_nop 0
	s_nop 0
	s_nop 0
	s_nop 0
	s_nop 0
	s_nop 0
	s_nop 0
	s_nop 0
	s_nop 0
	s_nop 0
	s_nop 0
	s_nop 0
	s_nop 0
	s_nop 0
	s_nop 0
	s_nop 0
	s_nop 0
	s_nop 0
	s_nop 0
	s_nop 0
	s_nop 0
	s_nop 0
	s_nop 0
	s_nop 0
	s_nop 0
	s_nop 0
	s_nop 0
	s_nop 0
	s_nop 0
	s_nop 0
	s_nop 0
	s_nop 0
	s_nop 0
	s_nop 0
	s_nop 0
	s_nop 0
	s_nop 0
	s_nop 0
	s_nop 0
	s_nop 0
	s_nop 0
	s_nop 0
	s_nop 0
	s_nop 0
	s_nop 0
	s_nop 0
	s_nop 0
	s_nop 0
	s_nop 0
	s_nop 0
	s_nop 0
	s_nop 0
	s_nop 0
	s_nop 0
	s_nop 0
	s_nop 0
	s_nop 0
	s_nop 0
	s_nop 0
	s_nop 0
	s_nop 0
	s_nop 0
	s_nop 0
	s_nop 0
	s_nop 0
	s_nop 0
	s_nop 0
	s_nop 0
	s_nop 0
.LBB0_166:
	v_mov_b32_e32 v0, 0
	v_mov_b32_e32 v15, v0
	v_mov_b32_e32 v14, v0
	v_mov_b32_e32 v13, v0
	v_mov_b32_e32 v12, v0
	v_mov_b32_e32 v11, v0
	v_mov_b32_e32 v10, v0
	v_mov_b32_e32 v9, v0
	v_mov_b32_e32 v8, v0
	v_mov_b32_e32 v7, v0
	v_mov_b32_e32 v6, v0
	v_mov_b32_e32 v5, v0
	v_mov_b32_e32 v4, v0
	v_mov_b32_e32 v3, v0
	v_mov_b32_e32 v2, v0
	v_mov_b32_e32 v1, v0
	v_mov_b64_e32 v[46:47], v[14:15]
	v_mov_b32_e32 v31, v0
	v_mov_b32_e32 v30, v0
	v_mov_b32_e32 v29, v0
	v_mov_b32_e32 v28, v0
	v_mov_b32_e32 v27, v0
	v_mov_b32_e32 v26, v0
	v_mov_b32_e32 v25, v0
	v_mov_b32_e32 v24, v0
	v_mov_b32_e32 v23, v0
	v_mov_b32_e32 v22, v0
	v_mov_b32_e32 v21, v0
	v_mov_b32_e32 v20, v0
	v_mov_b32_e32 v19, v0
	v_mov_b32_e32 v18, v0
	v_mov_b32_e32 v17, v0
	v_mov_b32_e32 v16, v0
	v_mov_b64_e32 v[44:45], v[12:13]
	v_mov_b64_e32 v[42:43], v[10:11]
	v_mov_b64_e32 v[40:41], v[8:9]
	v_mov_b64_e32 v[38:39], v[6:7]
	v_mov_b64_e32 v[36:37], v[4:5]
	v_mov_b64_e32 v[34:35], v[2:3]
	v_mov_b64_e32 v[32:33], v[0:1]
	s_branch .LBB0_126

; __device__ __forceinline__ float hf_lo(unsigned w) { return (float)__builtin_bit_cast(_Float16, (unsigned short)(w & 0xffffu)); }
; __device__ __forceinline__ float hf_hi(unsigned w) { return (float)__builtin_bit_cast(_Float16, (unsigned short)(w >> 16)); }
; template <int R, bool SRCB> ...
;     ...
;         for (int j = 0; j < 2; ++j) { const int c = 8 * lane + 512 * j;
;             if (SRCB) { const u32x4 t = *(const u32x4*)((const bf16_t*)hp_ + (size_t)r * DM + c);
;                 h[r][j][0] = (f32x4){hf_lo(t.x), hf_hi(t.x), hf_lo(t.y), hf_hi(t.y)}; h[r][j][1] = (f32x4){hf_lo(t.z), hf_hi(t.z), hf_lo(t.w), hf_hi(t.w)}; }
;             else { h[r][j][0] = *(const f32x4*)((const float*)hp_ + (size_t)r * DM + c); h[r][j][1] = *(const f32x4*)((const float*)hp_ + (size_t)r * DM + c + 4); }
;             if (Y) yr[r][j] = *(const u32x4*)(Y + (size_t)(row0 + r) * DM + c); }
;     if (Y) {
;         f32x4 gg[2][2];
; #pragma unroll
;         for (int j = 0; j < 2; ++j)
; #pragma unroll
;             for (int k = 0; k < 2; ++k) { const int c = 8 * lane + 512 * j + 4 * k; gg[j][k] = *(const f32x4*)(gpost + c) * *(const f32x4*)(gate + (size_t)mrow * 9216 + c); }
;     ...
;             for (int k = 0; k < 2; ++k) { const int c = 8 * lane + 512 * j + 4 * k; gp[j][k] = *(const f32x4*)(gpre + c); sc1[j][k] = *(const f32x4*)(scale + (size_t)mrow * 9216 + c) + 1.0f; sh[j][k] = *(const f32x4*)(shift + (size_t)mrow * 9216 + c); }
nrmx_chunk:
	s_lshr_b32 s2, s23, 8
	s_and_b32 s3, s23, 0xff
	s_lshl_b32 s4, s2, 23
	s_lshl_b32 s3, s3, 13
	s_add_u32 s4, s4, s3
	s_add_u32 s42, s98, s4
	s_addc_u32 s43, s99, 0
	s_add_u32 s44, s14, s4
	s_addc_u32 s45, s15, 0
	s_mul_i32 s2, s2, 0x9000
	s_add_u32 s8, s36, s2
	s_addc_u32 s9, s37, 0
	s_add_u32 s10, s30, s2
	s_addc_u32 s11, s31, 0
	s_add_u32 s12, s28, s2
	s_addc_u32 s13, s29, 0
	global_load_dwordx4 v[0:3], v182, s[34:35]
	global_load_dwordx4 v[4:7], v182, s[34:35] offset:16
	global_load_dwordx4 v[8:11], v182, s[34:35] offset:2048
	global_load_dwordx4 v[12:15], v182, s[34:35] offset:2064
	global_load_dwordx4 v[116:119], v182, s[8:9]
	global_load_dwordx4 v[120:123], v182, s[8:9] offset:16
	global_load_dwordx4 v[124:127], v182, s[8:9] offset:2048
	global_load_dwordx4 v[128:131], v182, s[8:9] offset:2064
	global_load_dwordx4 v[16:19], v182, s[26:27]
	global_load_dwordx4 v[20:23], v182, s[26:27] offset:16
	global_load_dwordx4 v[24:27], v182, s[26:27] offset:2048
	global_load_dwordx4 v[28:31], v182, s[26:27] offset:2064
	global_load_dwordx4 v[32:35], v182, s[10:11]
	global_load_dwordx4 v[36:39], v182, s[10:11] offset:16
	global_load_dwordx4 v[40:43], v182, s[10:11] offset:2048
	global_load_dwordx4 v[44:47], v182, s[10:11] offset:2064
	global_load_dwordx4 v[48:51], v182, s[12:13]
	global_load_dwordx4 v[52:55], v182, s[12:13] offset:16
	global_load_dwordx4 v[56:59], v182, s[12:13] offset:2048
	global_load_dwordx4 v[60:63], v182, s[12:13] offset:2064
	global_load_dwordx4 v[64:67], v184, s[42:43] offset:-4096
	global_load_dwordx4 v[68:71], v184, s[42:43] offset:-3072
	global_load_dwordx4 v[148:151], v184, s[44:45] offset:-4096
	global_load_dwordx4 v[152:155], v184, s[44:45] offset:-3072
	global_load_dwordx4 v[72:75], v184, s[42:43] offset:-2048
	global_load_dwordx4 v[76:79], v184, s[42:43] offset:-1024
	global_load_dwordx4 v[156:159], v184, s[44:45] offset:-2048
	global_load_dwordx4 v[160:163], v184, s[44:45] offset:-1024
	global_load_dwordx4 v[80:83], v184, s[42:43] offset:0
	global_load_dwordx4 v[84:87], v184, s[42:43] offset:1024
	global_load_dwordx4 v[164:167], v184, s[44:45] offset:0
	global_load_dwordx4 v[168:171], v184, s[44:45] offset:1024
	global_load_dwordx4 v[88:91], v184, s[42:43] offset:2048
	global_load_dwordx4 v[92:95], v184, s[42:43] offset:3072
	global_load_dwordx4 v[172:175], v184, s[44:45] offset:2048
	global_load_dwordx4 v[176:179], v184, s[44:45] offset:3072
	s_waitcnt vmcnt(16)
	v_pk_mul_f32 v[0:1], v[0:1], v[116:117]
	v_pk_mul_f32 v[2:3], v[2:3], v[118:119]
	v_pk_mul_f32 v[4:5], v[4:5], v[120:121]
	v_pk_mul_f32 v[6:7], v[6:7], v[122:123]
	v_pk_mul_f32 v[8:9], v[8:9], v[124:125]
	v_pk_mul_f32 v[10:11], v[10:11], v[126:127]
	v_pk_mul_f32 v[12:13], v[12:13], v[128:129]
	v_pk_mul_f32 v[14:15], v[14:15], v[130:131]
	v_pk_add_f32 v[32:33], v[32:33], 1.0 op_sel_hi:[1,0]
	v_pk_add_f32 v[34:35], v[34:35], 1.0 op_sel_hi:[1,0]
	v_pk_add_f32 v[36:37], v[36:37], 1.0 op_sel_hi:[1,0]
	v_pk_add_f32 v[38:39], v[38:39], 1.0 op_sel_hi:[1,0]
	v_pk_add_f32 v[40:41], v[40:41], 1.0 op_sel_hi:[1,0]
	v_pk_add_f32 v[42:43], v[42:43], 1.0 op_sel_hi:[1,0]
	v_pk_add_f32 v[44:45], v[44:45], 1.0 op_sel_hi:[1,0]
	v_pk_add_f32 v[46:47], v[46:47], 1.0 op_sel_hi:[1,0]
	s_waitcnt vmcnt(12)
	v_lshlrev_b32_e32 v116, 16, v148
	v_and_b32_e32 v117, 0xffff0000, v148
	v_lshlrev_b32_e32 v118, 16, v149
	v_and_b32_e32 v119, 0xffff0000, v149
	v_lshlrev_b32_e32 v120, 16, v150
	v_and_b32_e32 v121, 0xffff0000, v150
	v_lshlrev_b32_e32 v122, 16, v151
	v_and_b32_e32 v123, 0xffff0000, v151
	v_lshlrev_b32_e32 v124, 16, v152
	v_and_b32_e32 v125, 0xffff0000, v152
	v_lshlrev_b32_e32 v126, 16, v153
	v_and_b32_e32 v127, 0xffff0000, v153
	v_lshlrev_b32_e32 v128, 16, v154
	v_and_b32_e32 v129, 0xffff0000, v154
	v_lshlrev_b32_e32 v130, 16, v155
	v_and_b32_e32 v131, 0xffff0000, v155
	v_cvt_f32_f16_e32 v198, v64
	v_cvt_f32_f16_sdwa v199, v64 dst_sel:DWORD dst_unused:UNUSED_PAD src0_sel:WORD_1
	v_cvt_f32_f16_e32 v200, v65
	v_cvt_f32_f16_sdwa v201, v65 dst_sel:DWORD dst_unused:UNUSED_PAD src0_sel:WORD_1
	v_cvt_f32_f16_e32 v202, v66
	v_cvt_f32_f16_sdwa v203, v66 dst_sel:DWORD dst_unused:UNUSED_PAD src0_sel:WORD_1
	v_cvt_f32_f16_e32 v204, v67
	v_cvt_f32_f16_sdwa v205, v67 dst_sel:DWORD dst_unused:UNUSED_PAD src0_sel:WORD_1
	v_cvt_f32_f16_e32 v206, v68
	v_cvt_f32_f16_sdwa v207, v68 dst_sel:DWORD dst_unused:UNUSED_PAD src0_sel:WORD_1
	v_cvt_f32_f16_e32 v208, v69
	v_cvt_f32_f16_sdwa v209, v69 dst_sel:DWORD dst_unused:UNUSED_PAD src0_sel:WORD_1
	v_cvt_f32_f16_e32 v210, v70
	v_cvt_f32_f16_sdwa v211, v70 dst_sel:DWORD dst_unused:UNUSED_PAD src0_sel:WORD_1
	v_cvt_f32_f16_e32 v212, v71
	v_cvt_f32_f16_sdwa v213, v71 dst_sel:DWORD dst_unused:UNUSED_PAD src0_sel:WORD_1
	global_load_dwordx4 v[64:67], v185, s[42:43] offset:-4096
	global_load_dwordx4 v[68:71], v185, s[42:43] offset:-3072
	global_load_dwordx4 v[148:151], v185, s[44:45] offset:-4096
	global_load_dwordx4 v[152:155], v185, s[44:45] offset:-3072
	v_pk_mul_f32 v[140:141], v[116:117], v[116:117]
	v_pk_fma_f32 v[140:141], v[118:119], v[118:119], v[140:141]
	v_pk_fma_f32 v[140:141], v[120:121], v[120:121], v[140:141]
	v_pk_fma_f32 v[140:141], v[122:123], v[122:123], v[140:141]
	v_pk_fma_f32 v[140:141], v[124:125], v[124:125], v[140:141]
	v_pk_fma_f32 v[140:141], v[126:127], v[126:127], v[140:141]
	v_pk_fma_f32 v[140:141], v[128:129], v[128:129], v[140:141]
	v_pk_fma_f32 v[140:141], v[130:131], v[130:131], v[140:141]
	v_add_f32_e32 v140, v140, v141
	s_nop 1
	v_add_f32_dpp v140, v140, v140 quad_perm:[1,0,3,2] row_mask:0xf bank_mask:0xf
	s_nop 1
	v_add_f32_dpp v140, v140, v140 quad_perm:[2,3,0,1] row_mask:0xf bank_mask:0xf
	s_nop 1
; __device__ __forceinline__ unsigned pk2(float lo, float hi) { return pg8::cvt_pk_bf16(lo, hi); }
; template <int R, bool SRCB> ...
;     ...
;             const float rr = __builtin_amdgcn_rsqf(wave_sum(ss) * (1.0f / DM) + 1e-6f) * w;
; #pragma unroll
;             for (int j = 0; j < 2; ++j)
; #pragma unroll
;                 for (int k = 0; k < 2; ++k) h[r][j][k] = h[r][j][k] + gg[j][k] * (y[j][k] * rr);
;         }
;     }
; #pragma unroll
;     for (int r = 0; r < R; ++r)
; #pragma unroll
;         for (int j = 0; j < 2; ++j) { const int c = 8 * lane + 512 * j;
;             if (final_out) { *(f32x4*)(final_out + (size_t)(row0 + r) * DM + c) = h[r][j][0]; *(f32x4*)(final_out + (size_t)(row0 + r) * DM + c + 4) = h[r][j][1]; }
;             else { u32x4 t; t.x = pkh2(h[r][j][0][0], h[r][j][0][1]); t.y = pkh2(h[r][j][0][2], h[r][j][0][3]); t.z = pkh2(h[r][j][1][0], h[r][j][1][1]); t.w = pkh2(h[r][j][1][2], h[r][j][1][3]);
;                 *(u32x4*)(hout + (size_t)(row0 + r) * DM + c) = t; } }
;     if (U) {
;         f32x4 gp[2][2], sc1[2][2], sh[2][2];
; #pragma unroll
;         for (int j = 0; j < 2; ++j)
; #pragma unroll
;             for (int k = 0; k < 2; ++k) { const int c = 8 * lane + 512 * j + 4 * k; gp[j][k] = *(const f32x4*)(gpre + c); sc1[j][k] = *(const f32x4*)(scale + (size_t)mrow * 9216 + c) + 1.0f; sh[j][k] = *(const f32x4*)(shift + (size_t)mrow * 9216 + c); }
; #pragma unroll
;         for (int r = 0; r < R; ++r) {
;             float ss = 0.f;
; #pragma unroll
;             for (int j = 0; j < 2; ++j)
; #pragma unroll
;                 for (int k = 0; k < 2; ++k) ss += (h[r][j][k][0] * h[r][j][k][0] + h[r][j][k][1] * h[r][j][k][1]) + (h[r][j][k][2] * h[r][j][k][2] + h[r][j][k][3] * h[r][j][k][3]);
;             const float rr = __builtin_amdgcn_rsqf(wave_sum(ss) * (1.0f / DM) + 1e-6f);
; #pragma unroll
;             for (int j = 0; j < 2; ++j) { const f32x4 v0 = (h[r][j][0] * rr * gp[j][0]) * sc1[j][0] + sh[j][0], v1 = (h[r][j][1] * rr * gp[j][1]) * sc1[j][1] + sh[j][1];
;                 u32x4 t; t.x = pk2(v0[0], v0[1]); t.y = pk2(v0[2], v0[3]); t.z = pk2(v1[0], v1[1]); t.w = pk2(v1[2], v1[3]);
;                 *(u32x4*)(U + (size_t)(row0 + r) * DM + 8 * lane + 512 * j) = t; }
	v_add_f32_dpp v140, v140, v140 row_ror:4 row_mask:0xf bank_mask:0xf
	s_nop 1
	v_add_f32_dpp v140, v140, v140 row_ror:8 row_mask:0xf bank_mask:0xf
	s_nop 1
	v_add_f32_dpp v140, v140, v140 row_bcast:15 row_mask:0xa bank_mask:0xf
	s_nop 1
	v_add_f32_dpp v140, v140, v140 row_bcast:31 row_mask:0xc bank_mask:0xf
	s_nop 1
	v_fmamk_f32 v140, v140, 0x3a800000, v224
	v_rsq_f32_e32 v140, v140
	s_nop 0
	v_mul_f32_e32 v140, v144, v140
	s_nop 0
	v_readlane_b32 s4, v140, 63
	s_nop 1
	v_pk_mul_f32 v[116:117], v[116:117], s[4:5] op_sel_hi:[1,0]
	v_pk_mul_f32 v[118:119], v[118:119], s[4:5] op_sel_hi:[1,0]
	v_pk_mul_f32 v[120:121], v[120:121], s[4:5] op_sel_hi:[1,0]
	v_pk_mul_f32 v[122:123], v[122:123], s[4:5] op_sel_hi:[1,0]
	v_pk_mul_f32 v[124:125], v[124:125], s[4:5] op_sel_hi:[1,0]
	v_pk_mul_f32 v[126:127], v[126:127], s[4:5] op_sel_hi:[1,0]
	v_pk_mul_f32 v[128:129], v[128:129], s[4:5] op_sel_hi:[1,0]
	v_pk_mul_f32 v[130:131], v[130:131], s[4:5] op_sel_hi:[1,0]
	v_pk_fma_f32 v[198:199], v[0:1], v[116:117], v[198:199]
	v_pk_fma_f32 v[200:201], v[2:3], v[118:119], v[200:201]
	v_pk_fma_f32 v[202:203], v[4:5], v[120:121], v[202:203]
	v_pk_fma_f32 v[204:205], v[6:7], v[122:123], v[204:205]
	v_pk_fma_f32 v[206:207], v[8:9], v[124:125], v[206:207]
	v_pk_fma_f32 v[208:209], v[10:11], v[126:127], v[208:209]
	v_pk_fma_f32 v[210:211], v[12:13], v[128:129], v[210:211]
	v_pk_fma_f32 v[212:213], v[14:15], v[130:131], v[212:213]
	v_cvt_f16_f32_e32 v132, v198
	v_cvt_f16_f32_e32 v133, v200
	v_cvt_f16_f32_e32 v134, v202
	v_cvt_f16_f32_e32 v135, v204
	v_cvt_f16_f32_e32 v136, v206
	v_cvt_f16_f32_e32 v137, v208
	v_cvt_f16_f32_e32 v138, v210
	v_cvt_f16_f32_e32 v139, v212
	v_cvt_f16_f32_sdwa v132, v199 dst_sel:WORD_1 dst_unused:UNUSED_PRESERVE src0_sel:DWORD
	v_cvt_f16_f32_sdwa v133, v201 dst_sel:WORD_1 dst_unused:UNUSED_PRESERVE src0_sel:DWORD
	v_cvt_f16_f32_sdwa v134, v203 dst_sel:WORD_1 dst_unused:UNUSED_PRESERVE src0_sel:DWORD
	v_cvt_f16_f32_sdwa v135, v205 dst_sel:WORD_1 dst_unused:UNUSED_PRESERVE src0_sel:DWORD
	v_cvt_f16_f32_sdwa v136, v207 dst_sel:WORD_1 dst_unused:UNUSED_PRESERVE src0_sel:DWORD
	v_cvt_f16_f32_sdwa v137, v209 dst_sel:WORD_1 dst_unused:UNUSED_PRESERVE src0_sel:DWORD
	v_cvt_f16_f32_sdwa v138, v211 dst_sel:WORD_1 dst_unused:UNUSED_PRESERVE src0_sel:DWORD
	v_cvt_f16_f32_sdwa v139, v213 dst_sel:WORD_1 dst_unused:UNUSED_PRESERVE src0_sel:DWORD
	s_nop 0
	global_store_dwordx4 v184, v[132:135], s[42:43] offset:-4096 sc1
	global_store_dwordx4 v184, v[136:139], s[42:43] offset:-3072 sc1
	v_pk_mul_f32 v[140:141], v[198:199], v[198:199]
	v_pk_fma_f32 v[140:141], v[200:201], v[200:201], v[140:141]
	v_pk_fma_f32 v[140:141], v[202:203], v[202:203], v[140:141]
	v_pk_fma_f32 v[140:141], v[204:205], v[204:205], v[140:141]
	v_pk_fma_f32 v[140:141], v[206:207], v[206:207], v[140:141]
	v_pk_fma_f32 v[140:141], v[208:209], v[208:209], v[140:141]
	v_pk_fma_f32 v[140:141], v[210:211], v[210:211], v[140:141]
	v_pk_fma_f32 v[140:141], v[212:213], v[212:213], v[140:141]
	v_add_f32_e32 v140, v140, v141
	s_nop 1
	v_add_f32_dpp v140, v140, v140 quad_perm:[1,0,3,2] row_mask:0xf bank_mask:0xf
	s_nop 1
	v_add_f32_dpp v140, v140, v140 quad_perm:[2,3,0,1] row_mask:0xf bank_mask:0xf
	s_nop 1
	v_add_f32_dpp v140, v140, v140 row_ror:4 row_mask:0xf bank_mask:0xf
	s_nop 1
	v_add_f32_dpp v140, v140, v140 row_ror:8 row_mask:0xf bank_mask:0xf
	s_nop 1
	v_add_f32_dpp v140, v140, v140 row_bcast:15 row_mask:0xa bank_mask:0xf
	s_nop 1
	v_add_f32_dpp v140, v140, v140 row_bcast:31 row_mask:0xc bank_mask:0xf
	s_nop 1
	v_fmamk_f32 v140, v140, 0x3a800000, v224
	v_rsq_f32_e32 v140, v140
	s_nop 0
	v_readlane_b32 s6, v140, 63
	s_nop 1
	v_pk_mul_f32 v[198:199], v[198:199], s[6:7] op_sel_hi:[1,0]
	v_pk_mul_f32 v[200:201], v[200:201], s[6:7] op_sel_hi:[1,0]
	v_pk_mul_f32 v[202:203], v[202:203], s[6:7] op_sel_hi:[1,0]
	v_pk_mul_f32 v[204:205], v[204:205], s[6:7] op_sel_hi:[1,0]
	v_pk_mul_f32 v[206:207], v[206:207], s[6:7] op_sel_hi:[1,0]
	v_pk_mul_f32 v[208:209], v[208:209], s[6:7] op_sel_hi:[1,0]
	v_pk_mul_f32 v[210:211], v[210:211], s[6:7] op_sel_hi:[1,0]
	v_pk_mul_f32 v[212:213], v[212:213], s[6:7] op_sel_hi:[1,0]
	v_pk_mul_f32 v[198:199], v[16:17], v[198:199]
	v_pk_mul_f32 v[200:201], v[18:19], v[200:201]
	v_pk_mul_f32 v[202:203], v[20:21], v[202:203]
	v_pk_mul_f32 v[204:205], v[22:23], v[204:205]
	v_pk_mul_f32 v[206:207], v[24:25], v[206:207]
	v_pk_mul_f32 v[208:209], v[26:27], v[208:209]
	v_pk_mul_f32 v[210:211], v[28:29], v[210:211]
	v_pk_mul_f32 v[212:213], v[30:31], v[212:213]
	v_pk_fma_f32 v[198:199], v[32:33], v[198:199], v[48:49]
	v_pk_fma_f32 v[200:201], v[34:35], v[200:201], v[50:51]
	v_pk_fma_f32 v[202:203], v[36:37], v[202:203], v[52:53]
	v_pk_fma_f32 v[204:205], v[38:39], v[204:205], v[54:55]
	v_pk_fma_f32 v[206:207], v[40:41], v[206:207], v[56:57]
	v_pk_fma_f32 v[208:209], v[42:43], v[208:209], v[58:59]
	v_pk_fma_f32 v[210:211], v[44:45], v[210:211], v[60:61]
	v_pk_fma_f32 v[212:213], v[46:47], v[212:213], v[62:63]
	v_cvt_pk_bf16_f32 v230, v198, v199
	v_cvt_pk_bf16_f32 v231, v200, v201
	v_cvt_pk_bf16_f32 v232, v202, v203
	v_cvt_pk_bf16_f32 v233, v204, v205
	v_cvt_pk_bf16_f32 v234, v206, v207
	v_cvt_pk_bf16_f32 v235, v208, v209
	v_cvt_pk_bf16_f32 v236, v210, v211
	v_cvt_pk_bf16_f32 v237, v212, v213
	global_store_dwordx4 v184, v[230:233], s[44:45] offset:-4096 sc1
	global_store_dwordx4 v184, v[234:237], s[44:45] offset:-3072 sc1
	s_waitcnt vmcnt(16)
; __device__ __forceinline__ float bf_lo(unsigned w) { return __uint_as_float(w << 16); }
; template <int R, bool SRCB> ...
;     ...
;             for (int j = 0; j < 2; ++j) { const u32x4 t = yr[r][j];
;                 y[j][0] = (f32x4){bf_lo(t.x), bf_hi(t.x), bf_lo(t.y), bf_hi(t.y)}; y[j][1] = (f32x4){bf_lo(t.z), bf_hi(t.z), bf_lo(t.w), bf_hi(t.w)};
;                 if (R == 1 && YP) {
; #pragma unroll
;                     for (int k = 0; k < 2; ++k) { const float* pp = YP + (size_t)(row0 - M_LAT) * DM + 8 * lane + 512 * j + 4 * k; f32x4 s = *(const f32x4*)pp;
; #pragma unroll
;                         for (int q = 1; q < pg8::NSL; ++q) s = s + *(const f32x4*)(pp + (size_t)q * 2048 * DM);
;                         y[j][k] = s; } }
; #pragma unroll
;                 for (int k = 0; k < 2; ++k) ss += (y[j][k][0] * y[j][k][0] + y[j][k][1] * y[j][k][1]) + (y[j][k][2] * y[j][k][2] + y[j][k][3] * y[j][k][3]); }
;             const float rr = __builtin_amdgcn_rsqf(wave_sum(ss) * (1.0f / DM) + 1e-6f) * w;
; #pragma unroll
;             for (int j = 0; j < 2; ++j)
; #pragma unroll
;                 for (int k = 0; k < 2; ++k) h[r][j][k] = h[r][j][k] + gg[j][k] * (y[j][k] * rr);
;         }
;     }
; #pragma unroll
;     for (int r = 0; r < R; ++r)
; #pragma unroll
;         for (int j = 0; j < 2; ++j) { const int c = 8 * lane + 512 * j;
;             if (final_out) { *(f32x4*)(final_out + (size_t)(row0 + r) * DM + c) = h[r][j][0]; *(f32x4*)(final_out + (size_t)(row0 + r) * DM + c + 4) = h[r][j][1]; }
;             else { u32x4 t; t.x = pkh2(h[r][j][0][0], h[r][j][0][1]); t.y = pkh2(h[r][j][0][2], h[r][j][0][3]); t.z = pkh2(h[r][j][1][0], h[r][j][1][1]); t.w = pkh2(h[r][j][1][2], h[r][j][1][3]);
;                 *(u32x4*)(hout + (size_t)(row0 + r) * DM + c) = t; } }
;     if (U) {
;         f32x4 gp[2][2], sc1[2][2], sh[2][2];
; #pragma unroll
;         for (int j = 0; j < 2; ++j)
; #pragma unroll
;             for (int k = 0; k < 2; ++k) { const int c = 8 * lane + 512 * j + 4 * k; gp[j][k] = *(const f32x4*)(gpre + c); sc1[j][k] = *(const f32x4*)(scale + (size_t)mrow * 9216 + c) + 1.0f; sh[j][k] = *(const f32x4*)(shift + (size_t)mrow * 9216 + c); }
; #pragma unroll
;         for (int r = 0; r < R; ++r) {
;             float ss = 0.f;
; #pragma unroll
;             for (int j = 0; j < 2; ++j)
; #pragma unroll
	v_lshlrev_b32_e32 v116, 16, v156
	v_and_b32_e32 v117, 0xffff0000, v156
	v_lshlrev_b32_e32 v118, 16, v157
	v_and_b32_e32 v119, 0xffff0000, v157
	v_lshlrev_b32_e32 v120, 16, v158
	v_and_b32_e32 v121, 0xffff0000, v158
	v_lshlrev_b32_e32 v122, 16, v159
	v_and_b32_e32 v123, 0xffff0000, v159
	v_lshlrev_b32_e32 v124, 16, v160
	v_and_b32_e32 v125, 0xffff0000, v160
	v_lshlrev_b32_e32 v126, 16, v161
	v_and_b32_e32 v127, 0xffff0000, v161
	v_lshlrev_b32_e32 v128, 16, v162
	v_and_b32_e32 v129, 0xffff0000, v162
	v_lshlrev_b32_e32 v130, 16, v163
	v_and_b32_e32 v131, 0xffff0000, v163
	v_cvt_f32_f16_e32 v198, v72
	v_cvt_f32_f16_sdwa v199, v72 dst_sel:DWORD dst_unused:UNUSED_PAD src0_sel:WORD_1
	v_cvt_f32_f16_e32 v200, v73
	v_cvt_f32_f16_sdwa v201, v73 dst_sel:DWORD dst_unused:UNUSED_PAD src0_sel:WORD_1
	v_cvt_f32_f16_e32 v202, v74
	v_cvt_f32_f16_sdwa v203, v74 dst_sel:DWORD dst_unused:UNUSED_PAD src0_sel:WORD_1
	v_cvt_f32_f16_e32 v204, v75
	v_cvt_f32_f16_sdwa v205, v75 dst_sel:DWORD dst_unused:UNUSED_PAD src0_sel:WORD_1
	v_cvt_f32_f16_e32 v206, v76
	v_cvt_f32_f16_sdwa v207, v76 dst_sel:DWORD dst_unused:UNUSED_PAD src0_sel:WORD_1
	v_cvt_f32_f16_e32 v208, v77
	v_cvt_f32_f16_sdwa v209, v77 dst_sel:DWORD dst_unused:UNUSED_PAD src0_sel:WORD_1
	v_cvt_f32_f16_e32 v210, v78
	v_cvt_f32_f16_sdwa v211, v78 dst_sel:DWORD dst_unused:UNUSED_PAD src0_sel:WORD_1
	v_cvt_f32_f16_e32 v212, v79
	v_cvt_f32_f16_sdwa v213, v79 dst_sel:DWORD dst_unused:UNUSED_PAD src0_sel:WORD_1
	global_load_dwordx4 v[72:75], v185, s[42:43] offset:-2048
	global_load_dwordx4 v[76:79], v185, s[42:43] offset:-1024
	global_load_dwordx4 v[156:159], v185, s[44:45] offset:-2048
	global_load_dwordx4 v[160:163], v185, s[44:45] offset:-1024
	v_pk_mul_f32 v[140:141], v[116:117], v[116:117]
	v_pk_fma_f32 v[140:141], v[118:119], v[118:119], v[140:141]
	v_pk_fma_f32 v[140:141], v[120:121], v[120:121], v[140:141]
	v_pk_fma_f32 v[140:141], v[122:123], v[122:123], v[140:141]
	v_pk_fma_f32 v[140:141], v[124:125], v[124:125], v[140:141]
	v_pk_fma_f32 v[140:141], v[126:127], v[126:127], v[140:141]
	v_pk_fma_f32 v[140:141], v[128:129], v[128:129], v[140:141]
	v_pk_fma_f32 v[140:141], v[130:131], v[130:131], v[140:141]
	v_add_f32_e32 v140, v140, v141
	s_nop 1
	v_add_f32_dpp v140, v140, v140 quad_perm:[1,0,3,2] row_mask:0xf bank_mask:0xf
	s_nop 1
	v_add_f32_dpp v140, v140, v140 quad_perm:[2,3,0,1] row_mask:0xf bank_mask:0xf
	s_nop 1
	v_add_f32_dpp v140, v140, v140 row_ror:4 row_mask:0xf bank_mask:0xf
	s_nop 1
	v_add_f32_dpp v140, v140, v140 row_ror:8 row_mask:0xf bank_mask:0xf
	s_nop 1
	v_add_f32_dpp v140, v140, v140 row_bcast:15 row_mask:0xa bank_mask:0xf
	s_nop 1
	v_add_f32_dpp v140, v140, v140 row_bcast:31 row_mask:0xc bank_mask:0xf
	s_nop 1
	v_fmamk_f32 v140, v140, 0x3a800000, v224
	v_rsq_f32_e32 v140, v140
	s_nop 0
	v_mul_f32_e32 v140, v144, v140
	s_nop 0
	v_readlane_b32 s4, v140, 63
	s_nop 1
	v_pk_mul_f32 v[116:117], v[116:117], s[4:5] op_sel_hi:[1,0]
	v_pk_mul_f32 v[118:119], v[118:119], s[4:5] op_sel_hi:[1,0]
	v_pk_mul_f32 v[120:121], v[120:121], s[4:5] op_sel_hi:[1,0]
	v_pk_mul_f32 v[122:123], v[122:123], s[4:5] op_sel_hi:[1,0]
	v_pk_mul_f32 v[124:125], v[124:125], s[4:5] op_sel_hi:[1,0]
	v_pk_mul_f32 v[126:127], v[126:127], s[4:5] op_sel_hi:[1,0]
	v_pk_mul_f32 v[128:129], v[128:129], s[4:5] op_sel_hi:[1,0]
	v_pk_mul_f32 v[130:131], v[130:131], s[4:5] op_sel_hi:[1,0]
	v_pk_fma_f32 v[198:199], v[0:1], v[116:117], v[198:199]
	v_pk_fma_f32 v[200:201], v[2:3], v[118:119], v[200:201]
	v_pk_fma_f32 v[202:203], v[4:5], v[120:121], v[202:203]
	v_pk_fma_f32 v[204:205], v[6:7], v[122:123], v[204:205]
	v_pk_fma_f32 v[206:207], v[8:9], v[124:125], v[206:207]
	v_pk_fma_f32 v[208:209], v[10:11], v[126:127], v[208:209]
	v_pk_fma_f32 v[210:211], v[12:13], v[128:129], v[210:211]
	v_pk_fma_f32 v[212:213], v[14:15], v[130:131], v[212:213]
	v_cvt_f16_f32_e32 v132, v198
	v_cvt_f16_f32_e32 v133, v200
	v_cvt_f16_f32_e32 v134, v202
	v_cvt_f16_f32_e32 v135, v204
	v_cvt_f16_f32_e32 v136, v206
	v_cvt_f16_f32_e32 v137, v208
	v_cvt_f16_f32_e32 v138, v210
	v_cvt_f16_f32_e32 v139, v212
	v_cvt_f16_f32_sdwa v132, v199 dst_sel:WORD_1 dst_unused:UNUSED_PRESERVE src0_sel:DWORD
	v_cvt_f16_f32_sdwa v133, v201 dst_sel:WORD_1 dst_unused:UNUSED_PRESERVE src0_sel:DWORD
	v_cvt_f16_f32_sdwa v134, v203 dst_sel:WORD_1 dst_unused:UNUSED_PRESERVE src0_sel:DWORD
	v_cvt_f16_f32_sdwa v135, v205 dst_sel:WORD_1 dst_unused:UNUSED_PRESERVE src0_sel:DWORD
	v_cvt_f16_f32_sdwa v136, v207 dst_sel:WORD_1 dst_unused:UNUSED_PRESERVE src0_sel:DWORD
	v_cvt_f16_f32_sdwa v137, v209 dst_sel:WORD_1 dst_unused:UNUSED_PRESERVE src0_sel:DWORD
	v_cvt_f16_f32_sdwa v138, v211 dst_sel:WORD_1 dst_unused:UNUSED_PRESERVE src0_sel:DWORD
	v_cvt_f16_f32_sdwa v139, v213 dst_sel:WORD_1 dst_unused:UNUSED_PRESERVE src0_sel:DWORD
	s_nop 0
	global_store_dwordx4 v184, v[132:135], s[42:43] offset:-2048 sc1
	global_store_dwordx4 v184, v[136:139], s[42:43] offset:-1024 sc1
	v_pk_mul_f32 v[140:141], v[198:199], v[198:199]
	v_pk_fma_f32 v[140:141], v[200:201], v[200:201], v[140:141]
	v_pk_fma_f32 v[140:141], v[202:203], v[202:203], v[140:141]
	v_pk_fma_f32 v[140:141], v[204:205], v[204:205], v[140:141]
	v_pk_fma_f32 v[140:141], v[206:207], v[206:207], v[140:141]
	v_pk_fma_f32 v[140:141], v[208:209], v[208:209], v[140:141]
	v_pk_fma_f32 v[140:141], v[210:211], v[210:211], v[140:141]
	v_pk_fma_f32 v[140:141], v[212:213], v[212:213], v[140:141]
	v_add_f32_e32 v140, v140, v141
	s_nop 1
	v_add_f32_dpp v140, v140, v140 quad_perm:[1,0,3,2] row_mask:0xf bank_mask:0xf
	s_nop 1
	v_add_f32_dpp v140, v140, v140 quad_perm:[2,3,0,1] row_mask:0xf bank_mask:0xf
	s_nop 1
	v_add_f32_dpp v140, v140, v140 row_ror:4 row_mask:0xf bank_mask:0xf
; __device__ __forceinline__ float bf_lo(unsigned w) { return __uint_as_float(w << 16); }
; template <int R, bool SRCB> ...
;     ...
;             for (int j = 0; j < 2; ++j) { const u32x4 t = yr[r][j];
;                 y[j][0] = (f32x4){bf_lo(t.x), bf_hi(t.x), bf_lo(t.y), bf_hi(t.y)}; y[j][1] = (f32x4){bf_lo(t.z), bf_hi(t.z), bf_lo(t.w), bf_hi(t.w)};
;                 if (R == 1 && YP) {
; #pragma unroll
;                     for (int k = 0; k < 2; ++k) { const float* pp = YP + (size_t)(row0 - M_LAT) * DM + 8 * lane + 512 * j + 4 * k; f32x4 s = *(const f32x4*)pp;
; #pragma unroll
;                         for (int q = 1; q < pg8::NSL; ++q) s = s + *(const f32x4*)(pp + (size_t)q * 2048 * DM);
;                         y[j][k] = s; } }
; #pragma unroll
;                 for (int k = 0; k < 2; ++k) ss += (y[j][k][0] * y[j][k][0] + y[j][k][1] * y[j][k][1]) + (y[j][k][2] * y[j][k][2] + y[j][k][3] * y[j][k][3]); }
;             const float rr = __builtin_amdgcn_rsqf(wave_sum(ss) * (1.0f / DM) + 1e-6f) * w;
; #pragma unroll
;             for (int j = 0; j < 2; ++j)
; #pragma unroll
;                 for (int k = 0; k < 2; ++k) h[r][j][k] = h[r][j][k] + gg[j][k] * (y[j][k] * rr);
;         }
;     }
; #pragma unroll
;     for (int r = 0; r < R; ++r)
; #pragma unroll
;         for (int j = 0; j < 2; ++j) { const int c = 8 * lane + 512 * j;
;             if (final_out) { *(f32x4*)(final_out + (size_t)(row0 + r) * DM + c) = h[r][j][0]; *(f32x4*)(final_out + (size_t)(row0 + r) * DM + c + 4) = h[r][j][1]; }
;             else { u32x4 t; t.x = pkh2(h[r][j][0][0], h[r][j][0][1]); t.y = pkh2(h[r][j][0][2], h[r][j][0][3]); t.z = pkh2(h[r][j][1][0], h[r][j][1][1]); t.w = pkh2(h[r][j][1][2], h[r][j][1][3]);
;                 *(u32x4*)(hout + (size_t)(row0 + r) * DM + c) = t; } }
;     if (U) {
;         f32x4 gp[2][2], sc1[2][2], sh[2][2];
; #pragma unroll
;         for (int j = 0; j < 2; ++j)
; #pragma unroll
;             for (int k = 0; k < 2; ++k) { const int c = 8 * lane + 512 * j + 4 * k; gp[j][k] = *(const f32x4*)(gpre + c); sc1[j][k] = *(const f32x4*)(scale + (size_t)mrow * 9216 + c) + 1.0f; sh[j][k] = *(const f32x4*)(shift + (size_t)mrow * 9216 + c); }
; #pragma unroll
;         for (int r = 0; r < R; ++r) {
;             float ss = 0.f;
; #pragma unroll
;             for (int j = 0; j < 2; ++j)
; #pragma unroll
	s_nop 1
	v_add_f32_dpp v140, v140, v140 row_ror:8 row_mask:0xf bank_mask:0xf
	s_nop 1
	v_add_f32_dpp v140, v140, v140 row_bcast:15 row_mask:0xa bank_mask:0xf
	s_nop 1
	v_add_f32_dpp v140, v140, v140 row_bcast:31 row_mask:0xc bank_mask:0xf
	s_nop 1
	v_fmamk_f32 v140, v140, 0x3a800000, v224
	v_rsq_f32_e32 v140, v140
	s_nop 0
	v_readlane_b32 s6, v140, 63
	s_nop 1
	v_pk_mul_f32 v[198:199], v[198:199], s[6:7] op_sel_hi:[1,0]
	v_pk_mul_f32 v[200:201], v[200:201], s[6:7] op_sel_hi:[1,0]
	v_pk_mul_f32 v[202:203], v[202:203], s[6:7] op_sel_hi:[1,0]
	v_pk_mul_f32 v[204:205], v[204:205], s[6:7] op_sel_hi:[1,0]
	v_pk_mul_f32 v[206:207], v[206:207], s[6:7] op_sel_hi:[1,0]
	v_pk_mul_f32 v[208:209], v[208:209], s[6:7] op_sel_hi:[1,0]
	v_pk_mul_f32 v[210:211], v[210:211], s[6:7] op_sel_hi:[1,0]
	v_pk_mul_f32 v[212:213], v[212:213], s[6:7] op_sel_hi:[1,0]
	v_pk_mul_f32 v[198:199], v[16:17], v[198:199]
	v_pk_mul_f32 v[200:201], v[18:19], v[200:201]
	v_pk_mul_f32 v[202:203], v[20:21], v[202:203]
	v_pk_mul_f32 v[204:205], v[22:23], v[204:205]
	v_pk_mul_f32 v[206:207], v[24:25], v[206:207]
	v_pk_mul_f32 v[208:209], v[26:27], v[208:209]
	v_pk_mul_f32 v[210:211], v[28:29], v[210:211]
	v_pk_mul_f32 v[212:213], v[30:31], v[212:213]
	v_pk_fma_f32 v[198:199], v[32:33], v[198:199], v[48:49]
	v_pk_fma_f32 v[200:201], v[34:35], v[200:201], v[50:51]
	v_pk_fma_f32 v[202:203], v[36:37], v[202:203], v[52:53]
	v_pk_fma_f32 v[204:205], v[38:39], v[204:205], v[54:55]
	v_pk_fma_f32 v[206:207], v[40:41], v[206:207], v[56:57]
	v_pk_fma_f32 v[208:209], v[42:43], v[208:209], v[58:59]
	v_pk_fma_f32 v[210:211], v[44:45], v[210:211], v[60:61]
	v_pk_fma_f32 v[212:213], v[46:47], v[212:213], v[62:63]
	v_cvt_pk_bf16_f32 v230, v198, v199
	v_cvt_pk_bf16_f32 v231, v200, v201
	v_cvt_pk_bf16_f32 v232, v202, v203
	v_cvt_pk_bf16_f32 v233, v204, v205
	v_cvt_pk_bf16_f32 v234, v206, v207
	v_cvt_pk_bf16_f32 v235, v208, v209
	v_cvt_pk_bf16_f32 v236, v210, v211
	v_cvt_pk_bf16_f32 v237, v212, v213
	global_store_dwordx4 v184, v[230:233], s[44:45] offset:-2048 sc1
	global_store_dwordx4 v184, v[234:237], s[44:45] offset:-1024 sc1
	s_waitcnt vmcnt(20)
	v_lshlrev_b32_e32 v116, 16, v164
	v_and_b32_e32 v117, 0xffff0000, v164
	v_lshlrev_b32_e32 v118, 16, v165
	v_and_b32_e32 v119, 0xffff0000, v165
	v_lshlrev_b32_e32 v120, 16, v166
	v_and_b32_e32 v121, 0xffff0000, v166
	v_lshlrev_b32_e32 v122, 16, v167
	v_and_b32_e32 v123, 0xffff0000, v167
	v_lshlrev_b32_e32 v124, 16, v168
	v_and_b32_e32 v125, 0xffff0000, v168
	v_lshlrev_b32_e32 v126, 16, v169
	v_and_b32_e32 v127, 0xffff0000, v169
	v_lshlrev_b32_e32 v128, 16, v170
	v_and_b32_e32 v129, 0xffff0000, v170
	v_lshlrev_b32_e32 v130, 16, v171
	v_and_b32_e32 v131, 0xffff0000, v171
	v_cvt_f32_f16_e32 v198, v80
	v_cvt_f32_f16_sdwa v199, v80 dst_sel:DWORD dst_unused:UNUSED_PAD src0_sel:WORD_1
	v_cvt_f32_f16_e32 v200, v81
	v_cvt_f32_f16_sdwa v201, v81 dst_sel:DWORD dst_unused:UNUSED_PAD src0_sel:WORD_1
	v_cvt_f32_f16_e32 v202, v82
	v_cvt_f32_f16_sdwa v203, v82 dst_sel:DWORD dst_unused:UNUSED_PAD src0_sel:WORD_1
	v_cvt_f32_f16_e32 v204, v83
	v_cvt_f32_f16_sdwa v205, v83 dst_sel:DWORD dst_unused:UNUSED_PAD src0_sel:WORD_1
	v_cvt_f32_f16_e32 v206, v84
	v_cvt_f32_f16_sdwa v207, v84 dst_sel:DWORD dst_unused:UNUSED_PAD src0_sel:WORD_1
	v_cvt_f32_f16_e32 v208, v85
	v_cvt_f32_f16_sdwa v209, v85 dst_sel:DWORD dst_unused:UNUSED_PAD src0_sel:WORD_1
	v_cvt_f32_f16_e32 v210, v86
	v_cvt_f32_f16_sdwa v211, v86 dst_sel:DWORD dst_unused:UNUSED_PAD src0_sel:WORD_1
	v_cvt_f32_f16_e32 v212, v87
	v_cvt_f32_f16_sdwa v213, v87 dst_sel:DWORD dst_unused:UNUSED_PAD src0_sel:WORD_1
	global_load_dwordx4 v[80:83], v185, s[42:43] offset:0
	global_load_dwordx4 v[84:87], v185, s[42:43] offset:1024
	global_load_dwordx4 v[164:167], v185, s[44:45] offset:0
	global_load_dwordx4 v[168:171], v185, s[44:45] offset:1024
	v_pk_mul_f32 v[140:141], v[116:117], v[116:117]
	v_pk_fma_f32 v[140:141], v[118:119], v[118:119], v[140:141]
	v_pk_fma_f32 v[140:141], v[120:121], v[120:121], v[140:141]
	v_pk_fma_f32 v[140:141], v[122:123], v[122:123], v[140:141]
	v_pk_fma_f32 v[140:141], v[124:125], v[124:125], v[140:141]
	v_pk_fma_f32 v[140:141], v[126:127], v[126:127], v[140:141]
	v_pk_fma_f32 v[140:141], v[128:129], v[128:129], v[140:141]
	v_pk_fma_f32 v[140:141], v[130:131], v[130:131], v[140:141]
	v_add_f32_e32 v140, v140, v141
	s_nop 1
	v_add_f32_dpp v140, v140, v140 quad_perm:[1,0,3,2] row_mask:0xf bank_mask:0xf
	s_nop 1
	v_add_f32_dpp v140, v140, v140 quad_perm:[2,3,0,1] row_mask:0xf bank_mask:0xf
	s_nop 1
	v_add_f32_dpp v140, v140, v140 row_ror:4 row_mask:0xf bank_mask:0xf
	s_nop 1
	v_add_f32_dpp v140, v140, v140 row_ror:8 row_mask:0xf bank_mask:0xf
	s_nop 1
	v_add_f32_dpp v140, v140, v140 row_bcast:15 row_mask:0xa bank_mask:0xf
	s_nop 1
	v_add_f32_dpp v140, v140, v140 row_bcast:31 row_mask:0xc bank_mask:0xf
	s_nop 1
	v_fmamk_f32 v140, v140, 0x3a800000, v224
	v_rsq_f32_e32 v140, v140
	s_nop 0
	v_mul_f32_e32 v140, v144, v140
	s_nop 0
	v_readlane_b32 s4, v140, 63
	s_nop 1
	v_pk_mul_f32 v[116:117], v[116:117], s[4:5] op_sel_hi:[1,0]
	v_pk_mul_f32 v[118:119], v[118:119], s[4:5] op_sel_hi:[1,0]
	v_pk_mul_f32 v[120:121], v[120:121], s[4:5] op_sel_hi:[1,0]
	v_pk_mul_f32 v[122:123], v[122:123], s[4:5] op_sel_hi:[1,0]
	v_pk_mul_f32 v[124:125], v[124:125], s[4:5] op_sel_hi:[1,0]
	v_pk_mul_f32 v[126:127], v[126:127], s[4:5] op_sel_hi:[1,0]
	v_pk_mul_f32 v[128:129], v[128:129], s[4:5] op_sel_hi:[1,0]
	v_pk_mul_f32 v[130:131], v[130:131], s[4:5] op_sel_hi:[1,0]
	v_pk_fma_f32 v[198:199], v[0:1], v[116:117], v[198:199]
	v_pk_fma_f32 v[200:201], v[2:3], v[118:119], v[200:201]
	v_pk_fma_f32 v[202:203], v[4:5], v[120:121], v[202:203]
; __device__ __forceinline__ unsigned pk2(float lo, float hi) { return pg8::cvt_pk_bf16(lo, hi); }
; __device__ __forceinline__ unsigned pkh2(float lo, float hi) { return (unsigned)__builtin_bit_cast(unsigned short, (_Float16)lo) | ((unsigned)__builtin_bit_cast(unsigned short, (_Float16)hi) << 16); }
; template <int R, bool SRCB> ...
;     ...
;                 for (int k = 0; k < 2; ++k) h[r][j][k] = h[r][j][k] + gg[j][k] * (y[j][k] * rr);
;         }
;     }
; #pragma unroll
;     for (int r = 0; r < R; ++r)
; #pragma unroll
;         for (int j = 0; j < 2; ++j) { const int c = 8 * lane + 512 * j;
;             if (final_out) { *(f32x4*)(final_out + (size_t)(row0 + r) * DM + c) = h[r][j][0]; *(f32x4*)(final_out + (size_t)(row0 + r) * DM + c + 4) = h[r][j][1]; }
;             else { u32x4 t; t.x = pkh2(h[r][j][0][0], h[r][j][0][1]); t.y = pkh2(h[r][j][0][2], h[r][j][0][3]); t.z = pkh2(h[r][j][1][0], h[r][j][1][1]); t.w = pkh2(h[r][j][1][2], h[r][j][1][3]);
;                 *(u32x4*)(hout + (size_t)(row0 + r) * DM + c) = t; } }
;     if (U) {
;         f32x4 gp[2][2], sc1[2][2], sh[2][2];
; #pragma unroll
;         for (int j = 0; j < 2; ++j)
; #pragma unroll
;             for (int k = 0; k < 2; ++k) { const int c = 8 * lane + 512 * j + 4 * k; gp[j][k] = *(const f32x4*)(gpre + c); sc1[j][k] = *(const f32x4*)(scale + (size_t)mrow * 9216 + c) + 1.0f; sh[j][k] = *(const f32x4*)(shift + (size_t)mrow * 9216 + c); }
; #pragma unroll
;         for (int r = 0; r < R; ++r) {
;             float ss = 0.f;
; #pragma unroll
;             for (int j = 0; j < 2; ++j)
; #pragma unroll
;                 for (int k = 0; k < 2; ++k) ss += (h[r][j][k][0] * h[r][j][k][0] + h[r][j][k][1] * h[r][j][k][1]) + (h[r][j][k][2] * h[r][j][k][2] + h[r][j][k][3] * h[r][j][k][3]);
;             const float rr = __builtin_amdgcn_rsqf(wave_sum(ss) * (1.0f / DM) + 1e-6f);
; #pragma unroll
;             for (int j = 0; j < 2; ++j) { const f32x4 v0 = (h[r][j][0] * rr * gp[j][0]) * sc1[j][0] + sh[j][0], v1 = (h[r][j][1] * rr * gp[j][1]) * sc1[j][1] + sh[j][1];
;                 u32x4 t; t.x = pk2(v0[0], v0[1]); t.y = pk2(v0[2], v0[3]); t.z = pk2(v1[0], v1[1]); t.w = pk2(v1[2], v1[3]);
;                 *(u32x4*)(U + (size_t)(row0 + r) * DM + 8 * lane + 512 * j) = t; }
	v_pk_fma_f32 v[204:205], v[6:7], v[122:123], v[204:205]
	v_pk_fma_f32 v[206:207], v[8:9], v[124:125], v[206:207]
	v_pk_fma_f32 v[208:209], v[10:11], v[126:127], v[208:209]
	v_pk_fma_f32 v[210:211], v[12:13], v[128:129], v[210:211]
	v_pk_fma_f32 v[212:213], v[14:15], v[130:131], v[212:213]
	v_cvt_f16_f32_e32 v132, v198
	v_cvt_f16_f32_e32 v133, v200
	v_cvt_f16_f32_e32 v134, v202
	v_cvt_f16_f32_e32 v135, v204
	v_cvt_f16_f32_e32 v136, v206
	v_cvt_f16_f32_e32 v137, v208
	v_cvt_f16_f32_e32 v138, v210
	v_cvt_f16_f32_e32 v139, v212
	v_cvt_f16_f32_sdwa v132, v199 dst_sel:WORD_1 dst_unused:UNUSED_PRESERVE src0_sel:DWORD
	v_cvt_f16_f32_sdwa v133, v201 dst_sel:WORD_1 dst_unused:UNUSED_PRESERVE src0_sel:DWORD
	v_cvt_f16_f32_sdwa v134, v203 dst_sel:WORD_1 dst_unused:UNUSED_PRESERVE src0_sel:DWORD
	v_cvt_f16_f32_sdwa v135, v205 dst_sel:WORD_1 dst_unused:UNUSED_PRESERVE src0_sel:DWORD
	v_cvt_f16_f32_sdwa v136, v207 dst_sel:WORD_1 dst_unused:UNUSED_PRESERVE src0_sel:DWORD
	v_cvt_f16_f32_sdwa v137, v209 dst_sel:WORD_1 dst_unused:UNUSED_PRESERVE src0_sel:DWORD
	v_cvt_f16_f32_sdwa v138, v211 dst_sel:WORD_1 dst_unused:UNUSED_PRESERVE src0_sel:DWORD
	v_cvt_f16_f32_sdwa v139, v213 dst_sel:WORD_1 dst_unused:UNUSED_PRESERVE src0_sel:DWORD
	s_nop 0
	global_store_dwordx4 v184, v[132:135], s[42:43] offset:0 sc1
	global_store_dwordx4 v184, v[136:139], s[42:43] offset:1024 sc1
	v_pk_mul_f32 v[140:141], v[198:199], v[198:199]
	v_pk_fma_f32 v[140:141], v[200:201], v[200:201], v[140:141]
	v_pk_fma_f32 v[140:141], v[202:203], v[202:203], v[140:141]
	v_pk_fma_f32 v[140:141], v[204:205], v[204:205], v[140:141]
	v_pk_fma_f32 v[140:141], v[206:207], v[206:207], v[140:141]
	v_pk_fma_f32 v[140:141], v[208:209], v[208:209], v[140:141]
	v_pk_fma_f32 v[140:141], v[210:211], v[210:211], v[140:141]
	v_pk_fma_f32 v[140:141], v[212:213], v[212:213], v[140:141]
	v_add_f32_e32 v140, v140, v141
	s_nop 1
	v_add_f32_dpp v140, v140, v140 quad_perm:[1,0,3,2] row_mask:0xf bank_mask:0xf
	s_nop 1
	v_add_f32_dpp v140, v140, v140 quad_perm:[2,3,0,1] row_mask:0xf bank_mask:0xf
	s_nop 1
	v_add_f32_dpp v140, v140, v140 row_ror:4 row_mask:0xf bank_mask:0xf
	s_nop 1
	v_add_f32_dpp v140, v140, v140 row_ror:8 row_mask:0xf bank_mask:0xf
	s_nop 1
	v_add_f32_dpp v140, v140, v140 row_bcast:15 row_mask:0xa bank_mask:0xf
	s_nop 1
	v_add_f32_dpp v140, v140, v140 row_bcast:31 row_mask:0xc bank_mask:0xf
	s_nop 1
	v_fmamk_f32 v140, v140, 0x3a800000, v224
	v_rsq_f32_e32 v140, v140
	s_nop 0
	v_readlane_b32 s6, v140, 63
	s_nop 1
	v_pk_mul_f32 v[198:199], v[198:199], s[6:7] op_sel_hi:[1,0]
	v_pk_mul_f32 v[200:201], v[200:201], s[6:7] op_sel_hi:[1,0]
	v_pk_mul_f32 v[202:203], v[202:203], s[6:7] op_sel_hi:[1,0]
	v_pk_mul_f32 v[204:205], v[204:205], s[6:7] op_sel_hi:[1,0]
	v_pk_mul_f32 v[206:207], v[206:207], s[6:7] op_sel_hi:[1,0]
	v_pk_mul_f32 v[208:209], v[208:209], s[6:7] op_sel_hi:[1,0]
	v_pk_mul_f32 v[210:211], v[210:211], s[6:7] op_sel_hi:[1,0]
	v_pk_mul_f32 v[212:213], v[212:213], s[6:7] op_sel_hi:[1,0]
	v_pk_mul_f32 v[198:199], v[16:17], v[198:199]
	v_pk_mul_f32 v[200:201], v[18:19], v[200:201]
	v_pk_mul_f32 v[202:203], v[20:21], v[202:203]
	v_pk_mul_f32 v[204:205], v[22:23], v[204:205]
	v_pk_mul_f32 v[206:207], v[24:25], v[206:207]
	v_pk_mul_f32 v[208:209], v[26:27], v[208:209]
	v_pk_mul_f32 v[210:211], v[28:29], v[210:211]
	v_pk_mul_f32 v[212:213], v[30:31], v[212:213]
	v_pk_fma_f32 v[198:199], v[32:33], v[198:199], v[48:49]
	v_pk_fma_f32 v[200:201], v[34:35], v[200:201], v[50:51]
	v_pk_fma_f32 v[202:203], v[36:37], v[202:203], v[52:53]
	v_pk_fma_f32 v[204:205], v[38:39], v[204:205], v[54:55]
	v_pk_fma_f32 v[206:207], v[40:41], v[206:207], v[56:57]
	v_pk_fma_f32 v[208:209], v[42:43], v[208:209], v[58:59]
	v_pk_fma_f32 v[210:211], v[44:45], v[210:211], v[60:61]
	v_pk_fma_f32 v[212:213], v[46:47], v[212:213], v[62:63]
	v_cvt_pk_bf16_f32 v230, v198, v199
	v_cvt_pk_bf16_f32 v231, v200, v201
	v_cvt_pk_bf16_f32 v232, v202, v203
	v_cvt_pk_bf16_f32 v233, v204, v205
	v_cvt_pk_bf16_f32 v234, v206, v207
	v_cvt_pk_bf16_f32 v235, v208, v209
	v_cvt_pk_bf16_f32 v236, v210, v211
	v_cvt_pk_bf16_f32 v237, v212, v213
	global_store_dwordx4 v184, v[230:233], s[44:45] offset:0 sc1
	global_store_dwordx4 v184, v[234:237], s[44:45] offset:1024 sc1
	s_waitcnt vmcnt(24)
; __device__ __forceinline__ float bf_lo(unsigned w) { return __uint_as_float(w << 16); }
; template <int R, bool SRCB> ...
;     ...
;             for (int j = 0; j < 2; ++j) { const u32x4 t = yr[r][j];
;                 y[j][0] = (f32x4){bf_lo(t.x), bf_hi(t.x), bf_lo(t.y), bf_hi(t.y)}; y[j][1] = (f32x4){bf_lo(t.z), bf_hi(t.z), bf_lo(t.w), bf_hi(t.w)};
;                 if (R == 1 && YP) {
; #pragma unroll
;                     for (int k = 0; k < 2; ++k) { const float* pp = YP + (size_t)(row0 - M_LAT) * DM + 8 * lane + 512 * j + 4 * k; f32x4 s = *(const f32x4*)pp;
; #pragma unroll
;                         for (int q = 1; q < pg8::NSL; ++q) s = s + *(const f32x4*)(pp + (size_t)q * 2048 * DM);
;                         y[j][k] = s; } }
; #pragma unroll
;                 for (int k = 0; k < 2; ++k) ss += (y[j][k][0] * y[j][k][0] + y[j][k][1] * y[j][k][1]) + (y[j][k][2] * y[j][k][2] + y[j][k][3] * y[j][k][3]); }
;             const float rr = __builtin_amdgcn_rsqf(wave_sum(ss) * (1.0f / DM) + 1e-6f) * w;
; #pragma unroll
;             for (int j = 0; j < 2; ++j)
; #pragma unroll
;                 for (int k = 0; k < 2; ++k) h[r][j][k] = h[r][j][k] + gg[j][k] * (y[j][k] * rr);
;         }
;     }
; #pragma unroll
;     for (int r = 0; r < R; ++r)
; #pragma unroll
;         for (int j = 0; j < 2; ++j) { const int c = 8 * lane + 512 * j;
;             if (final_out) { *(f32x4*)(final_out + (size_t)(row0 + r) * DM + c) = h[r][j][0]; *(f32x4*)(final_out + (size_t)(row0 + r) * DM + c + 4) = h[r][j][1]; }
;             else { u32x4 t; t.x = pkh2(h[r][j][0][0], h[r][j][0][1]); t.y = pkh2(h[r][j][0][2], h[r][j][0][3]); t.z = pkh2(h[r][j][1][0], h[r][j][1][1]); t.w = pkh2(h[r][j][1][2], h[r][j][1][3]);
;                 *(u32x4*)(hout + (size_t)(row0 + r) * DM + c) = t; } }
;     if (U) {
;         f32x4 gp[2][2], sc1[2][2], sh[2][2];
; #pragma unroll
;         for (int j = 0; j < 2; ++j)
; #pragma unroll
;             for (int k = 0; k < 2; ++k) { const int c = 8 * lane + 512 * j + 4 * k; gp[j][k] = *(const f32x4*)(gpre + c); sc1[j][k] = *(const f32x4*)(scale + (size_t)mrow * 9216 + c) + 1.0f; sh[j][k] = *(const f32x4*)(shift + (size_t)mrow * 9216 + c); }
; #pragma unroll
;         for (int r = 0; r < R; ++r) {
;             float ss = 0.f;
; #pragma unroll
;             for (int j = 0; j < 2; ++j)
; #pragma unroll
	v_lshlrev_b32_e32 v116, 16, v172
	v_and_b32_e32 v117, 0xffff0000, v172
	v_lshlrev_b32_e32 v118, 16, v173
	v_and_b32_e32 v119, 0xffff0000, v173
	v_lshlrev_b32_e32 v120, 16, v174
	v_and_b32_e32 v121, 0xffff0000, v174
	v_lshlrev_b32_e32 v122, 16, v175
	v_and_b32_e32 v123, 0xffff0000, v175
	v_lshlrev_b32_e32 v124, 16, v176
	v_and_b32_e32 v125, 0xffff0000, v176
	v_lshlrev_b32_e32 v126, 16, v177
	v_and_b32_e32 v127, 0xffff0000, v177
	v_lshlrev_b32_e32 v128, 16, v178
	v_and_b32_e32 v129, 0xffff0000, v178
	v_lshlrev_b32_e32 v130, 16, v179
	v_and_b32_e32 v131, 0xffff0000, v179
	v_cvt_f32_f16_e32 v198, v88
	v_cvt_f32_f16_sdwa v199, v88 dst_sel:DWORD dst_unused:UNUSED_PAD src0_sel:WORD_1
	v_cvt_f32_f16_e32 v200, v89
	v_cvt_f32_f16_sdwa v201, v89 dst_sel:DWORD dst_unused:UNUSED_PAD src0_sel:WORD_1
	v_cvt_f32_f16_e32 v202, v90
	v_cvt_f32_f16_sdwa v203, v90 dst_sel:DWORD dst_unused:UNUSED_PAD src0_sel:WORD_1
	v_cvt_f32_f16_e32 v204, v91
	v_cvt_f32_f16_sdwa v205, v91 dst_sel:DWORD dst_unused:UNUSED_PAD src0_sel:WORD_1
	v_cvt_f32_f16_e32 v206, v92
	v_cvt_f32_f16_sdwa v207, v92 dst_sel:DWORD dst_unused:UNUSED_PAD src0_sel:WORD_1
	v_cvt_f32_f16_e32 v208, v93
	v_cvt_f32_f16_sdwa v209, v93 dst_sel:DWORD dst_unused:UNUSED_PAD src0_sel:WORD_1
	v_cvt_f32_f16_e32 v210, v94
	v_cvt_f32_f16_sdwa v211, v94 dst_sel:DWORD dst_unused:UNUSED_PAD src0_sel:WORD_1
	v_cvt_f32_f16_e32 v212, v95
	v_cvt_f32_f16_sdwa v213, v95 dst_sel:DWORD dst_unused:UNUSED_PAD src0_sel:WORD_1
	global_load_dwordx4 v[88:91], v185, s[42:43] offset:2048
	global_load_dwordx4 v[92:95], v185, s[42:43] offset:3072
	global_load_dwordx4 v[172:175], v185, s[44:45] offset:2048
	global_load_dwordx4 v[176:179], v185, s[44:45] offset:3072
	v_pk_mul_f32 v[140:141], v[116:117], v[116:117]
	v_pk_fma_f32 v[140:141], v[118:119], v[118:119], v[140:141]
	v_pk_fma_f32 v[140:141], v[120:121], v[120:121], v[140:141]
	v_pk_fma_f32 v[140:141], v[122:123], v[122:123], v[140:141]
	v_pk_fma_f32 v[140:141], v[124:125], v[124:125], v[140:141]
	v_pk_fma_f32 v[140:141], v[126:127], v[126:127], v[140:141]
	v_pk_fma_f32 v[140:141], v[128:129], v[128:129], v[140:141]
	v_pk_fma_f32 v[140:141], v[130:131], v[130:131], v[140:141]
	v_add_f32_e32 v140, v140, v141
	s_nop 1
	v_add_f32_dpp v140, v140, v140 quad_perm:[1,0,3,2] row_mask:0xf bank_mask:0xf
	s_nop 1
	v_add_f32_dpp v140, v140, v140 quad_perm:[2,3,0,1] row_mask:0xf bank_mask:0xf
	s_nop 1
	v_add_f32_dpp v140, v140, v140 row_ror:4 row_mask:0xf bank_mask:0xf
	s_nop 1
	v_add_f32_dpp v140, v140, v140 row_ror:8 row_mask:0xf bank_mask:0xf
	s_nop 1
	v_add_f32_dpp v140, v140, v140 row_bcast:15 row_mask:0xa bank_mask:0xf
	s_nop 1
	v_add_f32_dpp v140, v140, v140 row_bcast:31 row_mask:0xc bank_mask:0xf
	s_nop 1
	v_fmamk_f32 v140, v140, 0x3a800000, v224
	v_rsq_f32_e32 v140, v140
	s_nop 0
	v_mul_f32_e32 v140, v144, v140
	s_nop 0
	v_readlane_b32 s4, v140, 63
	s_nop 1
	v_pk_mul_f32 v[116:117], v[116:117], s[4:5] op_sel_hi:[1,0]
	v_pk_mul_f32 v[118:119], v[118:119], s[4:5] op_sel_hi:[1,0]
	v_pk_mul_f32 v[120:121], v[120:121], s[4:5] op_sel_hi:[1,0]
	v_pk_mul_f32 v[122:123], v[122:123], s[4:5] op_sel_hi:[1,0]
	v_pk_mul_f32 v[124:125], v[124:125], s[4:5] op_sel_hi:[1,0]
	v_pk_mul_f32 v[126:127], v[126:127], s[4:5] op_sel_hi:[1,0]
	v_pk_mul_f32 v[128:129], v[128:129], s[4:5] op_sel_hi:[1,0]
	v_pk_mul_f32 v[130:131], v[130:131], s[4:5] op_sel_hi:[1,0]
	v_pk_fma_f32 v[198:199], v[0:1], v[116:117], v[198:199]
	v_pk_fma_f32 v[200:201], v[2:3], v[118:119], v[200:201]
	v_pk_fma_f32 v[202:203], v[4:5], v[120:121], v[202:203]
	v_pk_fma_f32 v[204:205], v[6:7], v[122:123], v[204:205]
	v_pk_fma_f32 v[206:207], v[8:9], v[124:125], v[206:207]
	v_pk_fma_f32 v[208:209], v[10:11], v[126:127], v[208:209]
	v_pk_fma_f32 v[210:211], v[12:13], v[128:129], v[210:211]
	v_pk_fma_f32 v[212:213], v[14:15], v[130:131], v[212:213]
	v_cvt_f16_f32_e32 v132, v198
	v_cvt_f16_f32_e32 v133, v200
	v_cvt_f16_f32_e32 v134, v202
	v_cvt_f16_f32_e32 v135, v204
	v_cvt_f16_f32_e32 v136, v206
	v_cvt_f16_f32_e32 v137, v208
	v_cvt_f16_f32_e32 v138, v210
	v_cvt_f16_f32_e32 v139, v212
	v_cvt_f16_f32_sdwa v132, v199 dst_sel:WORD_1 dst_unused:UNUSED_PRESERVE src0_sel:DWORD
	v_cvt_f16_f32_sdwa v133, v201 dst_sel:WORD_1 dst_unused:UNUSED_PRESERVE src0_sel:DWORD
	v_cvt_f16_f32_sdwa v134, v203 dst_sel:WORD_1 dst_unused:UNUSED_PRESERVE src0_sel:DWORD
	v_cvt_f16_f32_sdwa v135, v205 dst_sel:WORD_1 dst_unused:UNUSED_PRESERVE src0_sel:DWORD
	v_cvt_f16_f32_sdwa v136, v207 dst_sel:WORD_1 dst_unused:UNUSED_PRESERVE src0_sel:DWORD
	v_cvt_f16_f32_sdwa v137, v209 dst_sel:WORD_1 dst_unused:UNUSED_PRESERVE src0_sel:DWORD
	v_cvt_f16_f32_sdwa v138, v211 dst_sel:WORD_1 dst_unused:UNUSED_PRESERVE src0_sel:DWORD
	v_cvt_f16_f32_sdwa v139, v213 dst_sel:WORD_1 dst_unused:UNUSED_PRESERVE src0_sel:DWORD
	s_nop 0
	global_store_dwordx4 v184, v[132:135], s[42:43] offset:2048 sc1
	global_store_dwordx4 v184, v[136:139], s[42:43] offset:3072 sc1
	v_pk_mul_f32 v[140:141], v[198:199], v[198:199]
	v_pk_fma_f32 v[140:141], v[200:201], v[200:201], v[140:141]
	v_pk_fma_f32 v[140:141], v[202:203], v[202:203], v[140:141]
	v_pk_fma_f32 v[140:141], v[204:205], v[204:205], v[140:141]
	v_pk_fma_f32 v[140:141], v[206:207], v[206:207], v[140:141]
	v_pk_fma_f32 v[140:141], v[208:209], v[208:209], v[140:141]
	v_pk_fma_f32 v[140:141], v[210:211], v[210:211], v[140:141]
	v_pk_fma_f32 v[140:141], v[212:213], v[212:213], v[140:141]
	v_add_f32_e32 v140, v140, v141
	s_nop 1
	v_add_f32_dpp v140, v140, v140 quad_perm:[1,0,3,2] row_mask:0xf bank_mask:0xf
	s_nop 1
	v_add_f32_dpp v140, v140, v140 quad_perm:[2,3,0,1] row_mask:0xf bank_mask:0xf
	s_nop 1
	v_add_f32_dpp v140, v140, v140 row_ror:4 row_mask:0xf bank_mask:0xf
; __device__ __forceinline__ float bf_lo(unsigned w) { return __uint_as_float(w << 16); }
; template <int R, bool SRCB> ...
;     ...
;             for (int j = 0; j < 2; ++j) { const u32x4 t = yr[r][j];
;                 y[j][0] = (f32x4){bf_lo(t.x), bf_hi(t.x), bf_lo(t.y), bf_hi(t.y)}; y[j][1] = (f32x4){bf_lo(t.z), bf_hi(t.z), bf_lo(t.w), bf_hi(t.w)};
;                 if (R == 1 && YP) {
; #pragma unroll
;                     for (int k = 0; k < 2; ++k) { const float* pp = YP + (size_t)(row0 - M_LAT) * DM + 8 * lane + 512 * j + 4 * k; f32x4 s = *(const f32x4*)pp;
; #pragma unroll
;                         for (int q = 1; q < pg8::NSL; ++q) s = s + *(const f32x4*)(pp + (size_t)q * 2048 * DM);
;                         y[j][k] = s; } }
; #pragma unroll
;                 for (int k = 0; k < 2; ++k) ss += (y[j][k][0] * y[j][k][0] + y[j][k][1] * y[j][k][1]) + (y[j][k][2] * y[j][k][2] + y[j][k][3] * y[j][k][3]); }
;             const float rr = __builtin_amdgcn_rsqf(wave_sum(ss) * (1.0f / DM) + 1e-6f) * w;
; #pragma unroll
;             for (int j = 0; j < 2; ++j)
; #pragma unroll
;                 for (int k = 0; k < 2; ++k) h[r][j][k] = h[r][j][k] + gg[j][k] * (y[j][k] * rr);
;         }
;     }
; #pragma unroll
;     for (int r = 0; r < R; ++r)
; #pragma unroll
;         for (int j = 0; j < 2; ++j) { const int c = 8 * lane + 512 * j;
;             if (final_out) { *(f32x4*)(final_out + (size_t)(row0 + r) * DM + c) = h[r][j][0]; *(f32x4*)(final_out + (size_t)(row0 + r) * DM + c + 4) = h[r][j][1]; }
;             else { u32x4 t; t.x = pkh2(h[r][j][0][0], h[r][j][0][1]); t.y = pkh2(h[r][j][0][2], h[r][j][0][3]); t.z = pkh2(h[r][j][1][0], h[r][j][1][1]); t.w = pkh2(h[r][j][1][2], h[r][j][1][3]);
;                 *(u32x4*)(hout + (size_t)(row0 + r) * DM + c) = t; } }
;     if (U) {
;         f32x4 gp[2][2], sc1[2][2], sh[2][2];
; #pragma unroll
;         for (int j = 0; j < 2; ++j)
; #pragma unroll
;             for (int k = 0; k < 2; ++k) { const int c = 8 * lane + 512 * j + 4 * k; gp[j][k] = *(const f32x4*)(gpre + c); sc1[j][k] = *(const f32x4*)(scale + (size_t)mrow * 9216 + c) + 1.0f; sh[j][k] = *(const f32x4*)(shift + (size_t)mrow * 9216 + c); }
; #pragma unroll
;         for (int r = 0; r < R; ++r) {
;             float ss = 0.f;
; #pragma unroll
;             for (int j = 0; j < 2; ++j)
; #pragma unroll
	s_nop 1
	v_add_f32_dpp v140, v140, v140 row_ror:8 row_mask:0xf bank_mask:0xf
	s_nop 1
	v_add_f32_dpp v140, v140, v140 row_bcast:15 row_mask:0xa bank_mask:0xf
	s_nop 1
	v_add_f32_dpp v140, v140, v140 row_bcast:31 row_mask:0xc bank_mask:0xf
	s_nop 1
	v_fmamk_f32 v140, v140, 0x3a800000, v224
	v_rsq_f32_e32 v140, v140
	s_nop 0
	v_readlane_b32 s6, v140, 63
	s_nop 1
	v_pk_mul_f32 v[198:199], v[198:199], s[6:7] op_sel_hi:[1,0]
	v_pk_mul_f32 v[200:201], v[200:201], s[6:7] op_sel_hi:[1,0]
	v_pk_mul_f32 v[202:203], v[202:203], s[6:7] op_sel_hi:[1,0]
	v_pk_mul_f32 v[204:205], v[204:205], s[6:7] op_sel_hi:[1,0]
	v_pk_mul_f32 v[206:207], v[206:207], s[6:7] op_sel_hi:[1,0]
	v_pk_mul_f32 v[208:209], v[208:209], s[6:7] op_sel_hi:[1,0]
	v_pk_mul_f32 v[210:211], v[210:211], s[6:7] op_sel_hi:[1,0]
	v_pk_mul_f32 v[212:213], v[212:213], s[6:7] op_sel_hi:[1,0]
	v_pk_mul_f32 v[198:199], v[16:17], v[198:199]
	v_pk_mul_f32 v[200:201], v[18:19], v[200:201]
	v_pk_mul_f32 v[202:203], v[20:21], v[202:203]
	v_pk_mul_f32 v[204:205], v[22:23], v[204:205]
	v_pk_mul_f32 v[206:207], v[24:25], v[206:207]
	v_pk_mul_f32 v[208:209], v[26:27], v[208:209]
	v_pk_mul_f32 v[210:211], v[28:29], v[210:211]
	v_pk_mul_f32 v[212:213], v[30:31], v[212:213]
	v_pk_fma_f32 v[198:199], v[32:33], v[198:199], v[48:49]
	v_pk_fma_f32 v[200:201], v[34:35], v[200:201], v[50:51]
	v_pk_fma_f32 v[202:203], v[36:37], v[202:203], v[52:53]
	v_pk_fma_f32 v[204:205], v[38:39], v[204:205], v[54:55]
	v_pk_fma_f32 v[206:207], v[40:41], v[206:207], v[56:57]
	v_pk_fma_f32 v[208:209], v[42:43], v[208:209], v[58:59]
	v_pk_fma_f32 v[210:211], v[44:45], v[210:211], v[60:61]
	v_pk_fma_f32 v[212:213], v[46:47], v[212:213], v[62:63]
	v_cvt_pk_bf16_f32 v230, v198, v199
	v_cvt_pk_bf16_f32 v231, v200, v201
	v_cvt_pk_bf16_f32 v232, v202, v203
	v_cvt_pk_bf16_f32 v233, v204, v205
	v_cvt_pk_bf16_f32 v234, v206, v207
	v_cvt_pk_bf16_f32 v235, v208, v209
	v_cvt_pk_bf16_f32 v236, v210, v211
	v_cvt_pk_bf16_f32 v237, v212, v213
	global_store_dwordx4 v184, v[230:233], s[44:45] offset:2048 sc1
	global_store_dwordx4 v184, v[234:237], s[44:45] offset:3072 sc1
	s_waitcnt vmcnt(28)
	v_lshlrev_b32_e32 v116, 16, v148
	v_and_b32_e32 v117, 0xffff0000, v148
	v_lshlrev_b32_e32 v118, 16, v149
	v_and_b32_e32 v119, 0xffff0000, v149
	v_lshlrev_b32_e32 v120, 16, v150
	v_and_b32_e32 v121, 0xffff0000, v150
	v_lshlrev_b32_e32 v122, 16, v151
	v_and_b32_e32 v123, 0xffff0000, v151
	v_lshlrev_b32_e32 v124, 16, v152
	v_and_b32_e32 v125, 0xffff0000, v152
	v_lshlrev_b32_e32 v126, 16, v153
	v_and_b32_e32 v127, 0xffff0000, v153
	v_lshlrev_b32_e32 v128, 16, v154
	v_and_b32_e32 v129, 0xffff0000, v154
	v_lshlrev_b32_e32 v130, 16, v155
	v_and_b32_e32 v131, 0xffff0000, v155
	v_cvt_f32_f16_e32 v198, v64
	v_cvt_f32_f16_sdwa v199, v64 dst_sel:DWORD dst_unused:UNUSED_PAD src0_sel:WORD_1
	v_cvt_f32_f16_e32 v200, v65
	v_cvt_f32_f16_sdwa v201, v65 dst_sel:DWORD dst_unused:UNUSED_PAD src0_sel:WORD_1
	v_cvt_f32_f16_e32 v202, v66
	v_cvt_f32_f16_sdwa v203, v66 dst_sel:DWORD dst_unused:UNUSED_PAD src0_sel:WORD_1
	v_cvt_f32_f16_e32 v204, v67
	v_cvt_f32_f16_sdwa v205, v67 dst_sel:DWORD dst_unused:UNUSED_PAD src0_sel:WORD_1
	v_cvt_f32_f16_e32 v206, v68
	v_cvt_f32_f16_sdwa v207, v68 dst_sel:DWORD dst_unused:UNUSED_PAD src0_sel:WORD_1
	v_cvt_f32_f16_e32 v208, v69
	v_cvt_f32_f16_sdwa v209, v69 dst_sel:DWORD dst_unused:UNUSED_PAD src0_sel:WORD_1
	v_cvt_f32_f16_e32 v210, v70
	v_cvt_f32_f16_sdwa v211, v70 dst_sel:DWORD dst_unused:UNUSED_PAD src0_sel:WORD_1
	v_cvt_f32_f16_e32 v212, v71
	v_cvt_f32_f16_sdwa v213, v71 dst_sel:DWORD dst_unused:UNUSED_PAD src0_sel:WORD_1
	global_load_dwordx4 v[64:67], v186, s[42:43] offset:-4096
	global_load_dwordx4 v[68:71], v186, s[42:43] offset:-3072
	global_load_dwordx4 v[148:151], v186, s[44:45] offset:-4096
	global_load_dwordx4 v[152:155], v186, s[44:45] offset:-3072
	v_pk_mul_f32 v[140:141], v[116:117], v[116:117]
	v_pk_fma_f32 v[140:141], v[118:119], v[118:119], v[140:141]
	v_pk_fma_f32 v[140:141], v[120:121], v[120:121], v[140:141]
	v_pk_fma_f32 v[140:141], v[122:123], v[122:123], v[140:141]
	v_pk_fma_f32 v[140:141], v[124:125], v[124:125], v[140:141]
	v_pk_fma_f32 v[140:141], v[126:127], v[126:127], v[140:141]
	v_pk_fma_f32 v[140:141], v[128:129], v[128:129], v[140:141]
	v_pk_fma_f32 v[140:141], v[130:131], v[130:131], v[140:141]
	v_add_f32_e32 v140, v140, v141
	s_nop 1
	v_add_f32_dpp v140, v140, v140 quad_perm:[1,0,3,2] row_mask:0xf bank_mask:0xf
	s_nop 1
	v_add_f32_dpp v140, v140, v140 quad_perm:[2,3,0,1] row_mask:0xf bank_mask:0xf
	s_nop 1
	v_add_f32_dpp v140, v140, v140 row_ror:4 row_mask:0xf bank_mask:0xf
	s_nop 1
	v_add_f32_dpp v140, v140, v140 row_ror:8 row_mask:0xf bank_mask:0xf
	s_nop 1
	v_add_f32_dpp v140, v140, v140 row_bcast:15 row_mask:0xa bank_mask:0xf
	s_nop 1
	v_add_f32_dpp v140, v140, v140 row_bcast:31 row_mask:0xc bank_mask:0xf
	s_nop 1
	v_fmamk_f32 v140, v140, 0x3a800000, v224
	v_rsq_f32_e32 v140, v140
	s_nop 0
	v_mul_f32_e32 v140, v144, v140
	s_nop 0
	v_readlane_b32 s4, v140, 63
	s_nop 1
	v_pk_mul_f32 v[116:117], v[116:117], s[4:5] op_sel_hi:[1,0]
	v_pk_mul_f32 v[118:119], v[118:119], s[4:5] op_sel_hi:[1,0]
	v_pk_mul_f32 v[120:121], v[120:121], s[4:5] op_sel_hi:[1,0]
	v_pk_mul_f32 v[122:123], v[122:123], s[4:5] op_sel_hi:[1,0]
	v_pk_mul_f32 v[124:125], v[124:125], s[4:5] op_sel_hi:[1,0]
	v_pk_mul_f32 v[126:127], v[126:127], s[4:5] op_sel_hi:[1,0]
	v_pk_mul_f32 v[128:129], v[128:129], s[4:5] op_sel_hi:[1,0]
	v_pk_mul_f32 v[130:131], v[130:131], s[4:5] op_sel_hi:[1,0]
	v_pk_fma_f32 v[198:199], v[0:1], v[116:117], v[198:199]
	v_pk_fma_f32 v[200:201], v[2:3], v[118:119], v[200:201]
	v_pk_fma_f32 v[202:203], v[4:5], v[120:121], v[202:203]
; __device__ __forceinline__ unsigned pk2(float lo, float hi) { return pg8::cvt_pk_bf16(lo, hi); }
; __device__ __forceinline__ unsigned pkh2(float lo, float hi) { return (unsigned)__builtin_bit_cast(unsigned short, (_Float16)lo) | ((unsigned)__builtin_bit_cast(unsigned short, (_Float16)hi) << 16); }
; template <int R, bool SRCB> ...
;     ...
;                 for (int k = 0; k < 2; ++k) h[r][j][k] = h[r][j][k] + gg[j][k] * (y[j][k] * rr);
;         }
;     }
; #pragma unroll
;     for (int r = 0; r < R; ++r)
; #pragma unroll
;         for (int j = 0; j < 2; ++j) { const int c = 8 * lane + 512 * j;
;             if (final_out) { *(f32x4*)(final_out + (size_t)(row0 + r) * DM + c) = h[r][j][0]; *(f32x4*)(final_out + (size_t)(row0 + r) * DM + c + 4) = h[r][j][1]; }
;             else { u32x4 t; t.x = pkh2(h[r][j][0][0], h[r][j][0][1]); t.y = pkh2(h[r][j][0][2], h[r][j][0][3]); t.z = pkh2(h[r][j][1][0], h[r][j][1][1]); t.w = pkh2(h[r][j][1][2], h[r][j][1][3]);
;                 *(u32x4*)(hout + (size_t)(row0 + r) * DM + c) = t; } }
;     if (U) {
;         f32x4 gp[2][2], sc1[2][2], sh[2][2];
; #pragma unroll
;         for (int j = 0; j < 2; ++j)
; #pragma unroll
;             for (int k = 0; k < 2; ++k) { const int c = 8 * lane + 512 * j + 4 * k; gp[j][k] = *(const f32x4*)(gpre + c); sc1[j][k] = *(const f32x4*)(scale + (size_t)mrow * 9216 + c) + 1.0f; sh[j][k] = *(const f32x4*)(shift + (size_t)mrow * 9216 + c); }
; #pragma unroll
;         for (int r = 0; r < R; ++r) {
;             float ss = 0.f;
; #pragma unroll
;             for (int j = 0; j < 2; ++j)
; #pragma unroll
;                 for (int k = 0; k < 2; ++k) ss += (h[r][j][k][0] * h[r][j][k][0] + h[r][j][k][1] * h[r][j][k][1]) + (h[r][j][k][2] * h[r][j][k][2] + h[r][j][k][3] * h[r][j][k][3]);
;             const float rr = __builtin_amdgcn_rsqf(wave_sum(ss) * (1.0f / DM) + 1e-6f);
; #pragma unroll
;             for (int j = 0; j < 2; ++j) { const f32x4 v0 = (h[r][j][0] * rr * gp[j][0]) * sc1[j][0] + sh[j][0], v1 = (h[r][j][1] * rr * gp[j][1]) * sc1[j][1] + sh[j][1];
;                 u32x4 t; t.x = pk2(v0[0], v0[1]); t.y = pk2(v0[2], v0[3]); t.z = pk2(v1[0], v1[1]); t.w = pk2(v1[2], v1[3]);
;                 *(u32x4*)(U + (size_t)(row0 + r) * DM + 8 * lane + 512 * j) = t; }
	v_pk_fma_f32 v[204:205], v[6:7], v[122:123], v[204:205]
	v_pk_fma_f32 v[206:207], v[8:9], v[124:125], v[206:207]
	v_pk_fma_f32 v[208:209], v[10:11], v[126:127], v[208:209]
	v_pk_fma_f32 v[210:211], v[12:13], v[128:129], v[210:211]
	v_pk_fma_f32 v[212:213], v[14:15], v[130:131], v[212:213]
	v_cvt_f16_f32_e32 v132, v198
	v_cvt_f16_f32_e32 v133, v200
	v_cvt_f16_f32_e32 v134, v202
	v_cvt_f16_f32_e32 v135, v204
	v_cvt_f16_f32_e32 v136, v206
	v_cvt_f16_f32_e32 v137, v208
	v_cvt_f16_f32_e32 v138, v210
	v_cvt_f16_f32_e32 v139, v212
	v_cvt_f16_f32_sdwa v132, v199 dst_sel:WORD_1 dst_unused:UNUSED_PRESERVE src0_sel:DWORD
	v_cvt_f16_f32_sdwa v133, v201 dst_sel:WORD_1 dst_unused:UNUSED_PRESERVE src0_sel:DWORD
	v_cvt_f16_f32_sdwa v134, v203 dst_sel:WORD_1 dst_unused:UNUSED_PRESERVE src0_sel:DWORD
	v_cvt_f16_f32_sdwa v135, v205 dst_sel:WORD_1 dst_unused:UNUSED_PRESERVE src0_sel:DWORD
	v_cvt_f16_f32_sdwa v136, v207 dst_sel:WORD_1 dst_unused:UNUSED_PRESERVE src0_sel:DWORD
	v_cvt_f16_f32_sdwa v137, v209 dst_sel:WORD_1 dst_unused:UNUSED_PRESERVE src0_sel:DWORD
	v_cvt_f16_f32_sdwa v138, v211 dst_sel:WORD_1 dst_unused:UNUSED_PRESERVE src0_sel:DWORD
	v_cvt_f16_f32_sdwa v139, v213 dst_sel:WORD_1 dst_unused:UNUSED_PRESERVE src0_sel:DWORD
	s_nop 0
	global_store_dwordx4 v185, v[132:135], s[42:43] offset:-4096 sc1
	global_store_dwordx4 v185, v[136:139], s[42:43] offset:-3072 sc1
	v_pk_mul_f32 v[140:141], v[198:199], v[198:199]
	v_pk_fma_f32 v[140:141], v[200:201], v[200:201], v[140:141]
	v_pk_fma_f32 v[140:141], v[202:203], v[202:203], v[140:141]
	v_pk_fma_f32 v[140:141], v[204:205], v[204:205], v[140:141]
	v_pk_fma_f32 v[140:141], v[206:207], v[206:207], v[140:141]
	v_pk_fma_f32 v[140:141], v[208:209], v[208:209], v[140:141]
	v_pk_fma_f32 v[140:141], v[210:211], v[210:211], v[140:141]
	v_pk_fma_f32 v[140:141], v[212:213], v[212:213], v[140:141]
	v_add_f32_e32 v140, v140, v141
	s_nop 1
	v_add_f32_dpp v140, v140, v140 quad_perm:[1,0,3,2] row_mask:0xf bank_mask:0xf
	s_nop 1
	v_add_f32_dpp v140, v140, v140 quad_perm:[2,3,0,1] row_mask:0xf bank_mask:0xf
	s_nop 1
	v_add_f32_dpp v140, v140, v140 row_ror:4 row_mask:0xf bank_mask:0xf
	s_nop 1
	v_add_f32_dpp v140, v140, v140 row_ror:8 row_mask:0xf bank_mask:0xf
	s_nop 1
	v_add_f32_dpp v140, v140, v140 row_bcast:15 row_mask:0xa bank_mask:0xf
	s_nop 1
	v_add_f32_dpp v140, v140, v140 row_bcast:31 row_mask:0xc bank_mask:0xf
	s_nop 1
	v_fmamk_f32 v140, v140, 0x3a800000, v224
	v_rsq_f32_e32 v140, v140
	s_nop 0
	v_readlane_b32 s6, v140, 63
	s_nop 1
	v_pk_mul_f32 v[198:199], v[198:199], s[6:7] op_sel_hi:[1,0]
	v_pk_mul_f32 v[200:201], v[200:201], s[6:7] op_sel_hi:[1,0]
	v_pk_mul_f32 v[202:203], v[202:203], s[6:7] op_sel_hi:[1,0]
	v_pk_mul_f32 v[204:205], v[204:205], s[6:7] op_sel_hi:[1,0]
	v_pk_mul_f32 v[206:207], v[206:207], s[6:7] op_sel_hi:[1,0]
	v_pk_mul_f32 v[208:209], v[208:209], s[6:7] op_sel_hi:[1,0]
	v_pk_mul_f32 v[210:211], v[210:211], s[6:7] op_sel_hi:[1,0]
	v_pk_mul_f32 v[212:213], v[212:213], s[6:7] op_sel_hi:[1,0]
	v_pk_mul_f32 v[198:199], v[16:17], v[198:199]
	v_pk_mul_f32 v[200:201], v[18:19], v[200:201]
	v_pk_mul_f32 v[202:203], v[20:21], v[202:203]
	v_pk_mul_f32 v[204:205], v[22:23], v[204:205]
	v_pk_mul_f32 v[206:207], v[24:25], v[206:207]
	v_pk_mul_f32 v[208:209], v[26:27], v[208:209]
	v_pk_mul_f32 v[210:211], v[28:29], v[210:211]
	v_pk_mul_f32 v[212:213], v[30:31], v[212:213]
	v_pk_fma_f32 v[198:199], v[32:33], v[198:199], v[48:49]
	v_pk_fma_f32 v[200:201], v[34:35], v[200:201], v[50:51]
	v_pk_fma_f32 v[202:203], v[36:37], v[202:203], v[52:53]
	v_pk_fma_f32 v[204:205], v[38:39], v[204:205], v[54:55]
	v_pk_fma_f32 v[206:207], v[40:41], v[206:207], v[56:57]
	v_pk_fma_f32 v[208:209], v[42:43], v[208:209], v[58:59]
	v_pk_fma_f32 v[210:211], v[44:45], v[210:211], v[60:61]
	v_pk_fma_f32 v[212:213], v[46:47], v[212:213], v[62:63]
	v_cvt_pk_bf16_f32 v230, v198, v199
	v_cvt_pk_bf16_f32 v231, v200, v201
	v_cvt_pk_bf16_f32 v232, v202, v203
	v_cvt_pk_bf16_f32 v233, v204, v205
	v_cvt_pk_bf16_f32 v234, v206, v207
	v_cvt_pk_bf16_f32 v235, v208, v209
	v_cvt_pk_bf16_f32 v236, v210, v211
	v_cvt_pk_bf16_f32 v237, v212, v213
	global_store_dwordx4 v185, v[230:233], s[44:45] offset:-4096 sc1
	global_store_dwordx4 v185, v[234:237], s[44:45] offset:-3072 sc1
	s_waitcnt vmcnt(28)
; __device__ __forceinline__ float bf_lo(unsigned w) { return __uint_as_float(w << 16); }
; template <int R, bool SRCB> ...
;     ...
;             for (int j = 0; j < 2; ++j) { const u32x4 t = yr[r][j];
;                 y[j][0] = (f32x4){bf_lo(t.x), bf_hi(t.x), bf_lo(t.y), bf_hi(t.y)}; y[j][1] = (f32x4){bf_lo(t.z), bf_hi(t.z), bf_lo(t.w), bf_hi(t.w)};
;                 if (R == 1 && YP) {
; #pragma unroll
;                     for (int k = 0; k < 2; ++k) { const float* pp = YP + (size_t)(row0 - M_LAT) * DM + 8 * lane + 512 * j + 4 * k; f32x4 s = *(const f32x4*)pp;
; #pragma unroll
;                         for (int q = 1; q < pg8::NSL; ++q) s = s + *(const f32x4*)(pp + (size_t)q * 2048 * DM);
;                         y[j][k] = s; } }
; #pragma unroll
;                 for (int k = 0; k < 2; ++k) ss += (y[j][k][0] * y[j][k][0] + y[j][k][1] * y[j][k][1]) + (y[j][k][2] * y[j][k][2] + y[j][k][3] * y[j][k][3]); }
;             const float rr = __builtin_amdgcn_rsqf(wave_sum(ss) * (1.0f / DM) + 1e-6f) * w;
; #pragma unroll
;             for (int j = 0; j < 2; ++j)
; #pragma unroll
;                 for (int k = 0; k < 2; ++k) h[r][j][k] = h[r][j][k] + gg[j][k] * (y[j][k] * rr);
;         }
;     }
; #pragma unroll
;     for (int r = 0; r < R; ++r)
; #pragma unroll
;         for (int j = 0; j < 2; ++j) { const int c = 8 * lane + 512 * j;
;             if (final_out) { *(f32x4*)(final_out + (size_t)(row0 + r) * DM + c) = h[r][j][0]; *(f32x4*)(final_out + (size_t)(row0 + r) * DM + c + 4) = h[r][j][1]; }
;             else { u32x4 t; t.x = pkh2(h[r][j][0][0], h[r][j][0][1]); t.y = pkh2(h[r][j][0][2], h[r][j][0][3]); t.z = pkh2(h[r][j][1][0], h[r][j][1][1]); t.w = pkh2(h[r][j][1][2], h[r][j][1][3]);
;                 *(u32x4*)(hout + (size_t)(row0 + r) * DM + c) = t; } }
;     if (U) {
;         f32x4 gp[2][2], sc1[2][2], sh[2][2];
; #pragma unroll
;         for (int j = 0; j < 2; ++j)
; #pragma unroll
;             for (int k = 0; k < 2; ++k) { const int c = 8 * lane + 512 * j + 4 * k; gp[j][k] = *(const f32x4*)(gpre + c); sc1[j][k] = *(const f32x4*)(scale + (size_t)mrow * 9216 + c) + 1.0f; sh[j][k] = *(const f32x4*)(shift + (size_t)mrow * 9216 + c); }
; #pragma unroll
;         for (int r = 0; r < R; ++r) {
;             float ss = 0.f;
; #pragma unroll
;             for (int j = 0; j < 2; ++j)
; #pragma unroll
	v_lshlrev_b32_e32 v116, 16, v156
	v_and_b32_e32 v117, 0xffff0000, v156
	v_lshlrev_b32_e32 v118, 16, v157
	v_and_b32_e32 v119, 0xffff0000, v157
	v_lshlrev_b32_e32 v120, 16, v158
	v_and_b32_e32 v121, 0xffff0000, v158
	v_lshlrev_b32_e32 v122, 16, v159
	v_and_b32_e32 v123, 0xffff0000, v159
	v_lshlrev_b32_e32 v124, 16, v160
	v_and_b32_e32 v125, 0xffff0000, v160
	v_lshlrev_b32_e32 v126, 16, v161
	v_and_b32_e32 v127, 0xffff0000, v161
	v_lshlrev_b32_e32 v128, 16, v162
	v_and_b32_e32 v129, 0xffff0000, v162
	v_lshlrev_b32_e32 v130, 16, v163
	v_and_b32_e32 v131, 0xffff0000, v163
	v_cvt_f32_f16_e32 v198, v72
	v_cvt_f32_f16_sdwa v199, v72 dst_sel:DWORD dst_unused:UNUSED_PAD src0_sel:WORD_1
	v_cvt_f32_f16_e32 v200, v73
	v_cvt_f32_f16_sdwa v201, v73 dst_sel:DWORD dst_unused:UNUSED_PAD src0_sel:WORD_1
	v_cvt_f32_f16_e32 v202, v74
	v_cvt_f32_f16_sdwa v203, v74 dst_sel:DWORD dst_unused:UNUSED_PAD src0_sel:WORD_1
	v_cvt_f32_f16_e32 v204, v75
	v_cvt_f32_f16_sdwa v205, v75 dst_sel:DWORD dst_unused:UNUSED_PAD src0_sel:WORD_1
	v_cvt_f32_f16_e32 v206, v76
	v_cvt_f32_f16_sdwa v207, v76 dst_sel:DWORD dst_unused:UNUSED_PAD src0_sel:WORD_1
	v_cvt_f32_f16_e32 v208, v77
	v_cvt_f32_f16_sdwa v209, v77 dst_sel:DWORD dst_unused:UNUSED_PAD src0_sel:WORD_1
	v_cvt_f32_f16_e32 v210, v78
	v_cvt_f32_f16_sdwa v211, v78 dst_sel:DWORD dst_unused:UNUSED_PAD src0_sel:WORD_1
	v_cvt_f32_f16_e32 v212, v79
	v_cvt_f32_f16_sdwa v213, v79 dst_sel:DWORD dst_unused:UNUSED_PAD src0_sel:WORD_1
	global_load_dwordx4 v[72:75], v186, s[42:43] offset:-2048
	global_load_dwordx4 v[76:79], v186, s[42:43] offset:-1024
	global_load_dwordx4 v[156:159], v186, s[44:45] offset:-2048
	global_load_dwordx4 v[160:163], v186, s[44:45] offset:-1024
	v_pk_mul_f32 v[140:141], v[116:117], v[116:117]
	v_pk_fma_f32 v[140:141], v[118:119], v[118:119], v[140:141]
	v_pk_fma_f32 v[140:141], v[120:121], v[120:121], v[140:141]
	v_pk_fma_f32 v[140:141], v[122:123], v[122:123], v[140:141]
	v_pk_fma_f32 v[140:141], v[124:125], v[124:125], v[140:141]
	v_pk_fma_f32 v[140:141], v[126:127], v[126:127], v[140:141]
	v_pk_fma_f32 v[140:141], v[128:129], v[128:129], v[140:141]
	v_pk_fma_f32 v[140:141], v[130:131], v[130:131], v[140:141]
	v_add_f32_e32 v140, v140, v141
	s_nop 1
	v_add_f32_dpp v140, v140, v140 quad_perm:[1,0,3,2] row_mask:0xf bank_mask:0xf
	s_nop 1
	v_add_f32_dpp v140, v140, v140 quad_perm:[2,3,0,1] row_mask:0xf bank_mask:0xf
	s_nop 1
	v_add_f32_dpp v140, v140, v140 row_ror:4 row_mask:0xf bank_mask:0xf
	s_nop 1
	v_add_f32_dpp v140, v140, v140 row_ror:8 row_mask:0xf bank_mask:0xf
	s_nop 1
	v_add_f32_dpp v140, v140, v140 row_bcast:15 row_mask:0xa bank_mask:0xf
	s_nop 1
	v_add_f32_dpp v140, v140, v140 row_bcast:31 row_mask:0xc bank_mask:0xf
	s_nop 1
	v_fmamk_f32 v140, v140, 0x3a800000, v224
	v_rsq_f32_e32 v140, v140
	s_nop 0
	v_mul_f32_e32 v140, v144, v140
	s_nop 0
	v_readlane_b32 s4, v140, 63
	s_nop 1
	v_pk_mul_f32 v[116:117], v[116:117], s[4:5] op_sel_hi:[1,0]
	v_pk_mul_f32 v[118:119], v[118:119], s[4:5] op_sel_hi:[1,0]
	v_pk_mul_f32 v[120:121], v[120:121], s[4:5] op_sel_hi:[1,0]
	v_pk_mul_f32 v[122:123], v[122:123], s[4:5] op_sel_hi:[1,0]
	v_pk_mul_f32 v[124:125], v[124:125], s[4:5] op_sel_hi:[1,0]
	v_pk_mul_f32 v[126:127], v[126:127], s[4:5] op_sel_hi:[1,0]
	v_pk_mul_f32 v[128:129], v[128:129], s[4:5] op_sel_hi:[1,0]
	v_pk_mul_f32 v[130:131], v[130:131], s[4:5] op_sel_hi:[1,0]
	v_pk_fma_f32 v[198:199], v[0:1], v[116:117], v[198:199]
	v_pk_fma_f32 v[200:201], v[2:3], v[118:119], v[200:201]
	v_pk_fma_f32 v[202:203], v[4:5], v[120:121], v[202:203]
	v_pk_fma_f32 v[204:205], v[6:7], v[122:123], v[204:205]
	v_pk_fma_f32 v[206:207], v[8:9], v[124:125], v[206:207]
	v_pk_fma_f32 v[208:209], v[10:11], v[126:127], v[208:209]
	v_pk_fma_f32 v[210:211], v[12:13], v[128:129], v[210:211]
	v_pk_fma_f32 v[212:213], v[14:15], v[130:131], v[212:213]
	v_cvt_f16_f32_e32 v132, v198
	v_cvt_f16_f32_e32 v133, v200
	v_cvt_f16_f32_e32 v134, v202
	v_cvt_f16_f32_e32 v135, v204
	v_cvt_f16_f32_e32 v136, v206
	v_cvt_f16_f32_e32 v137, v208
	v_cvt_f16_f32_e32 v138, v210
	v_cvt_f16_f32_e32 v139, v212
	v_cvt_f16_f32_sdwa v132, v199 dst_sel:WORD_1 dst_unused:UNUSED_PRESERVE src0_sel:DWORD
	v_cvt_f16_f32_sdwa v133, v201 dst_sel:WORD_1 dst_unused:UNUSED_PRESERVE src0_sel:DWORD
	v_cvt_f16_f32_sdwa v134, v203 dst_sel:WORD_1 dst_unused:UNUSED_PRESERVE src0_sel:DWORD
	v_cvt_f16_f32_sdwa v135, v205 dst_sel:WORD_1 dst_unused:UNUSED_PRESERVE src0_sel:DWORD
	v_cvt_f16_f32_sdwa v136, v207 dst_sel:WORD_1 dst_unused:UNUSED_PRESERVE src0_sel:DWORD
	v_cvt_f16_f32_sdwa v137, v209 dst_sel:WORD_1 dst_unused:UNUSED_PRESERVE src0_sel:DWORD
	v_cvt_f16_f32_sdwa v138, v211 dst_sel:WORD_1 dst_unused:UNUSED_PRESERVE src0_sel:DWORD
	v_cvt_f16_f32_sdwa v139, v213 dst_sel:WORD_1 dst_unused:UNUSED_PRESERVE src0_sel:DWORD
	s_nop 0
	global_store_dwordx4 v185, v[132:135], s[42:43] offset:-2048 sc1
	global_store_dwordx4 v185, v[136:139], s[42:43] offset:-1024 sc1
	v_pk_mul_f32 v[140:141], v[198:199], v[198:199]
	v_pk_fma_f32 v[140:141], v[200:201], v[200:201], v[140:141]
	v_pk_fma_f32 v[140:141], v[202:203], v[202:203], v[140:141]
	v_pk_fma_f32 v[140:141], v[204:205], v[204:205], v[140:141]
	v_pk_fma_f32 v[140:141], v[206:207], v[206:207], v[140:141]
	v_pk_fma_f32 v[140:141], v[208:209], v[208:209], v[140:141]
	v_pk_fma_f32 v[140:141], v[210:211], v[210:211], v[140:141]
	v_pk_fma_f32 v[140:141], v[212:213], v[212:213], v[140:141]
	v_add_f32_e32 v140, v140, v141
	s_nop 1
	v_add_f32_dpp v140, v140, v140 quad_perm:[1,0,3,2] row_mask:0xf bank_mask:0xf
	s_nop 1
	v_add_f32_dpp v140, v140, v140 quad_perm:[2,3,0,1] row_mask:0xf bank_mask:0xf
	s_nop 1
	v_add_f32_dpp v140, v140, v140 row_ror:4 row_mask:0xf bank_mask:0xf
; __device__ __forceinline__ float bf_lo(unsigned w) { return __uint_as_float(w << 16); }
; template <int R, bool SRCB> ...
;     ...
;             for (int j = 0; j < 2; ++j) { const u32x4 t = yr[r][j];
;                 y[j][0] = (f32x4){bf_lo(t.x), bf_hi(t.x), bf_lo(t.y), bf_hi(t.y)}; y[j][1] = (f32x4){bf_lo(t.z), bf_hi(t.z), bf_lo(t.w), bf_hi(t.w)};
;                 if (R == 1 && YP) {
; #pragma unroll
;                     for (int k = 0; k < 2; ++k) { const float* pp = YP + (size_t)(row0 - M_LAT) * DM + 8 * lane + 512 * j + 4 * k; f32x4 s = *(const f32x4*)pp;
; #pragma unroll
;                         for (int q = 1; q < pg8::NSL; ++q) s = s + *(const f32x4*)(pp + (size_t)q * 2048 * DM);
;                         y[j][k] = s; } }
; #pragma unroll
;                 for (int k = 0; k < 2; ++k) ss += (y[j][k][0] * y[j][k][0] + y[j][k][1] * y[j][k][1]) + (y[j][k][2] * y[j][k][2] + y[j][k][3] * y[j][k][3]); }
;             const float rr = __builtin_amdgcn_rsqf(wave_sum(ss) * (1.0f / DM) + 1e-6f) * w;
; #pragma unroll
;             for (int j = 0; j < 2; ++j)
; #pragma unroll
;                 for (int k = 0; k < 2; ++k) h[r][j][k] = h[r][j][k] + gg[j][k] * (y[j][k] * rr);
;         }
;     }
; #pragma unroll
;     for (int r = 0; r < R; ++r)
; #pragma unroll
;         for (int j = 0; j < 2; ++j) { const int c = 8 * lane + 512 * j;
;             if (final_out) { *(f32x4*)(final_out + (size_t)(row0 + r) * DM + c) = h[r][j][0]; *(f32x4*)(final_out + (size_t)(row0 + r) * DM + c + 4) = h[r][j][1]; }
;             else { u32x4 t; t.x = pkh2(h[r][j][0][0], h[r][j][0][1]); t.y = pkh2(h[r][j][0][2], h[r][j][0][3]); t.z = pkh2(h[r][j][1][0], h[r][j][1][1]); t.w = pkh2(h[r][j][1][2], h[r][j][1][3]);
;                 *(u32x4*)(hout + (size_t)(row0 + r) * DM + c) = t; } }
;     if (U) {
;         f32x4 gp[2][2], sc1[2][2], sh[2][2];
; #pragma unroll
;         for (int j = 0; j < 2; ++j)
; #pragma unroll
;             for (int k = 0; k < 2; ++k) { const int c = 8 * lane + 512 * j + 4 * k; gp[j][k] = *(const f32x4*)(gpre + c); sc1[j][k] = *(const f32x4*)(scale + (size_t)mrow * 9216 + c) + 1.0f; sh[j][k] = *(const f32x4*)(shift + (size_t)mrow * 9216 + c); }
; #pragma unroll
;         for (int r = 0; r < R; ++r) {
;             float ss = 0.f;
; #pragma unroll
;             for (int j = 0; j < 2; ++j)
; #pragma unroll
	s_nop 1
	v_add_f32_dpp v140, v140, v140 row_ror:8 row_mask:0xf bank_mask:0xf
	s_nop 1
	v_add_f32_dpp v140, v140, v140 row_bcast:15 row_mask:0xa bank_mask:0xf
	s_nop 1
	v_add_f32_dpp v140, v140, v140 row_bcast:31 row_mask:0xc bank_mask:0xf
	s_nop 1
	v_fmamk_f32 v140, v140, 0x3a800000, v224
	v_rsq_f32_e32 v140, v140
	s_nop 0
	v_readlane_b32 s6, v140, 63
	s_nop 1
	v_pk_mul_f32 v[198:199], v[198:199], s[6:7] op_sel_hi:[1,0]
	v_pk_mul_f32 v[200:201], v[200:201], s[6:7] op_sel_hi:[1,0]
	v_pk_mul_f32 v[202:203], v[202:203], s[6:7] op_sel_hi:[1,0]
	v_pk_mul_f32 v[204:205], v[204:205], s[6:7] op_sel_hi:[1,0]
	v_pk_mul_f32 v[206:207], v[206:207], s[6:7] op_sel_hi:[1,0]
	v_pk_mul_f32 v[208:209], v[208:209], s[6:7] op_sel_hi:[1,0]
	v_pk_mul_f32 v[210:211], v[210:211], s[6:7] op_sel_hi:[1,0]
	v_pk_mul_f32 v[212:213], v[212:213], s[6:7] op_sel_hi:[1,0]
	v_pk_mul_f32 v[198:199], v[16:17], v[198:199]
	v_pk_mul_f32 v[200:201], v[18:19], v[200:201]
	v_pk_mul_f32 v[202:203], v[20:21], v[202:203]
	v_pk_mul_f32 v[204:205], v[22:23], v[204:205]
	v_pk_mul_f32 v[206:207], v[24:25], v[206:207]
	v_pk_mul_f32 v[208:209], v[26:27], v[208:209]
	v_pk_mul_f32 v[210:211], v[28:29], v[210:211]
	v_pk_mul_f32 v[212:213], v[30:31], v[212:213]
	v_pk_fma_f32 v[198:199], v[32:33], v[198:199], v[48:49]
	v_pk_fma_f32 v[200:201], v[34:35], v[200:201], v[50:51]
	v_pk_fma_f32 v[202:203], v[36:37], v[202:203], v[52:53]
	v_pk_fma_f32 v[204:205], v[38:39], v[204:205], v[54:55]
	v_pk_fma_f32 v[206:207], v[40:41], v[206:207], v[56:57]
	v_pk_fma_f32 v[208:209], v[42:43], v[208:209], v[58:59]
	v_pk_fma_f32 v[210:211], v[44:45], v[210:211], v[60:61]
	v_pk_fma_f32 v[212:213], v[46:47], v[212:213], v[62:63]
	v_cvt_pk_bf16_f32 v230, v198, v199
	v_cvt_pk_bf16_f32 v231, v200, v201
	v_cvt_pk_bf16_f32 v232, v202, v203
	v_cvt_pk_bf16_f32 v233, v204, v205
	v_cvt_pk_bf16_f32 v234, v206, v207
	v_cvt_pk_bf16_f32 v235, v208, v209
	v_cvt_pk_bf16_f32 v236, v210, v211
	v_cvt_pk_bf16_f32 v237, v212, v213
	global_store_dwordx4 v185, v[230:233], s[44:45] offset:-2048 sc1
	global_store_dwordx4 v185, v[234:237], s[44:45] offset:-1024 sc1
	s_waitcnt vmcnt(28)
	v_lshlrev_b32_e32 v116, 16, v164
	v_and_b32_e32 v117, 0xffff0000, v164
	v_lshlrev_b32_e32 v118, 16, v165
	v_and_b32_e32 v119, 0xffff0000, v165
	v_lshlrev_b32_e32 v120, 16, v166
	v_and_b32_e32 v121, 0xffff0000, v166
	v_lshlrev_b32_e32 v122, 16, v167
	v_and_b32_e32 v123, 0xffff0000, v167
	v_lshlrev_b32_e32 v124, 16, v168
	v_and_b32_e32 v125, 0xffff0000, v168
	v_lshlrev_b32_e32 v126, 16, v169
	v_and_b32_e32 v127, 0xffff0000, v169
	v_lshlrev_b32_e32 v128, 16, v170
	v_and_b32_e32 v129, 0xffff0000, v170
	v_lshlrev_b32_e32 v130, 16, v171
	v_and_b32_e32 v131, 0xffff0000, v171
	v_cvt_f32_f16_e32 v198, v80
	v_cvt_f32_f16_sdwa v199, v80 dst_sel:DWORD dst_unused:UNUSED_PAD src0_sel:WORD_1
	v_cvt_f32_f16_e32 v200, v81
	v_cvt_f32_f16_sdwa v201, v81 dst_sel:DWORD dst_unused:UNUSED_PAD src0_sel:WORD_1
	v_cvt_f32_f16_e32 v202, v82
	v_cvt_f32_f16_sdwa v203, v82 dst_sel:DWORD dst_unused:UNUSED_PAD src0_sel:WORD_1
	v_cvt_f32_f16_e32 v204, v83
	v_cvt_f32_f16_sdwa v205, v83 dst_sel:DWORD dst_unused:UNUSED_PAD src0_sel:WORD_1
	v_cvt_f32_f16_e32 v206, v84
	v_cvt_f32_f16_sdwa v207, v84 dst_sel:DWORD dst_unused:UNUSED_PAD src0_sel:WORD_1
	v_cvt_f32_f16_e32 v208, v85
	v_cvt_f32_f16_sdwa v209, v85 dst_sel:DWORD dst_unused:UNUSED_PAD src0_sel:WORD_1
	v_cvt_f32_f16_e32 v210, v86
	v_cvt_f32_f16_sdwa v211, v86 dst_sel:DWORD dst_unused:UNUSED_PAD src0_sel:WORD_1
	v_cvt_f32_f16_e32 v212, v87
	v_cvt_f32_f16_sdwa v213, v87 dst_sel:DWORD dst_unused:UNUSED_PAD src0_sel:WORD_1
	global_load_dwordx4 v[80:83], v186, s[42:43] offset:0
	global_load_dwordx4 v[84:87], v186, s[42:43] offset:1024
	global_load_dwordx4 v[164:167], v186, s[44:45] offset:0
	global_load_dwordx4 v[168:171], v186, s[44:45] offset:1024
	v_pk_mul_f32 v[140:141], v[116:117], v[116:117]
	v_pk_fma_f32 v[140:141], v[118:119], v[118:119], v[140:141]
	v_pk_fma_f32 v[140:141], v[120:121], v[120:121], v[140:141]
	v_pk_fma_f32 v[140:141], v[122:123], v[122:123], v[140:141]
	v_pk_fma_f32 v[140:141], v[124:125], v[124:125], v[140:141]
	v_pk_fma_f32 v[140:141], v[126:127], v[126:127], v[140:141]
	v_pk_fma_f32 v[140:141], v[128:129], v[128:129], v[140:141]
	v_pk_fma_f32 v[140:141], v[130:131], v[130:131], v[140:141]
	v_add_f32_e32 v140, v140, v141
	s_nop 1
	v_add_f32_dpp v140, v140, v140 quad_perm:[1,0,3,2] row_mask:0xf bank_mask:0xf
	s_nop 1
	v_add_f32_dpp v140, v140, v140 quad_perm:[2,3,0,1] row_mask:0xf bank_mask:0xf
	s_nop 1
	v_add_f32_dpp v140, v140, v140 row_ror:4 row_mask:0xf bank_mask:0xf
	s_nop 1
	v_add_f32_dpp v140, v140, v140 row_ror:8 row_mask:0xf bank_mask:0xf
	s_nop 1
	v_add_f32_dpp v140, v140, v140 row_bcast:15 row_mask:0xa bank_mask:0xf
	s_nop 1
	v_add_f32_dpp v140, v140, v140 row_bcast:31 row_mask:0xc bank_mask:0xf
	s_nop 1
	v_fmamk_f32 v140, v140, 0x3a800000, v224
	v_rsq_f32_e32 v140, v140
	s_nop 0
	v_mul_f32_e32 v140, v144, v140
	s_nop 0
	v_readlane_b32 s4, v140, 63
	s_nop 1
	v_pk_mul_f32 v[116:117], v[116:117], s[4:5] op_sel_hi:[1,0]
	v_pk_mul_f32 v[118:119], v[118:119], s[4:5] op_sel_hi:[1,0]
	v_pk_mul_f32 v[120:121], v[120:121], s[4:5] op_sel_hi:[1,0]
	v_pk_mul_f32 v[122:123], v[122:123], s[4:5] op_sel_hi:[1,0]
	v_pk_mul_f32 v[124:125], v[124:125], s[4:5] op_sel_hi:[1,0]
	v_pk_mul_f32 v[126:127], v[126:127], s[4:5] op_sel_hi:[1,0]
	v_pk_mul_f32 v[128:129], v[128:129], s[4:5] op_sel_hi:[1,0]
	v_pk_mul_f32 v[130:131], v[130:131], s[4:5] op_sel_hi:[1,0]
	v_pk_fma_f32 v[198:199], v[0:1], v[116:117], v[198:199]
	v_pk_fma_f32 v[200:201], v[2:3], v[118:119], v[200:201]
	v_pk_fma_f32 v[202:203], v[4:5], v[120:121], v[202:203]
; template <int R, bool SRCB> ...
;     ...
;         for (int r = 0; r < R; ++r) {
;             f32x4 y[2][2]; float ss = 0.f;
; #pragma unroll
;             for (int j = 0; j < 2; ++j) { const u32x4 t = yr[r][j];
;                 y[j][0] = (f32x4){bf_lo(t.x), bf_hi(t.x), bf_lo(t.y), bf_hi(t.y)}; y[j][1] = (f32x4){bf_lo(t.z), bf_hi(t.z), bf_lo(t.w), bf_hi(t.w)};
;                 if (R == 1 && YP) {
; #pragma unroll
;                     for (int k = 0; k < 2; ++k) { const float* pp = YP + (size_t)(row0 - M_LAT) * DM + 8 * lane + 512 * j + 4 * k; f32x4 s = *(const f32x4*)pp;
; #pragma unroll
;                         for (int q = 1; q < pg8::NSL; ++q) s = s + *(const f32x4*)(pp + (size_t)q * 2048 * DM);
;                         y[j][k] = s; } }
; #pragma unroll
;                 for (int k = 0; k < 2; ++k) ss += (y[j][k][0] * y[j][k][0] + y[j][k][1] * y[j][k][1]) + (y[j][k][2] * y[j][k][2] + y[j][k][3] * y[j][k][3]); }
;             const float rr = __builtin_amdgcn_rsqf(wave_sum(ss) * (1.0f / DM) + 1e-6f) * w;
; #pragma unroll
;             for (int j = 0; j < 2; ++j)
; #pragma unroll
;                 for (int k = 0; k < 2; ++k) h[r][j][k] = h[r][j][k] + gg[j][k] * (y[j][k] * rr);
;         }
;     }
; #pragma unroll
;     for (int r = 0; r < R; ++r)
; #pragma unroll
;         for (int j = 0; j < 2; ++j) { const int c = 8 * lane + 512 * j;
;             if (final_out) { *(f32x4*)(final_out + (size_t)(row0 + r) * DM + c) = h[r][j][0]; *(f32x4*)(final_out + (size_t)(row0 + r) * DM + c + 4) = h[r][j][1]; }
;             else { u32x4 t; t.x = pkh2(h[r][j][0][0], h[r][j][0][1]); t.y = pkh2(h[r][j][0][2], h[r][j][0][3]); t.z = pkh2(h[r][j][1][0], h[r][j][1][1]); t.w = pkh2(h[r][j][1][2], h[r][j][1][3]);
;                 *(u32x4*)(hout + (size_t)(row0 + r) * DM + c) = t; } }
;     if (U) {
;         f32x4 gp[2][2], sc1[2][2], sh[2][2];
; #pragma unroll
;         for (int j = 0; j < 2; ++j)
; #pragma unroll
;             for (int k = 0; k < 2; ++k) { const int c = 8 * lane + 512 * j + 4 * k; gp[j][k] = *(const f32x4*)(gpre + c); sc1[j][k] = *(const f32x4*)(scale + (size_t)mrow * 9216 + c) + 1.0f; sh[j][k] = *(const f32x4*)(shift + (size_t)mrow * 9216 + c); }
; #pragma unroll
;         for (int r = 0; r < R; ++r) {
;             float ss = 0.f;
; #pragma unroll
;             for (int j = 0; j < 2; ++j)
; #pragma unroll
	v_pk_fma_f32 v[204:205], v[6:7], v[122:123], v[204:205]
	v_pk_fma_f32 v[206:207], v[8:9], v[124:125], v[206:207]
	v_pk_fma_f32 v[208:209], v[10:11], v[126:127], v[208:209]
	v_pk_fma_f32 v[210:211], v[12:13], v[128:129], v[210:211]
	v_pk_fma_f32 v[212:213], v[14:15], v[130:131], v[212:213]
	v_cvt_f16_f32_e32 v132, v198
	v_cvt_f16_f32_e32 v133, v200
	v_cvt_f16_f32_e32 v134, v202
	v_cvt_f16_f32_e32 v135, v204
	v_cvt_f16_f32_e32 v136, v206
	v_cvt_f16_f32_e32 v137, v208
	v_cvt_f16_f32_e32 v138, v210
	v_cvt_f16_f32_e32 v139, v212
	v_cvt_f16_f32_sdwa v132, v199 dst_sel:WORD_1 dst_unused:UNUSED_PRESERVE src0_sel:DWORD
	v_cvt_f16_f32_sdwa v133, v201 dst_sel:WORD_1 dst_unused:UNUSED_PRESERVE src0_sel:DWORD
	v_cvt_f16_f32_sdwa v134, v203 dst_sel:WORD_1 dst_unused:UNUSED_PRESERVE src0_sel:DWORD
	v_cvt_f16_f32_sdwa v135, v205 dst_sel:WORD_1 dst_unused:UNUSED_PRESERVE src0_sel:DWORD
	v_cvt_f16_f32_sdwa v136, v207 dst_sel:WORD_1 dst_unused:UNUSED_PRESERVE src0_sel:DWORD
	v_cvt_f16_f32_sdwa v137, v209 dst_sel:WORD_1 dst_unused:UNUSED_PRESERVE src0_sel:DWORD
	v_cvt_f16_f32_sdwa v138, v211 dst_sel:WORD_1 dst_unused:UNUSED_PRESERVE src0_sel:DWORD
	v_cvt_f16_f32_sdwa v139, v213 dst_sel:WORD_1 dst_unused:UNUSED_PRESERVE src0_sel:DWORD
	s_nop 0
	global_store_dwordx4 v185, v[132:135], s[42:43] offset:0 sc1
	global_store_dwordx4 v185, v[136:139], s[42:43] offset:1024 sc1
	v_pk_mul_f32 v[140:141], v[198:199], v[198:199]
	v_pk_fma_f32 v[140:141], v[200:201], v[200:201], v[140:141]
	v_pk_fma_f32 v[140:141], v[202:203], v[202:203], v[140:141]
	v_pk_fma_f32 v[140:141], v[204:205], v[204:205], v[140:141]
	v_pk_fma_f32 v[140:141], v[206:207], v[206:207], v[140:141]
	v_pk_fma_f32 v[140:141], v[208:209], v[208:209], v[140:141]
	v_pk_fma_f32 v[140:141], v[210:211], v[210:211], v[140:141]
	v_pk_fma_f32 v[140:141], v[212:213], v[212:213], v[140:141]
	v_add_f32_e32 v140, v140, v141
	s_nop 1
	v_add_f32_dpp v140, v140, v140 quad_perm:[1,0,3,2] row_mask:0xf bank_mask:0xf
	s_nop 1
	v_add_f32_dpp v140, v140, v140 quad_perm:[2,3,0,1] row_mask:0xf bank_mask:0xf
	s_nop 1
	v_add_f32_dpp v140, v140, v140 row_ror:4 row_mask:0xf bank_mask:0xf
	s_nop 1
	v_add_f32_dpp v140, v140, v140 row_ror:8 row_mask:0xf bank_mask:0xf
	s_nop 1
	v_add_f32_dpp v140, v140, v140 row_bcast:15 row_mask:0xa bank_mask:0xf
	s_nop 1
	v_add_f32_dpp v140, v140, v140 row_bcast:31 row_mask:0xc bank_mask:0xf
	s_nop 1
	v_fmamk_f32 v140, v140, 0x3a800000, v224
	v_rsq_f32_e32 v140, v140
	s_nop 0
	v_readlane_b32 s6, v140, 63
	s_nop 1
	v_pk_mul_f32 v[198:199], v[198:199], s[6:7] op_sel_hi:[1,0]
	v_pk_mul_f32 v[200:201], v[200:201], s[6:7] op_sel_hi:[1,0]
	v_pk_mul_f32 v[202:203], v[202:203], s[6:7] op_sel_hi:[1,0]
	v_pk_mul_f32 v[204:205], v[204:205], s[6:7] op_sel_hi:[1,0]
	v_pk_mul_f32 v[206:207], v[206:207], s[6:7] op_sel_hi:[1,0]
	v_pk_mul_f32 v[208:209], v[208:209], s[6:7] op_sel_hi:[1,0]
	v_pk_mul_f32 v[210:211], v[210:211], s[6:7] op_sel_hi:[1,0]
	v_pk_mul_f32 v[212:213], v[212:213], s[6:7] op_sel_hi:[1,0]
	v_pk_mul_f32 v[198:199], v[16:17], v[198:199]
	v_pk_mul_f32 v[200:201], v[18:19], v[200:201]
	v_pk_mul_f32 v[202:203], v[20:21], v[202:203]
	v_pk_mul_f32 v[204:205], v[22:23], v[204:205]
	v_pk_mul_f32 v[206:207], v[24:25], v[206:207]
	v_pk_mul_f32 v[208:209], v[26:27], v[208:209]
	v_pk_mul_f32 v[210:211], v[28:29], v[210:211]
	v_pk_mul_f32 v[212:213], v[30:31], v[212:213]
	v_pk_fma_f32 v[198:199], v[32:33], v[198:199], v[48:49]
	v_pk_fma_f32 v[200:201], v[34:35], v[200:201], v[50:51]
	v_pk_fma_f32 v[202:203], v[36:37], v[202:203], v[52:53]
	v_pk_fma_f32 v[204:205], v[38:39], v[204:205], v[54:55]
	v_pk_fma_f32 v[206:207], v[40:41], v[206:207], v[56:57]
	v_pk_fma_f32 v[208:209], v[42:43], v[208:209], v[58:59]
	v_pk_fma_f32 v[210:211], v[44:45], v[210:211], v[60:61]
	v_pk_fma_f32 v[212:213], v[46:47], v[212:213], v[62:63]
	v_cvt_pk_bf16_f32 v230, v198, v199
	v_cvt_pk_bf16_f32 v231, v200, v201
	v_cvt_pk_bf16_f32 v232, v202, v203
	v_cvt_pk_bf16_f32 v233, v204, v205
	v_cvt_pk_bf16_f32 v234, v206, v207
	v_cvt_pk_bf16_f32 v235, v208, v209
	v_cvt_pk_bf16_f32 v236, v210, v211
	v_cvt_pk_bf16_f32 v237, v212, v213
	global_store_dwordx4 v185, v[230:233], s[44:45] offset:0 sc1
	global_store_dwordx4 v185, v[234:237], s[44:45] offset:1024 sc1
	s_waitcnt vmcnt(28)
; template <int R, bool SRCB> ...
;     ...
;         for (int r = 0; r < R; ++r) {
;             f32x4 y[2][2]; float ss = 0.f;
; #pragma unroll
;             for (int j = 0; j < 2; ++j) { const u32x4 t = yr[r][j];
;                 y[j][0] = (f32x4){bf_lo(t.x), bf_hi(t.x), bf_lo(t.y), bf_hi(t.y)}; y[j][1] = (f32x4){bf_lo(t.z), bf_hi(t.z), bf_lo(t.w), bf_hi(t.w)};
;                 if (R == 1 && YP) {
; #pragma unroll
;                     for (int k = 0; k < 2; ++k) { const float* pp = YP + (size_t)(row0 - M_LAT) * DM + 8 * lane + 512 * j + 4 * k; f32x4 s = *(const f32x4*)pp;
; #pragma unroll
;                         for (int q = 1; q < pg8::NSL; ++q) s = s + *(const f32x4*)(pp + (size_t)q * 2048 * DM);
;                         y[j][k] = s; } }
; #pragma unroll
;                 for (int k = 0; k < 2; ++k) ss += (y[j][k][0] * y[j][k][0] + y[j][k][1] * y[j][k][1]) + (y[j][k][2] * y[j][k][2] + y[j][k][3] * y[j][k][3]); }
;             const float rr = __builtin_amdgcn_rsqf(wave_sum(ss) * (1.0f / DM) + 1e-6f) * w;
; #pragma unroll
;             for (int j = 0; j < 2; ++j)
; #pragma unroll
;                 for (int k = 0; k < 2; ++k) h[r][j][k] = h[r][j][k] + gg[j][k] * (y[j][k] * rr);
;         }
;     }
; #pragma unroll
;     for (int r = 0; r < R; ++r)
; #pragma unroll
;         for (int j = 0; j < 2; ++j) { const int c = 8 * lane + 512 * j;
;             if (final_out) { *(f32x4*)(final_out + (size_t)(row0 + r) * DM + c) = h[r][j][0]; *(f32x4*)(final_out + (size_t)(row0 + r) * DM + c + 4) = h[r][j][1]; }
;             else { u32x4 t; t.x = pkh2(h[r][j][0][0], h[r][j][0][1]); t.y = pkh2(h[r][j][0][2], h[r][j][0][3]); t.z = pkh2(h[r][j][1][0], h[r][j][1][1]); t.w = pkh2(h[r][j][1][2], h[r][j][1][3]);
;                 *(u32x4*)(hout + (size_t)(row0 + r) * DM + c) = t; } }
;     if (U) {
;         f32x4 gp[2][2], sc1[2][2], sh[2][2];
; #pragma unroll
;         for (int j = 0; j < 2; ++j)
; #pragma unroll
;             for (int k = 0; k < 2; ++k) { const int c = 8 * lane + 512 * j + 4 * k; gp[j][k] = *(const f32x4*)(gpre + c); sc1[j][k] = *(const f32x4*)(scale + (size_t)mrow * 9216 + c) + 1.0f; sh[j][k] = *(const f32x4*)(shift + (size_t)mrow * 9216 + c); }
; #pragma unroll
;         for (int r = 0; r < R; ++r) {
;             float ss = 0.f;
; #pragma unroll
;             for (int j = 0; j < 2; ++j)
; #pragma unroll
	v_lshlrev_b32_e32 v116, 16, v172
	v_and_b32_e32 v117, 0xffff0000, v172
	v_lshlrev_b32_e32 v118, 16, v173
	v_and_b32_e32 v119, 0xffff0000, v173
	v_lshlrev_b32_e32 v120, 16, v174
	v_and_b32_e32 v121, 0xffff0000, v174
	v_lshlrev_b32_e32 v122, 16, v175
	v_and_b32_e32 v123, 0xffff0000, v175
	v_lshlrev_b32_e32 v124, 16, v176
	v_and_b32_e32 v125, 0xffff0000, v176
	v_lshlrev_b32_e32 v126, 16, v177
	v_and_b32_e32 v127, 0xffff0000, v177
	v_lshlrev_b32_e32 v128, 16, v178
	v_and_b32_e32 v129, 0xffff0000, v178
	v_lshlrev_b32_e32 v130, 16, v179
	v_and_b32_e32 v131, 0xffff0000, v179
	v_cvt_f32_f16_e32 v198, v88
	v_cvt_f32_f16_sdwa v199, v88 dst_sel:DWORD dst_unused:UNUSED_PAD src0_sel:WORD_1
	v_cvt_f32_f16_e32 v200, v89
	v_cvt_f32_f16_sdwa v201, v89 dst_sel:DWORD dst_unused:UNUSED_PAD src0_sel:WORD_1
	v_cvt_f32_f16_e32 v202, v90
	v_cvt_f32_f16_sdwa v203, v90 dst_sel:DWORD dst_unused:UNUSED_PAD src0_sel:WORD_1
	v_cvt_f32_f16_e32 v204, v91
	v_cvt_f32_f16_sdwa v205, v91 dst_sel:DWORD dst_unused:UNUSED_PAD src0_sel:WORD_1
	v_cvt_f32_f16_e32 v206, v92
	v_cvt_f32_f16_sdwa v207, v92 dst_sel:DWORD dst_unused:UNUSED_PAD src0_sel:WORD_1
	v_cvt_f32_f16_e32 v208, v93
	v_cvt_f32_f16_sdwa v209, v93 dst_sel:DWORD dst_unused:UNUSED_PAD src0_sel:WORD_1
	v_cvt_f32_f16_e32 v210, v94
	v_cvt_f32_f16_sdwa v211, v94 dst_sel:DWORD dst_unused:UNUSED_PAD src0_sel:WORD_1
	v_cvt_f32_f16_e32 v212, v95
	v_cvt_f32_f16_sdwa v213, v95 dst_sel:DWORD dst_unused:UNUSED_PAD src0_sel:WORD_1
	global_load_dwordx4 v[88:91], v186, s[42:43] offset:2048
	global_load_dwordx4 v[92:95], v186, s[42:43] offset:3072
	global_load_dwordx4 v[172:175], v186, s[44:45] offset:2048
	global_load_dwordx4 v[176:179], v186, s[44:45] offset:3072
	v_pk_mul_f32 v[140:141], v[116:117], v[116:117]
	v_pk_fma_f32 v[140:141], v[118:119], v[118:119], v[140:141]
	v_pk_fma_f32 v[140:141], v[120:121], v[120:121], v[140:141]
	v_pk_fma_f32 v[140:141], v[122:123], v[122:123], v[140:141]
	v_pk_fma_f32 v[140:141], v[124:125], v[124:125], v[140:141]
	v_pk_fma_f32 v[140:141], v[126:127], v[126:127], v[140:141]
	v_pk_fma_f32 v[140:141], v[128:129], v[128:129], v[140:141]
	v_pk_fma_f32 v[140:141], v[130:131], v[130:131], v[140:141]
	v_add_f32_e32 v140, v140, v141
	s_nop 1
	v_add_f32_dpp v140, v140, v140 quad_perm:[1,0,3,2] row_mask:0xf bank_mask:0xf
	s_nop 1
	v_add_f32_dpp v140, v140, v140 quad_perm:[2,3,0,1] row_mask:0xf bank_mask:0xf
	s_nop 1
	v_add_f32_dpp v140, v140, v140 row_ror:4 row_mask:0xf bank_mask:0xf
	s_nop 1
	v_add_f32_dpp v140, v140, v140 row_ror:8 row_mask:0xf bank_mask:0xf
	s_nop 1
	v_add_f32_dpp v140, v140, v140 row_bcast:15 row_mask:0xa bank_mask:0xf
	s_nop 1
	v_add_f32_dpp v140, v140, v140 row_bcast:31 row_mask:0xc bank_mask:0xf
	s_nop 1
	v_fmamk_f32 v140, v140, 0x3a800000, v224
	v_rsq_f32_e32 v140, v140
	s_nop 0
	v_mul_f32_e32 v140, v144, v140
	s_nop 0
	v_readlane_b32 s4, v140, 63
	s_nop 1
	v_pk_mul_f32 v[116:117], v[116:117], s[4:5] op_sel_hi:[1,0]
	v_pk_mul_f32 v[118:119], v[118:119], s[4:5] op_sel_hi:[1,0]
	v_pk_mul_f32 v[120:121], v[120:121], s[4:5] op_sel_hi:[1,0]
	v_pk_mul_f32 v[122:123], v[122:123], s[4:5] op_sel_hi:[1,0]
	v_pk_mul_f32 v[124:125], v[124:125], s[4:5] op_sel_hi:[1,0]
	v_pk_mul_f32 v[126:127], v[126:127], s[4:5] op_sel_hi:[1,0]
	v_pk_mul_f32 v[128:129], v[128:129], s[4:5] op_sel_hi:[1,0]
	v_pk_mul_f32 v[130:131], v[130:131], s[4:5] op_sel_hi:[1,0]
	v_pk_fma_f32 v[198:199], v[0:1], v[116:117], v[198:199]
	v_pk_fma_f32 v[200:201], v[2:3], v[118:119], v[200:201]
	v_pk_fma_f32 v[202:203], v[4:5], v[120:121], v[202:203]
	v_pk_fma_f32 v[204:205], v[6:7], v[122:123], v[204:205]
	v_pk_fma_f32 v[206:207], v[8:9], v[124:125], v[206:207]
	v_pk_fma_f32 v[208:209], v[10:11], v[126:127], v[208:209]
	v_pk_fma_f32 v[210:211], v[12:13], v[128:129], v[210:211]
	v_pk_fma_f32 v[212:213], v[14:15], v[130:131], v[212:213]
	v_cvt_f16_f32_e32 v132, v198
	v_cvt_f16_f32_e32 v133, v200
	v_cvt_f16_f32_e32 v134, v202
	v_cvt_f16_f32_e32 v135, v204
	v_cvt_f16_f32_e32 v136, v206
	v_cvt_f16_f32_e32 v137, v208
	v_cvt_f16_f32_e32 v138, v210
	v_cvt_f16_f32_e32 v139, v212
	v_cvt_f16_f32_sdwa v132, v199 dst_sel:WORD_1 dst_unused:UNUSED_PRESERVE src0_sel:DWORD
	v_cvt_f16_f32_sdwa v133, v201 dst_sel:WORD_1 dst_unused:UNUSED_PRESERVE src0_sel:DWORD
	v_cvt_f16_f32_sdwa v134, v203 dst_sel:WORD_1 dst_unused:UNUSED_PRESERVE src0_sel:DWORD
	v_cvt_f16_f32_sdwa v135, v205 dst_sel:WORD_1 dst_unused:UNUSED_PRESERVE src0_sel:DWORD
	v_cvt_f16_f32_sdwa v136, v207 dst_sel:WORD_1 dst_unused:UNUSED_PRESERVE src0_sel:DWORD
	v_cvt_f16_f32_sdwa v137, v209 dst_sel:WORD_1 dst_unused:UNUSED_PRESERVE src0_sel:DWORD
	v_cvt_f16_f32_sdwa v138, v211 dst_sel:WORD_1 dst_unused:UNUSED_PRESERVE src0_sel:DWORD
	v_cvt_f16_f32_sdwa v139, v213 dst_sel:WORD_1 dst_unused:UNUSED_PRESERVE src0_sel:DWORD
	s_nop 0
	global_store_dwordx4 v185, v[132:135], s[42:43] offset:2048 sc1
	global_store_dwordx4 v185, v[136:139], s[42:43] offset:3072 sc1
	v_pk_mul_f32 v[140:141], v[198:199], v[198:199]
	v_pk_fma_f32 v[140:141], v[200:201], v[200:201], v[140:141]
	v_pk_fma_f32 v[140:141], v[202:203], v[202:203], v[140:141]
	v_pk_fma_f32 v[140:141], v[204:205], v[204:205], v[140:141]
	v_pk_fma_f32 v[140:141], v[206:207], v[206:207], v[140:141]
	v_pk_fma_f32 v[140:141], v[208:209], v[208:209], v[140:141]
	v_pk_fma_f32 v[140:141], v[210:211], v[210:211], v[140:141]
	v_pk_fma_f32 v[140:141], v[212:213], v[212:213], v[140:141]
	v_add_f32_e32 v140, v140, v141
	s_nop 1
	v_add_f32_dpp v140, v140, v140 quad_perm:[1,0,3,2] row_mask:0xf bank_mask:0xf
	s_nop 1
	v_add_f32_dpp v140, v140, v140 quad_perm:[2,3,0,1] row_mask:0xf bank_mask:0xf
	s_nop 1
	v_add_f32_dpp v140, v140, v140 row_ror:4 row_mask:0xf bank_mask:0xf
; template <int R, bool SRCB> ...
;     ...
;         for (int r = 0; r < R; ++r) {
;             f32x4 y[2][2]; float ss = 0.f;
; #pragma unroll
;             for (int j = 0; j < 2; ++j) { const u32x4 t = yr[r][j];
;                 y[j][0] = (f32x4){bf_lo(t.x), bf_hi(t.x), bf_lo(t.y), bf_hi(t.y)}; y[j][1] = (f32x4){bf_lo(t.z), bf_hi(t.z), bf_lo(t.w), bf_hi(t.w)};
;                 if (R == 1 && YP) {
; #pragma unroll
;                     for (int k = 0; k < 2; ++k) { const float* pp = YP + (size_t)(row0 - M_LAT) * DM + 8 * lane + 512 * j + 4 * k; f32x4 s = *(const f32x4*)pp;
; #pragma unroll
;                         for (int q = 1; q < pg8::NSL; ++q) s = s + *(const f32x4*)(pp + (size_t)q * 2048 * DM);
;                         y[j][k] = s; } }
; #pragma unroll
;                 for (int k = 0; k < 2; ++k) ss += (y[j][k][0] * y[j][k][0] + y[j][k][1] * y[j][k][1]) + (y[j][k][2] * y[j][k][2] + y[j][k][3] * y[j][k][3]); }
;             const float rr = __builtin_amdgcn_rsqf(wave_sum(ss) * (1.0f / DM) + 1e-6f) * w;
; #pragma unroll
;             for (int j = 0; j < 2; ++j)
; #pragma unroll
;                 for (int k = 0; k < 2; ++k) h[r][j][k] = h[r][j][k] + gg[j][k] * (y[j][k] * rr);
;         }
;     }
; #pragma unroll
;     for (int r = 0; r < R; ++r)
; #pragma unroll
;         for (int j = 0; j < 2; ++j) { const int c = 8 * lane + 512 * j;
;             if (final_out) { *(f32x4*)(final_out + (size_t)(row0 + r) * DM + c) = h[r][j][0]; *(f32x4*)(final_out + (size_t)(row0 + r) * DM + c + 4) = h[r][j][1]; }
;             else { u32x4 t; t.x = pkh2(h[r][j][0][0], h[r][j][0][1]); t.y = pkh2(h[r][j][0][2], h[r][j][0][3]); t.z = pkh2(h[r][j][1][0], h[r][j][1][1]); t.w = pkh2(h[r][j][1][2], h[r][j][1][3]);
;                 *(u32x4*)(hout + (size_t)(row0 + r) * DM + c) = t; } }
;     if (U) {
;         f32x4 gp[2][2], sc1[2][2], sh[2][2];
; #pragma unroll
;         for (int j = 0; j < 2; ++j)
; #pragma unroll
;             for (int k = 0; k < 2; ++k) { const int c = 8 * lane + 512 * j + 4 * k; gp[j][k] = *(const f32x4*)(gpre + c); sc1[j][k] = *(const f32x4*)(scale + (size_t)mrow * 9216 + c) + 1.0f; sh[j][k] = *(const f32x4*)(shift + (size_t)mrow * 9216 + c); }
; #pragma unroll
;         for (int r = 0; r < R; ++r) {
;             float ss = 0.f;
; #pragma unroll
;             for (int j = 0; j < 2; ++j)
; #pragma unroll
	s_nop 1
	v_add_f32_dpp v140, v140, v140 row_ror:8 row_mask:0xf bank_mask:0xf
	s_nop 1
	v_add_f32_dpp v140, v140, v140 row_bcast:15 row_mask:0xa bank_mask:0xf
	s_nop 1
	v_add_f32_dpp v140, v140, v140 row_bcast:31 row_mask:0xc bank_mask:0xf
	s_nop 1
	v_fmamk_f32 v140, v140, 0x3a800000, v224
	v_rsq_f32_e32 v140, v140
	s_nop 0
	v_readlane_b32 s6, v140, 63
	s_nop 1
	v_pk_mul_f32 v[198:199], v[198:199], s[6:7] op_sel_hi:[1,0]
	v_pk_mul_f32 v[200:201], v[200:201], s[6:7] op_sel_hi:[1,0]
	v_pk_mul_f32 v[202:203], v[202:203], s[6:7] op_sel_hi:[1,0]
	v_pk_mul_f32 v[204:205], v[204:205], s[6:7] op_sel_hi:[1,0]
	v_pk_mul_f32 v[206:207], v[206:207], s[6:7] op_sel_hi:[1,0]
	v_pk_mul_f32 v[208:209], v[208:209], s[6:7] op_sel_hi:[1,0]
	v_pk_mul_f32 v[210:211], v[210:211], s[6:7] op_sel_hi:[1,0]
	v_pk_mul_f32 v[212:213], v[212:213], s[6:7] op_sel_hi:[1,0]
	v_pk_mul_f32 v[198:199], v[16:17], v[198:199]
	v_pk_mul_f32 v[200:201], v[18:19], v[200:201]
	v_pk_mul_f32 v[202:203], v[20:21], v[202:203]
	v_pk_mul_f32 v[204:205], v[22:23], v[204:205]
	v_pk_mul_f32 v[206:207], v[24:25], v[206:207]
	v_pk_mul_f32 v[208:209], v[26:27], v[208:209]
	v_pk_mul_f32 v[210:211], v[28:29], v[210:211]
	v_pk_mul_f32 v[212:213], v[30:31], v[212:213]
	v_pk_fma_f32 v[198:199], v[32:33], v[198:199], v[48:49]
	v_pk_fma_f32 v[200:201], v[34:35], v[200:201], v[50:51]
	v_pk_fma_f32 v[202:203], v[36:37], v[202:203], v[52:53]
	v_pk_fma_f32 v[204:205], v[38:39], v[204:205], v[54:55]
	v_pk_fma_f32 v[206:207], v[40:41], v[206:207], v[56:57]
	v_pk_fma_f32 v[208:209], v[42:43], v[208:209], v[58:59]
	v_pk_fma_f32 v[210:211], v[44:45], v[210:211], v[60:61]
	v_pk_fma_f32 v[212:213], v[46:47], v[212:213], v[62:63]
	v_cvt_pk_bf16_f32 v230, v198, v199
	v_cvt_pk_bf16_f32 v231, v200, v201
	v_cvt_pk_bf16_f32 v232, v202, v203
	v_cvt_pk_bf16_f32 v233, v204, v205
	v_cvt_pk_bf16_f32 v234, v206, v207
	v_cvt_pk_bf16_f32 v235, v208, v209
	v_cvt_pk_bf16_f32 v236, v210, v211
	v_cvt_pk_bf16_f32 v237, v212, v213
	global_store_dwordx4 v185, v[230:233], s[44:45] offset:2048 sc1
	global_store_dwordx4 v185, v[234:237], s[44:45] offset:3072 sc1
	s_waitcnt vmcnt(28)
	v_lshlrev_b32_e32 v116, 16, v148
	v_and_b32_e32 v117, 0xffff0000, v148
	v_lshlrev_b32_e32 v118, 16, v149
	v_and_b32_e32 v119, 0xffff0000, v149
	v_lshlrev_b32_e32 v120, 16, v150
	v_and_b32_e32 v121, 0xffff0000, v150
	v_lshlrev_b32_e32 v122, 16, v151
	v_and_b32_e32 v123, 0xffff0000, v151
	v_lshlrev_b32_e32 v124, 16, v152
	v_and_b32_e32 v125, 0xffff0000, v152
	v_lshlrev_b32_e32 v126, 16, v153
	v_and_b32_e32 v127, 0xffff0000, v153
	v_lshlrev_b32_e32 v128, 16, v154
	v_and_b32_e32 v129, 0xffff0000, v154
	v_lshlrev_b32_e32 v130, 16, v155
	v_and_b32_e32 v131, 0xffff0000, v155
	v_cvt_f32_f16_e32 v198, v64
	v_cvt_f32_f16_sdwa v199, v64 dst_sel:DWORD dst_unused:UNUSED_PAD src0_sel:WORD_1
	v_cvt_f32_f16_e32 v200, v65
	v_cvt_f32_f16_sdwa v201, v65 dst_sel:DWORD dst_unused:UNUSED_PAD src0_sel:WORD_1
	v_cvt_f32_f16_e32 v202, v66
	v_cvt_f32_f16_sdwa v203, v66 dst_sel:DWORD dst_unused:UNUSED_PAD src0_sel:WORD_1
	v_cvt_f32_f16_e32 v204, v67
	v_cvt_f32_f16_sdwa v205, v67 dst_sel:DWORD dst_unused:UNUSED_PAD src0_sel:WORD_1
	v_cvt_f32_f16_e32 v206, v68
	v_cvt_f32_f16_sdwa v207, v68 dst_sel:DWORD dst_unused:UNUSED_PAD src0_sel:WORD_1
	v_cvt_f32_f16_e32 v208, v69
	v_cvt_f32_f16_sdwa v209, v69 dst_sel:DWORD dst_unused:UNUSED_PAD src0_sel:WORD_1
	v_cvt_f32_f16_e32 v210, v70
	v_cvt_f32_f16_sdwa v211, v70 dst_sel:DWORD dst_unused:UNUSED_PAD src0_sel:WORD_1
	v_cvt_f32_f16_e32 v212, v71
	v_cvt_f32_f16_sdwa v213, v71 dst_sel:DWORD dst_unused:UNUSED_PAD src0_sel:WORD_1
	global_load_dwordx4 v[64:67], v187, s[42:43] offset:-4096
	global_load_dwordx4 v[68:71], v187, s[42:43] offset:-3072
	global_load_dwordx4 v[148:151], v187, s[44:45] offset:-4096
	global_load_dwordx4 v[152:155], v187, s[44:45] offset:-3072
	v_pk_mul_f32 v[140:141], v[116:117], v[116:117]
	v_pk_fma_f32 v[140:141], v[118:119], v[118:119], v[140:141]
	v_pk_fma_f32 v[140:141], v[120:121], v[120:121], v[140:141]
	v_pk_fma_f32 v[140:141], v[122:123], v[122:123], v[140:141]
	v_pk_fma_f32 v[140:141], v[124:125], v[124:125], v[140:141]
	v_pk_fma_f32 v[140:141], v[126:127], v[126:127], v[140:141]
	v_pk_fma_f32 v[140:141], v[128:129], v[128:129], v[140:141]
	v_pk_fma_f32 v[140:141], v[130:131], v[130:131], v[140:141]
	v_add_f32_e32 v140, v140, v141
	s_nop 1
	v_add_f32_dpp v140, v140, v140 quad_perm:[1,0,3,2] row_mask:0xf bank_mask:0xf
	s_nop 1
	v_add_f32_dpp v140, v140, v140 quad_perm:[2,3,0,1] row_mask:0xf bank_mask:0xf
	s_nop 1
	v_add_f32_dpp v140, v140, v140 row_ror:4 row_mask:0xf bank_mask:0xf
	s_nop 1
	v_add_f32_dpp v140, v140, v140 row_ror:8 row_mask:0xf bank_mask:0xf
	s_nop 1
	v_add_f32_dpp v140, v140, v140 row_bcast:15 row_mask:0xa bank_mask:0xf
	s_nop 1
	v_add_f32_dpp v140, v140, v140 row_bcast:31 row_mask:0xc bank_mask:0xf
	s_nop 1
	v_fmamk_f32 v140, v140, 0x3a800000, v224
	v_rsq_f32_e32 v140, v140
	s_nop 0
	v_mul_f32_e32 v140, v144, v140
	s_nop 0
	v_readlane_b32 s4, v140, 63
	s_nop 1
	v_pk_mul_f32 v[116:117], v[116:117], s[4:5] op_sel_hi:[1,0]
	v_pk_mul_f32 v[118:119], v[118:119], s[4:5] op_sel_hi:[1,0]
	v_pk_mul_f32 v[120:121], v[120:121], s[4:5] op_sel_hi:[1,0]
	v_pk_mul_f32 v[122:123], v[122:123], s[4:5] op_sel_hi:[1,0]
	v_pk_mul_f32 v[124:125], v[124:125], s[4:5] op_sel_hi:[1,0]
	v_pk_mul_f32 v[126:127], v[126:127], s[4:5] op_sel_hi:[1,0]
	v_pk_mul_f32 v[128:129], v[128:129], s[4:5] op_sel_hi:[1,0]
	v_pk_mul_f32 v[130:131], v[130:131], s[4:5] op_sel_hi:[1,0]
	v_pk_fma_f32 v[198:199], v[0:1], v[116:117], v[198:199]
	v_pk_fma_f32 v[200:201], v[2:3], v[118:119], v[200:201]
	v_pk_fma_f32 v[202:203], v[4:5], v[120:121], v[202:203]
; template <int R, bool SRCB> ...
;     ...
;         for (int r = 0; r < R; ++r) {
;             f32x4 y[2][2]; float ss = 0.f;
; #pragma unroll
;             for (int j = 0; j < 2; ++j) { const u32x4 t = yr[r][j];
;                 y[j][0] = (f32x4){bf_lo(t.x), bf_hi(t.x), bf_lo(t.y), bf_hi(t.y)}; y[j][1] = (f32x4){bf_lo(t.z), bf_hi(t.z), bf_lo(t.w), bf_hi(t.w)};
;                 if (R == 1 && YP) {
; #pragma unroll
;                     for (int k = 0; k < 2; ++k) { const float* pp = YP + (size_t)(row0 - M_LAT) * DM + 8 * lane + 512 * j + 4 * k; f32x4 s = *(const f32x4*)pp;
; #pragma unroll
;                         for (int q = 1; q < pg8::NSL; ++q) s = s + *(const f32x4*)(pp + (size_t)q * 2048 * DM);
;                         y[j][k] = s; } }
; #pragma unroll
;                 for (int k = 0; k < 2; ++k) ss += (y[j][k][0] * y[j][k][0] + y[j][k][1] * y[j][k][1]) + (y[j][k][2] * y[j][k][2] + y[j][k][3] * y[j][k][3]); }
;             const float rr = __builtin_amdgcn_rsqf(wave_sum(ss) * (1.0f / DM) + 1e-6f) * w;
; #pragma unroll
;             for (int j = 0; j < 2; ++j)
; #pragma unroll
;                 for (int k = 0; k < 2; ++k) h[r][j][k] = h[r][j][k] + gg[j][k] * (y[j][k] * rr);
;         }
;     }
; #pragma unroll
;     for (int r = 0; r < R; ++r)
; #pragma unroll
;         for (int j = 0; j < 2; ++j) { const int c = 8 * lane + 512 * j;
;             if (final_out) { *(f32x4*)(final_out + (size_t)(row0 + r) * DM + c) = h[r][j][0]; *(f32x4*)(final_out + (size_t)(row0 + r) * DM + c + 4) = h[r][j][1]; }
;             else { u32x4 t; t.x = pkh2(h[r][j][0][0], h[r][j][0][1]); t.y = pkh2(h[r][j][0][2], h[r][j][0][3]); t.z = pkh2(h[r][j][1][0], h[r][j][1][1]); t.w = pkh2(h[r][j][1][2], h[r][j][1][3]);
;                 *(u32x4*)(hout + (size_t)(row0 + r) * DM + c) = t; } }
;     if (U) {
;         f32x4 gp[2][2], sc1[2][2], sh[2][2];
; #pragma unroll
;         for (int j = 0; j < 2; ++j)
; #pragma unroll
;             for (int k = 0; k < 2; ++k) { const int c = 8 * lane + 512 * j + 4 * k; gp[j][k] = *(const f32x4*)(gpre + c); sc1[j][k] = *(const f32x4*)(scale + (size_t)mrow * 9216 + c) + 1.0f; sh[j][k] = *(const f32x4*)(shift + (size_t)mrow * 9216 + c); }
; #pragma unroll
;         for (int r = 0; r < R; ++r) {
;             float ss = 0.f;
; #pragma unroll
;             for (int j = 0; j < 2; ++j)
; #pragma unroll
	v_pk_fma_f32 v[204:205], v[6:7], v[122:123], v[204:205]
	v_pk_fma_f32 v[206:207], v[8:9], v[124:125], v[206:207]
	v_pk_fma_f32 v[208:209], v[10:11], v[126:127], v[208:209]
	v_pk_fma_f32 v[210:211], v[12:13], v[128:129], v[210:211]
	v_pk_fma_f32 v[212:213], v[14:15], v[130:131], v[212:213]
	v_cvt_f16_f32_e32 v132, v198
	v_cvt_f16_f32_e32 v133, v200
	v_cvt_f16_f32_e32 v134, v202
	v_cvt_f16_f32_e32 v135, v204
	v_cvt_f16_f32_e32 v136, v206
	v_cvt_f16_f32_e32 v137, v208
	v_cvt_f16_f32_e32 v138, v210
	v_cvt_f16_f32_e32 v139, v212
	v_cvt_f16_f32_sdwa v132, v199 dst_sel:WORD_1 dst_unused:UNUSED_PRESERVE src0_sel:DWORD
	v_cvt_f16_f32_sdwa v133, v201 dst_sel:WORD_1 dst_unused:UNUSED_PRESERVE src0_sel:DWORD
	v_cvt_f16_f32_sdwa v134, v203 dst_sel:WORD_1 dst_unused:UNUSED_PRESERVE src0_sel:DWORD
	v_cvt_f16_f32_sdwa v135, v205 dst_sel:WORD_1 dst_unused:UNUSED_PRESERVE src0_sel:DWORD
	v_cvt_f16_f32_sdwa v136, v207 dst_sel:WORD_1 dst_unused:UNUSED_PRESERVE src0_sel:DWORD
	v_cvt_f16_f32_sdwa v137, v209 dst_sel:WORD_1 dst_unused:UNUSED_PRESERVE src0_sel:DWORD
	v_cvt_f16_f32_sdwa v138, v211 dst_sel:WORD_1 dst_unused:UNUSED_PRESERVE src0_sel:DWORD
	v_cvt_f16_f32_sdwa v139, v213 dst_sel:WORD_1 dst_unused:UNUSED_PRESERVE src0_sel:DWORD
	s_nop 0
	global_store_dwordx4 v186, v[132:135], s[42:43] offset:-4096 sc1
	global_store_dwordx4 v186, v[136:139], s[42:43] offset:-3072 sc1
	v_pk_mul_f32 v[140:141], v[198:199], v[198:199]
	v_pk_fma_f32 v[140:141], v[200:201], v[200:201], v[140:141]
	v_pk_fma_f32 v[140:141], v[202:203], v[202:203], v[140:141]
	v_pk_fma_f32 v[140:141], v[204:205], v[204:205], v[140:141]
	v_pk_fma_f32 v[140:141], v[206:207], v[206:207], v[140:141]
	v_pk_fma_f32 v[140:141], v[208:209], v[208:209], v[140:141]
	v_pk_fma_f32 v[140:141], v[210:211], v[210:211], v[140:141]
	v_pk_fma_f32 v[140:141], v[212:213], v[212:213], v[140:141]
	v_add_f32_e32 v140, v140, v141
	s_nop 1
	v_add_f32_dpp v140, v140, v140 quad_perm:[1,0,3,2] row_mask:0xf bank_mask:0xf
	s_nop 1
	v_add_f32_dpp v140, v140, v140 quad_perm:[2,3,0,1] row_mask:0xf bank_mask:0xf
	s_nop 1
	v_add_f32_dpp v140, v140, v140 row_ror:4 row_mask:0xf bank_mask:0xf
	s_nop 1
	v_add_f32_dpp v140, v140, v140 row_ror:8 row_mask:0xf bank_mask:0xf
	s_nop 1
	v_add_f32_dpp v140, v140, v140 row_bcast:15 row_mask:0xa bank_mask:0xf
	s_nop 1
	v_add_f32_dpp v140, v140, v140 row_bcast:31 row_mask:0xc bank_mask:0xf
	s_nop 1
	v_fmamk_f32 v140, v140, 0x3a800000, v224
	v_rsq_f32_e32 v140, v140
	s_nop 0
	v_readlane_b32 s6, v140, 63
	s_nop 1
	v_pk_mul_f32 v[198:199], v[198:199], s[6:7] op_sel_hi:[1,0]
	v_pk_mul_f32 v[200:201], v[200:201], s[6:7] op_sel_hi:[1,0]
	v_pk_mul_f32 v[202:203], v[202:203], s[6:7] op_sel_hi:[1,0]
	v_pk_mul_f32 v[204:205], v[204:205], s[6:7] op_sel_hi:[1,0]
	v_pk_mul_f32 v[206:207], v[206:207], s[6:7] op_sel_hi:[1,0]
	v_pk_mul_f32 v[208:209], v[208:209], s[6:7] op_sel_hi:[1,0]
	v_pk_mul_f32 v[210:211], v[210:211], s[6:7] op_sel_hi:[1,0]
	v_pk_mul_f32 v[212:213], v[212:213], s[6:7] op_sel_hi:[1,0]
	v_pk_mul_f32 v[198:199], v[16:17], v[198:199]
	v_pk_mul_f32 v[200:201], v[18:19], v[200:201]
	v_pk_mul_f32 v[202:203], v[20:21], v[202:203]
	v_pk_mul_f32 v[204:205], v[22:23], v[204:205]
	v_pk_mul_f32 v[206:207], v[24:25], v[206:207]
	v_pk_mul_f32 v[208:209], v[26:27], v[208:209]
	v_pk_mul_f32 v[210:211], v[28:29], v[210:211]
	v_pk_mul_f32 v[212:213], v[30:31], v[212:213]
	v_pk_fma_f32 v[198:199], v[32:33], v[198:199], v[48:49]
	v_pk_fma_f32 v[200:201], v[34:35], v[200:201], v[50:51]
	v_pk_fma_f32 v[202:203], v[36:37], v[202:203], v[52:53]
	v_pk_fma_f32 v[204:205], v[38:39], v[204:205], v[54:55]
	v_pk_fma_f32 v[206:207], v[40:41], v[206:207], v[56:57]
	v_pk_fma_f32 v[208:209], v[42:43], v[208:209], v[58:59]
	v_pk_fma_f32 v[210:211], v[44:45], v[210:211], v[60:61]
	v_pk_fma_f32 v[212:213], v[46:47], v[212:213], v[62:63]
	v_cvt_pk_bf16_f32 v230, v198, v199
	v_cvt_pk_bf16_f32 v231, v200, v201
	v_cvt_pk_bf16_f32 v232, v202, v203
	v_cvt_pk_bf16_f32 v233, v204, v205
	v_cvt_pk_bf16_f32 v234, v206, v207
	v_cvt_pk_bf16_f32 v235, v208, v209
	v_cvt_pk_bf16_f32 v236, v210, v211
	v_cvt_pk_bf16_f32 v237, v212, v213
	global_store_dwordx4 v186, v[230:233], s[44:45] offset:-4096 sc1
	global_store_dwordx4 v186, v[234:237], s[44:45] offset:-3072 sc1
	s_waitcnt vmcnt(28)
; template <int R, bool SRCB> ...
;     ...
;         for (int r = 0; r < R; ++r) {
;             f32x4 y[2][2]; float ss = 0.f;
; #pragma unroll
;             for (int j = 0; j < 2; ++j) { const u32x4 t = yr[r][j];
;                 y[j][0] = (f32x4){bf_lo(t.x), bf_hi(t.x), bf_lo(t.y), bf_hi(t.y)}; y[j][1] = (f32x4){bf_lo(t.z), bf_hi(t.z), bf_lo(t.w), bf_hi(t.w)};
;                 if (R == 1 && YP) {
; #pragma unroll
;                     for (int k = 0; k < 2; ++k) { const float* pp = YP + (size_t)(row0 - M_LAT) * DM + 8 * lane + 512 * j + 4 * k; f32x4 s = *(const f32x4*)pp;
; #pragma unroll
;                         for (int q = 1; q < pg8::NSL; ++q) s = s + *(const f32x4*)(pp + (size_t)q * 2048 * DM);
;                         y[j][k] = s; } }
; #pragma unroll
;                 for (int k = 0; k < 2; ++k) ss += (y[j][k][0] * y[j][k][0] + y[j][k][1] * y[j][k][1]) + (y[j][k][2] * y[j][k][2] + y[j][k][3] * y[j][k][3]); }
;             const float rr = __builtin_amdgcn_rsqf(wave_sum(ss) * (1.0f / DM) + 1e-6f) * w;
; #pragma unroll
;             for (int j = 0; j < 2; ++j)
; #pragma unroll
;                 for (int k = 0; k < 2; ++k) h[r][j][k] = h[r][j][k] + gg[j][k] * (y[j][k] * rr);
;         }
;     }
; #pragma unroll
;     for (int r = 0; r < R; ++r)
; #pragma unroll
;         for (int j = 0; j < 2; ++j) { const int c = 8 * lane + 512 * j;
;             if (final_out) { *(f32x4*)(final_out + (size_t)(row0 + r) * DM + c) = h[r][j][0]; *(f32x4*)(final_out + (size_t)(row0 + r) * DM + c + 4) = h[r][j][1]; }
;             else { u32x4 t; t.x = pkh2(h[r][j][0][0], h[r][j][0][1]); t.y = pkh2(h[r][j][0][2], h[r][j][0][3]); t.z = pkh2(h[r][j][1][0], h[r][j][1][1]); t.w = pkh2(h[r][j][1][2], h[r][j][1][3]);
;                 *(u32x4*)(hout + (size_t)(row0 + r) * DM + c) = t; } }
;     if (U) {
;         f32x4 gp[2][2], sc1[2][2], sh[2][2];
; #pragma unroll
;         for (int j = 0; j < 2; ++j)
; #pragma unroll
;             for (int k = 0; k < 2; ++k) { const int c = 8 * lane + 512 * j + 4 * k; gp[j][k] = *(const f32x4*)(gpre + c); sc1[j][k] = *(const f32x4*)(scale + (size_t)mrow * 9216 + c) + 1.0f; sh[j][k] = *(const f32x4*)(shift + (size_t)mrow * 9216 + c); }
; #pragma unroll
;         for (int r = 0; r < R; ++r) {
;             float ss = 0.f;
; #pragma unroll
;             for (int j = 0; j < 2; ++j)
; #pragma unroll
	v_lshlrev_b32_e32 v116, 16, v156
	v_and_b32_e32 v117, 0xffff0000, v156
	v_lshlrev_b32_e32 v118, 16, v157
	v_and_b32_e32 v119, 0xffff0000, v157
	v_lshlrev_b32_e32 v120, 16, v158
	v_and_b32_e32 v121, 0xffff0000, v158
	v_lshlrev_b32_e32 v122, 16, v159
	v_and_b32_e32 v123, 0xffff0000, v159
	v_lshlrev_b32_e32 v124, 16, v160
	v_and_b32_e32 v125, 0xffff0000, v160
	v_lshlrev_b32_e32 v126, 16, v161
	v_and_b32_e32 v127, 0xffff0000, v161
	v_lshlrev_b32_e32 v128, 16, v162
	v_and_b32_e32 v129, 0xffff0000, v162
	v_lshlrev_b32_e32 v130, 16, v163
	v_and_b32_e32 v131, 0xffff0000, v163
	v_cvt_f32_f16_e32 v198, v72
	v_cvt_f32_f16_sdwa v199, v72 dst_sel:DWORD dst_unused:UNUSED_PAD src0_sel:WORD_1
	v_cvt_f32_f16_e32 v200, v73
	v_cvt_f32_f16_sdwa v201, v73 dst_sel:DWORD dst_unused:UNUSED_PAD src0_sel:WORD_1
	v_cvt_f32_f16_e32 v202, v74
	v_cvt_f32_f16_sdwa v203, v74 dst_sel:DWORD dst_unused:UNUSED_PAD src0_sel:WORD_1
	v_cvt_f32_f16_e32 v204, v75
	v_cvt_f32_f16_sdwa v205, v75 dst_sel:DWORD dst_unused:UNUSED_PAD src0_sel:WORD_1
	v_cvt_f32_f16_e32 v206, v76
	v_cvt_f32_f16_sdwa v207, v76 dst_sel:DWORD dst_unused:UNUSED_PAD src0_sel:WORD_1
	v_cvt_f32_f16_e32 v208, v77
	v_cvt_f32_f16_sdwa v209, v77 dst_sel:DWORD dst_unused:UNUSED_PAD src0_sel:WORD_1
	v_cvt_f32_f16_e32 v210, v78
	v_cvt_f32_f16_sdwa v211, v78 dst_sel:DWORD dst_unused:UNUSED_PAD src0_sel:WORD_1
	v_cvt_f32_f16_e32 v212, v79
	v_cvt_f32_f16_sdwa v213, v79 dst_sel:DWORD dst_unused:UNUSED_PAD src0_sel:WORD_1
	global_load_dwordx4 v[72:75], v187, s[42:43] offset:-2048
	global_load_dwordx4 v[76:79], v187, s[42:43] offset:-1024
	global_load_dwordx4 v[156:159], v187, s[44:45] offset:-2048
	global_load_dwordx4 v[160:163], v187, s[44:45] offset:-1024
	v_pk_mul_f32 v[140:141], v[116:117], v[116:117]
	v_pk_fma_f32 v[140:141], v[118:119], v[118:119], v[140:141]
	v_pk_fma_f32 v[140:141], v[120:121], v[120:121], v[140:141]
	v_pk_fma_f32 v[140:141], v[122:123], v[122:123], v[140:141]
	v_pk_fma_f32 v[140:141], v[124:125], v[124:125], v[140:141]
	v_pk_fma_f32 v[140:141], v[126:127], v[126:127], v[140:141]
	v_pk_fma_f32 v[140:141], v[128:129], v[128:129], v[140:141]
	v_pk_fma_f32 v[140:141], v[130:131], v[130:131], v[140:141]
	v_add_f32_e32 v140, v140, v141
	s_nop 1
	v_add_f32_dpp v140, v140, v140 quad_perm:[1,0,3,2] row_mask:0xf bank_mask:0xf
	s_nop 1
	v_add_f32_dpp v140, v140, v140 quad_perm:[2,3,0,1] row_mask:0xf bank_mask:0xf
	s_nop 1
	v_add_f32_dpp v140, v140, v140 row_ror:4 row_mask:0xf bank_mask:0xf
	s_nop 1
	v_add_f32_dpp v140, v140, v140 row_ror:8 row_mask:0xf bank_mask:0xf
	s_nop 1
	v_add_f32_dpp v140, v140, v140 row_bcast:15 row_mask:0xa bank_mask:0xf
	s_nop 1
	v_add_f32_dpp v140, v140, v140 row_bcast:31 row_mask:0xc bank_mask:0xf
	s_nop 1
	v_fmamk_f32 v140, v140, 0x3a800000, v224
	v_rsq_f32_e32 v140, v140
	s_nop 0
	v_mul_f32_e32 v140, v144, v140
	s_nop 0
	v_readlane_b32 s4, v140, 63
	s_nop 1
	v_pk_mul_f32 v[116:117], v[116:117], s[4:5] op_sel_hi:[1,0]
	v_pk_mul_f32 v[118:119], v[118:119], s[4:5] op_sel_hi:[1,0]
	v_pk_mul_f32 v[120:121], v[120:121], s[4:5] op_sel_hi:[1,0]
	v_pk_mul_f32 v[122:123], v[122:123], s[4:5] op_sel_hi:[1,0]
	v_pk_mul_f32 v[124:125], v[124:125], s[4:5] op_sel_hi:[1,0]
	v_pk_mul_f32 v[126:127], v[126:127], s[4:5] op_sel_hi:[1,0]
	v_pk_mul_f32 v[128:129], v[128:129], s[4:5] op_sel_hi:[1,0]
	v_pk_mul_f32 v[130:131], v[130:131], s[4:5] op_sel_hi:[1,0]
	v_pk_fma_f32 v[198:199], v[0:1], v[116:117], v[198:199]
	v_pk_fma_f32 v[200:201], v[2:3], v[118:119], v[200:201]
	v_pk_fma_f32 v[202:203], v[4:5], v[120:121], v[202:203]
	v_pk_fma_f32 v[204:205], v[6:7], v[122:123], v[204:205]
	v_pk_fma_f32 v[206:207], v[8:9], v[124:125], v[206:207]
	v_pk_fma_f32 v[208:209], v[10:11], v[126:127], v[208:209]
	v_pk_fma_f32 v[210:211], v[12:13], v[128:129], v[210:211]
	v_pk_fma_f32 v[212:213], v[14:15], v[130:131], v[212:213]
	v_cvt_f16_f32_e32 v132, v198
	v_cvt_f16_f32_e32 v133, v200
	v_cvt_f16_f32_e32 v134, v202
	v_cvt_f16_f32_e32 v135, v204
	v_cvt_f16_f32_e32 v136, v206
	v_cvt_f16_f32_e32 v137, v208
	v_cvt_f16_f32_e32 v138, v210
	v_cvt_f16_f32_e32 v139, v212
	v_cvt_f16_f32_sdwa v132, v199 dst_sel:WORD_1 dst_unused:UNUSED_PRESERVE src0_sel:DWORD
	v_cvt_f16_f32_sdwa v133, v201 dst_sel:WORD_1 dst_unused:UNUSED_PRESERVE src0_sel:DWORD
	v_cvt_f16_f32_sdwa v134, v203 dst_sel:WORD_1 dst_unused:UNUSED_PRESERVE src0_sel:DWORD
	v_cvt_f16_f32_sdwa v135, v205 dst_sel:WORD_1 dst_unused:UNUSED_PRESERVE src0_sel:DWORD
	v_cvt_f16_f32_sdwa v136, v207 dst_sel:WORD_1 dst_unused:UNUSED_PRESERVE src0_sel:DWORD
	v_cvt_f16_f32_sdwa v137, v209 dst_sel:WORD_1 dst_unused:UNUSED_PRESERVE src0_sel:DWORD
	v_cvt_f16_f32_sdwa v138, v211 dst_sel:WORD_1 dst_unused:UNUSED_PRESERVE src0_sel:DWORD
	v_cvt_f16_f32_sdwa v139, v213 dst_sel:WORD_1 dst_unused:UNUSED_PRESERVE src0_sel:DWORD
	s_nop 0
	global_store_dwordx4 v186, v[132:135], s[42:43] offset:-2048 sc1
	global_store_dwordx4 v186, v[136:139], s[42:43] offset:-1024 sc1
	v_pk_mul_f32 v[140:141], v[198:199], v[198:199]
	v_pk_fma_f32 v[140:141], v[200:201], v[200:201], v[140:141]
	v_pk_fma_f32 v[140:141], v[202:203], v[202:203], v[140:141]
	v_pk_fma_f32 v[140:141], v[204:205], v[204:205], v[140:141]
	v_pk_fma_f32 v[140:141], v[206:207], v[206:207], v[140:141]
	v_pk_fma_f32 v[140:141], v[208:209], v[208:209], v[140:141]
	v_pk_fma_f32 v[140:141], v[210:211], v[210:211], v[140:141]
	v_pk_fma_f32 v[140:141], v[212:213], v[212:213], v[140:141]
	v_add_f32_e32 v140, v140, v141
	s_nop 1
	v_add_f32_dpp v140, v140, v140 quad_perm:[1,0,3,2] row_mask:0xf bank_mask:0xf
	s_nop 1
	v_add_f32_dpp v140, v140, v140 quad_perm:[2,3,0,1] row_mask:0xf bank_mask:0xf
	s_nop 1
	v_add_f32_dpp v140, v140, v140 row_ror:4 row_mask:0xf bank_mask:0xf
; template <int R, bool SRCB> ...
;     ...
;         for (int r = 0; r < R; ++r) {
;             f32x4 y[2][2]; float ss = 0.f;
; #pragma unroll
;             for (int j = 0; j < 2; ++j) { const u32x4 t = yr[r][j];
;                 y[j][0] = (f32x4){bf_lo(t.x), bf_hi(t.x), bf_lo(t.y), bf_hi(t.y)}; y[j][1] = (f32x4){bf_lo(t.z), bf_hi(t.z), bf_lo(t.w), bf_hi(t.w)};
;                 if (R == 1 && YP) {
; #pragma unroll
;                     for (int k = 0; k < 2; ++k) { const float* pp = YP + (size_t)(row0 - M_LAT) * DM + 8 * lane + 512 * j + 4 * k; f32x4 s = *(const f32x4*)pp;
; #pragma unroll
;                         for (int q = 1; q < pg8::NSL; ++q) s = s + *(const f32x4*)(pp + (size_t)q * 2048 * DM);
;                         y[j][k] = s; } }
; #pragma unroll
;                 for (int k = 0; k < 2; ++k) ss += (y[j][k][0] * y[j][k][0] + y[j][k][1] * y[j][k][1]) + (y[j][k][2] * y[j][k][2] + y[j][k][3] * y[j][k][3]); }
;             const float rr = __builtin_amdgcn_rsqf(wave_sum(ss) * (1.0f / DM) + 1e-6f) * w;
; #pragma unroll
;             for (int j = 0; j < 2; ++j)
; #pragma unroll
;                 for (int k = 0; k < 2; ++k) h[r][j][k] = h[r][j][k] + gg[j][k] * (y[j][k] * rr);
;         }
;     }
; #pragma unroll
;     for (int r = 0; r < R; ++r)
; #pragma unroll
;         for (int j = 0; j < 2; ++j) { const int c = 8 * lane + 512 * j;
;             if (final_out) { *(f32x4*)(final_out + (size_t)(row0 + r) * DM + c) = h[r][j][0]; *(f32x4*)(final_out + (size_t)(row0 + r) * DM + c + 4) = h[r][j][1]; }
;             else { u32x4 t; t.x = pkh2(h[r][j][0][0], h[r][j][0][1]); t.y = pkh2(h[r][j][0][2], h[r][j][0][3]); t.z = pkh2(h[r][j][1][0], h[r][j][1][1]); t.w = pkh2(h[r][j][1][2], h[r][j][1][3]);
;                 *(u32x4*)(hout + (size_t)(row0 + r) * DM + c) = t; } }
;     if (U) {
;         f32x4 gp[2][2], sc1[2][2], sh[2][2];
; #pragma unroll
;         for (int j = 0; j < 2; ++j)
; #pragma unroll
;             for (int k = 0; k < 2; ++k) { const int c = 8 * lane + 512 * j + 4 * k; gp[j][k] = *(const f32x4*)(gpre + c); sc1[j][k] = *(const f32x4*)(scale + (size_t)mrow * 9216 + c) + 1.0f; sh[j][k] = *(const f32x4*)(shift + (size_t)mrow * 9216 + c); }
; #pragma unroll
;         for (int r = 0; r < R; ++r) {
;             float ss = 0.f;
; #pragma unroll
;             for (int j = 0; j < 2; ++j)
; #pragma unroll
	s_nop 1
	v_add_f32_dpp v140, v140, v140 row_ror:8 row_mask:0xf bank_mask:0xf
	s_nop 1
	v_add_f32_dpp v140, v140, v140 row_bcast:15 row_mask:0xa bank_mask:0xf
	s_nop 1
	v_add_f32_dpp v140, v140, v140 row_bcast:31 row_mask:0xc bank_mask:0xf
	s_nop 1
	v_fmamk_f32 v140, v140, 0x3a800000, v224
	v_rsq_f32_e32 v140, v140
	s_nop 0
	v_readlane_b32 s6, v140, 63
	s_nop 1
	v_pk_mul_f32 v[198:199], v[198:199], s[6:7] op_sel_hi:[1,0]
	v_pk_mul_f32 v[200:201], v[200:201], s[6:7] op_sel_hi:[1,0]
	v_pk_mul_f32 v[202:203], v[202:203], s[6:7] op_sel_hi:[1,0]
	v_pk_mul_f32 v[204:205], v[204:205], s[6:7] op_sel_hi:[1,0]
	v_pk_mul_f32 v[206:207], v[206:207], s[6:7] op_sel_hi:[1,0]
	v_pk_mul_f32 v[208:209], v[208:209], s[6:7] op_sel_hi:[1,0]
	v_pk_mul_f32 v[210:211], v[210:211], s[6:7] op_sel_hi:[1,0]
	v_pk_mul_f32 v[212:213], v[212:213], s[6:7] op_sel_hi:[1,0]
	v_pk_mul_f32 v[198:199], v[16:17], v[198:199]
	v_pk_mul_f32 v[200:201], v[18:19], v[200:201]
	v_pk_mul_f32 v[202:203], v[20:21], v[202:203]
	v_pk_mul_f32 v[204:205], v[22:23], v[204:205]
	v_pk_mul_f32 v[206:207], v[24:25], v[206:207]
	v_pk_mul_f32 v[208:209], v[26:27], v[208:209]
	v_pk_mul_f32 v[210:211], v[28:29], v[210:211]
	v_pk_mul_f32 v[212:213], v[30:31], v[212:213]
	v_pk_fma_f32 v[198:199], v[32:33], v[198:199], v[48:49]
	v_pk_fma_f32 v[200:201], v[34:35], v[200:201], v[50:51]
	v_pk_fma_f32 v[202:203], v[36:37], v[202:203], v[52:53]
	v_pk_fma_f32 v[204:205], v[38:39], v[204:205], v[54:55]
	v_pk_fma_f32 v[206:207], v[40:41], v[206:207], v[56:57]
	v_pk_fma_f32 v[208:209], v[42:43], v[208:209], v[58:59]
	v_pk_fma_f32 v[210:211], v[44:45], v[210:211], v[60:61]
	v_pk_fma_f32 v[212:213], v[46:47], v[212:213], v[62:63]
	v_cvt_pk_bf16_f32 v230, v198, v199
	v_cvt_pk_bf16_f32 v231, v200, v201
	v_cvt_pk_bf16_f32 v232, v202, v203
	v_cvt_pk_bf16_f32 v233, v204, v205
	v_cvt_pk_bf16_f32 v234, v206, v207
	v_cvt_pk_bf16_f32 v235, v208, v209
	v_cvt_pk_bf16_f32 v236, v210, v211
	v_cvt_pk_bf16_f32 v237, v212, v213
	global_store_dwordx4 v186, v[230:233], s[44:45] offset:-2048 sc1
	global_store_dwordx4 v186, v[234:237], s[44:45] offset:-1024 sc1
	s_waitcnt vmcnt(28)
	v_lshlrev_b32_e32 v116, 16, v164
	v_and_b32_e32 v117, 0xffff0000, v164
	v_lshlrev_b32_e32 v118, 16, v165
	v_and_b32_e32 v119, 0xffff0000, v165
	v_lshlrev_b32_e32 v120, 16, v166
	v_and_b32_e32 v121, 0xffff0000, v166
	v_lshlrev_b32_e32 v122, 16, v167
	v_and_b32_e32 v123, 0xffff0000, v167
	v_lshlrev_b32_e32 v124, 16, v168
	v_and_b32_e32 v125, 0xffff0000, v168
	v_lshlrev_b32_e32 v126, 16, v169
	v_and_b32_e32 v127, 0xffff0000, v169
	v_lshlrev_b32_e32 v128, 16, v170
	v_and_b32_e32 v129, 0xffff0000, v170
	v_lshlrev_b32_e32 v130, 16, v171
	v_and_b32_e32 v131, 0xffff0000, v171
	v_cvt_f32_f16_e32 v198, v80
	v_cvt_f32_f16_sdwa v199, v80 dst_sel:DWORD dst_unused:UNUSED_PAD src0_sel:WORD_1
	v_cvt_f32_f16_e32 v200, v81
	v_cvt_f32_f16_sdwa v201, v81 dst_sel:DWORD dst_unused:UNUSED_PAD src0_sel:WORD_1
	v_cvt_f32_f16_e32 v202, v82
	v_cvt_f32_f16_sdwa v203, v82 dst_sel:DWORD dst_unused:UNUSED_PAD src0_sel:WORD_1
	v_cvt_f32_f16_e32 v204, v83
	v_cvt_f32_f16_sdwa v205, v83 dst_sel:DWORD dst_unused:UNUSED_PAD src0_sel:WORD_1
	v_cvt_f32_f16_e32 v206, v84
	v_cvt_f32_f16_sdwa v207, v84 dst_sel:DWORD dst_unused:UNUSED_PAD src0_sel:WORD_1
	v_cvt_f32_f16_e32 v208, v85
	v_cvt_f32_f16_sdwa v209, v85 dst_sel:DWORD dst_unused:UNUSED_PAD src0_sel:WORD_1
	v_cvt_f32_f16_e32 v210, v86
	v_cvt_f32_f16_sdwa v211, v86 dst_sel:DWORD dst_unused:UNUSED_PAD src0_sel:WORD_1
	v_cvt_f32_f16_e32 v212, v87
	v_cvt_f32_f16_sdwa v213, v87 dst_sel:DWORD dst_unused:UNUSED_PAD src0_sel:WORD_1
	global_load_dwordx4 v[80:83], v187, s[42:43] offset:0
	global_load_dwordx4 v[84:87], v187, s[42:43] offset:1024
	global_load_dwordx4 v[164:167], v187, s[44:45] offset:0
	global_load_dwordx4 v[168:171], v187, s[44:45] offset:1024
	v_pk_mul_f32 v[140:141], v[116:117], v[116:117]
	v_pk_fma_f32 v[140:141], v[118:119], v[118:119], v[140:141]
	v_pk_fma_f32 v[140:141], v[120:121], v[120:121], v[140:141]
	v_pk_fma_f32 v[140:141], v[122:123], v[122:123], v[140:141]
	v_pk_fma_f32 v[140:141], v[124:125], v[124:125], v[140:141]
	v_pk_fma_f32 v[140:141], v[126:127], v[126:127], v[140:141]
	v_pk_fma_f32 v[140:141], v[128:129], v[128:129], v[140:141]
	v_pk_fma_f32 v[140:141], v[130:131], v[130:131], v[140:141]
	v_add_f32_e32 v140, v140, v141
	s_nop 1
	v_add_f32_dpp v140, v140, v140 quad_perm:[1,0,3,2] row_mask:0xf bank_mask:0xf
	s_nop 1
	v_add_f32_dpp v140, v140, v140 quad_perm:[2,3,0,1] row_mask:0xf bank_mask:0xf
	s_nop 1
	v_add_f32_dpp v140, v140, v140 row_ror:4 row_mask:0xf bank_mask:0xf
	s_nop 1
	v_add_f32_dpp v140, v140, v140 row_ror:8 row_mask:0xf bank_mask:0xf
	s_nop 1
	v_add_f32_dpp v140, v140, v140 row_bcast:15 row_mask:0xa bank_mask:0xf
	s_nop 1
	v_add_f32_dpp v140, v140, v140 row_bcast:31 row_mask:0xc bank_mask:0xf
	s_nop 1
	v_fmamk_f32 v140, v140, 0x3a800000, v224
	v_rsq_f32_e32 v140, v140
	s_nop 0
	v_mul_f32_e32 v140, v144, v140
	s_nop 0
	v_readlane_b32 s4, v140, 63
	s_nop 1
	v_pk_mul_f32 v[116:117], v[116:117], s[4:5] op_sel_hi:[1,0]
	v_pk_mul_f32 v[118:119], v[118:119], s[4:5] op_sel_hi:[1,0]
	v_pk_mul_f32 v[120:121], v[120:121], s[4:5] op_sel_hi:[1,0]
	v_pk_mul_f32 v[122:123], v[122:123], s[4:5] op_sel_hi:[1,0]
	v_pk_mul_f32 v[124:125], v[124:125], s[4:5] op_sel_hi:[1,0]
	v_pk_mul_f32 v[126:127], v[126:127], s[4:5] op_sel_hi:[1,0]
	v_pk_mul_f32 v[128:129], v[128:129], s[4:5] op_sel_hi:[1,0]
	v_pk_mul_f32 v[130:131], v[130:131], s[4:5] op_sel_hi:[1,0]
	v_pk_fma_f32 v[198:199], v[0:1], v[116:117], v[198:199]
	v_pk_fma_f32 v[200:201], v[2:3], v[118:119], v[200:201]
	v_pk_fma_f32 v[202:203], v[4:5], v[120:121], v[202:203]
; template <int R, bool SRCB> ...
;     ...
;         for (int r = 0; r < R; ++r) {
;             f32x4 y[2][2]; float ss = 0.f;
; #pragma unroll
;             for (int j = 0; j < 2; ++j) { const u32x4 t = yr[r][j];
;                 y[j][0] = (f32x4){bf_lo(t.x), bf_hi(t.x), bf_lo(t.y), bf_hi(t.y)}; y[j][1] = (f32x4){bf_lo(t.z), bf_hi(t.z), bf_lo(t.w), bf_hi(t.w)};
;                 if (R == 1 && YP) {
; #pragma unroll
;                     for (int k = 0; k < 2; ++k) { const float* pp = YP + (size_t)(row0 - M_LAT) * DM + 8 * lane + 512 * j + 4 * k; f32x4 s = *(const f32x4*)pp;
; #pragma unroll
;                         for (int q = 1; q < pg8::NSL; ++q) s = s + *(const f32x4*)(pp + (size_t)q * 2048 * DM);
;                         y[j][k] = s; } }
; #pragma unroll
;                 for (int k = 0; k < 2; ++k) ss += (y[j][k][0] * y[j][k][0] + y[j][k][1] * y[j][k][1]) + (y[j][k][2] * y[j][k][2] + y[j][k][3] * y[j][k][3]); }
;             const float rr = __builtin_amdgcn_rsqf(wave_sum(ss) * (1.0f / DM) + 1e-6f) * w;
; #pragma unroll
;             for (int j = 0; j < 2; ++j)
; #pragma unroll
;                 for (int k = 0; k < 2; ++k) h[r][j][k] = h[r][j][k] + gg[j][k] * (y[j][k] * rr);
;         }
;     }
; #pragma unroll
;     for (int r = 0; r < R; ++r)
; #pragma unroll
;         for (int j = 0; j < 2; ++j) { const int c = 8 * lane + 512 * j;
;             if (final_out) { *(f32x4*)(final_out + (size_t)(row0 + r) * DM + c) = h[r][j][0]; *(f32x4*)(final_out + (size_t)(row0 + r) * DM + c + 4) = h[r][j][1]; }
;             else { u32x4 t; t.x = pkh2(h[r][j][0][0], h[r][j][0][1]); t.y = pkh2(h[r][j][0][2], h[r][j][0][3]); t.z = pkh2(h[r][j][1][0], h[r][j][1][1]); t.w = pkh2(h[r][j][1][2], h[r][j][1][3]);
;                 *(u32x4*)(hout + (size_t)(row0 + r) * DM + c) = t; } }
;     if (U) {
;         f32x4 gp[2][2], sc1[2][2], sh[2][2];
; #pragma unroll
;         for (int j = 0; j < 2; ++j)
; #pragma unroll
;             for (int k = 0; k < 2; ++k) { const int c = 8 * lane + 512 * j + 4 * k; gp[j][k] = *(const f32x4*)(gpre + c); sc1[j][k] = *(const f32x4*)(scale + (size_t)mrow * 9216 + c) + 1.0f; sh[j][k] = *(const f32x4*)(shift + (size_t)mrow * 9216 + c); }
; #pragma unroll
;         for (int r = 0; r < R; ++r) {
;             float ss = 0.f;
; #pragma unroll
;             for (int j = 0; j < 2; ++j)
; #pragma unroll
	v_pk_fma_f32 v[204:205], v[6:7], v[122:123], v[204:205]
	v_pk_fma_f32 v[206:207], v[8:9], v[124:125], v[206:207]
	v_pk_fma_f32 v[208:209], v[10:11], v[126:127], v[208:209]
	v_pk_fma_f32 v[210:211], v[12:13], v[128:129], v[210:211]
	v_pk_fma_f32 v[212:213], v[14:15], v[130:131], v[212:213]
	v_cvt_f16_f32_e32 v132, v198
	v_cvt_f16_f32_e32 v133, v200
	v_cvt_f16_f32_e32 v134, v202
	v_cvt_f16_f32_e32 v135, v204
	v_cvt_f16_f32_e32 v136, v206
	v_cvt_f16_f32_e32 v137, v208
	v_cvt_f16_f32_e32 v138, v210
	v_cvt_f16_f32_e32 v139, v212
	v_cvt_f16_f32_sdwa v132, v199 dst_sel:WORD_1 dst_unused:UNUSED_PRESERVE src0_sel:DWORD
	v_cvt_f16_f32_sdwa v133, v201 dst_sel:WORD_1 dst_unused:UNUSED_PRESERVE src0_sel:DWORD
	v_cvt_f16_f32_sdwa v134, v203 dst_sel:WORD_1 dst_unused:UNUSED_PRESERVE src0_sel:DWORD
	v_cvt_f16_f32_sdwa v135, v205 dst_sel:WORD_1 dst_unused:UNUSED_PRESERVE src0_sel:DWORD
	v_cvt_f16_f32_sdwa v136, v207 dst_sel:WORD_1 dst_unused:UNUSED_PRESERVE src0_sel:DWORD
	v_cvt_f16_f32_sdwa v137, v209 dst_sel:WORD_1 dst_unused:UNUSED_PRESERVE src0_sel:DWORD
	v_cvt_f16_f32_sdwa v138, v211 dst_sel:WORD_1 dst_unused:UNUSED_PRESERVE src0_sel:DWORD
	v_cvt_f16_f32_sdwa v139, v213 dst_sel:WORD_1 dst_unused:UNUSED_PRESERVE src0_sel:DWORD
	s_nop 0
	global_store_dwordx4 v186, v[132:135], s[42:43] offset:0 sc1
	global_store_dwordx4 v186, v[136:139], s[42:43] offset:1024 sc1
	v_pk_mul_f32 v[140:141], v[198:199], v[198:199]
	v_pk_fma_f32 v[140:141], v[200:201], v[200:201], v[140:141]
	v_pk_fma_f32 v[140:141], v[202:203], v[202:203], v[140:141]
	v_pk_fma_f32 v[140:141], v[204:205], v[204:205], v[140:141]
	v_pk_fma_f32 v[140:141], v[206:207], v[206:207], v[140:141]
	v_pk_fma_f32 v[140:141], v[208:209], v[208:209], v[140:141]
	v_pk_fma_f32 v[140:141], v[210:211], v[210:211], v[140:141]
	v_pk_fma_f32 v[140:141], v[212:213], v[212:213], v[140:141]
	v_add_f32_e32 v140, v140, v141
	s_nop 1
	v_add_f32_dpp v140, v140, v140 quad_perm:[1,0,3,2] row_mask:0xf bank_mask:0xf
	s_nop 1
	v_add_f32_dpp v140, v140, v140 quad_perm:[2,3,0,1] row_mask:0xf bank_mask:0xf
	s_nop 1
	v_add_f32_dpp v140, v140, v140 row_ror:4 row_mask:0xf bank_mask:0xf
	s_nop 1
	v_add_f32_dpp v140, v140, v140 row_ror:8 row_mask:0xf bank_mask:0xf
	s_nop 1
	v_add_f32_dpp v140, v140, v140 row_bcast:15 row_mask:0xa bank_mask:0xf
	s_nop 1
	v_add_f32_dpp v140, v140, v140 row_bcast:31 row_mask:0xc bank_mask:0xf
	s_nop 1
	v_fmamk_f32 v140, v140, 0x3a800000, v224
	v_rsq_f32_e32 v140, v140
	s_nop 0
	v_readlane_b32 s6, v140, 63
	s_nop 1
	v_pk_mul_f32 v[198:199], v[198:199], s[6:7] op_sel_hi:[1,0]
	v_pk_mul_f32 v[200:201], v[200:201], s[6:7] op_sel_hi:[1,0]
	v_pk_mul_f32 v[202:203], v[202:203], s[6:7] op_sel_hi:[1,0]
	v_pk_mul_f32 v[204:205], v[204:205], s[6:7] op_sel_hi:[1,0]
	v_pk_mul_f32 v[206:207], v[206:207], s[6:7] op_sel_hi:[1,0]
	v_pk_mul_f32 v[208:209], v[208:209], s[6:7] op_sel_hi:[1,0]
	v_pk_mul_f32 v[210:211], v[210:211], s[6:7] op_sel_hi:[1,0]
	v_pk_mul_f32 v[212:213], v[212:213], s[6:7] op_sel_hi:[1,0]
	v_pk_mul_f32 v[198:199], v[16:17], v[198:199]
	v_pk_mul_f32 v[200:201], v[18:19], v[200:201]
	v_pk_mul_f32 v[202:203], v[20:21], v[202:203]
	v_pk_mul_f32 v[204:205], v[22:23], v[204:205]
	v_pk_mul_f32 v[206:207], v[24:25], v[206:207]
	v_pk_mul_f32 v[208:209], v[26:27], v[208:209]
	v_pk_mul_f32 v[210:211], v[28:29], v[210:211]
	v_pk_mul_f32 v[212:213], v[30:31], v[212:213]
	v_pk_fma_f32 v[198:199], v[32:33], v[198:199], v[48:49]
	v_pk_fma_f32 v[200:201], v[34:35], v[200:201], v[50:51]
	v_pk_fma_f32 v[202:203], v[36:37], v[202:203], v[52:53]
	v_pk_fma_f32 v[204:205], v[38:39], v[204:205], v[54:55]
	v_pk_fma_f32 v[206:207], v[40:41], v[206:207], v[56:57]
	v_pk_fma_f32 v[208:209], v[42:43], v[208:209], v[58:59]
	v_pk_fma_f32 v[210:211], v[44:45], v[210:211], v[60:61]
	v_pk_fma_f32 v[212:213], v[46:47], v[212:213], v[62:63]
	v_cvt_pk_bf16_f32 v230, v198, v199
	v_cvt_pk_bf16_f32 v231, v200, v201
	v_cvt_pk_bf16_f32 v232, v202, v203
	v_cvt_pk_bf16_f32 v233, v204, v205
	v_cvt_pk_bf16_f32 v234, v206, v207
	v_cvt_pk_bf16_f32 v235, v208, v209
	v_cvt_pk_bf16_f32 v236, v210, v211
	v_cvt_pk_bf16_f32 v237, v212, v213
	global_store_dwordx4 v186, v[230:233], s[44:45] offset:0 sc1
	global_store_dwordx4 v186, v[234:237], s[44:45] offset:1024 sc1
	s_waitcnt vmcnt(28)
; template <int R, bool SRCB> ...
;     ...
;         for (int r = 0; r < R; ++r) {
;             f32x4 y[2][2]; float ss = 0.f;
; #pragma unroll
;             for (int j = 0; j < 2; ++j) { const u32x4 t = yr[r][j];
;                 y[j][0] = (f32x4){bf_lo(t.x), bf_hi(t.x), bf_lo(t.y), bf_hi(t.y)}; y[j][1] = (f32x4){bf_lo(t.z), bf_hi(t.z), bf_lo(t.w), bf_hi(t.w)};
;                 if (R == 1 && YP) {
; #pragma unroll
;                     for (int k = 0; k < 2; ++k) { const float* pp = YP + (size_t)(row0 - M_LAT) * DM + 8 * lane + 512 * j + 4 * k; f32x4 s = *(const f32x4*)pp;
; #pragma unroll
;                         for (int q = 1; q < pg8::NSL; ++q) s = s + *(const f32x4*)(pp + (size_t)q * 2048 * DM);
;                         y[j][k] = s; } }
; #pragma unroll
;                 for (int k = 0; k < 2; ++k) ss += (y[j][k][0] * y[j][k][0] + y[j][k][1] * y[j][k][1]) + (y[j][k][2] * y[j][k][2] + y[j][k][3] * y[j][k][3]); }
;             const float rr = __builtin_amdgcn_rsqf(wave_sum(ss) * (1.0f / DM) + 1e-6f) * w;
; #pragma unroll
;             for (int j = 0; j < 2; ++j)
; #pragma unroll
;                 for (int k = 0; k < 2; ++k) h[r][j][k] = h[r][j][k] + gg[j][k] * (y[j][k] * rr);
;         }
;     }
; #pragma unroll
;     for (int r = 0; r < R; ++r)
; #pragma unroll
;         for (int j = 0; j < 2; ++j) { const int c = 8 * lane + 512 * j;
;             if (final_out) { *(f32x4*)(final_out + (size_t)(row0 + r) * DM + c) = h[r][j][0]; *(f32x4*)(final_out + (size_t)(row0 + r) * DM + c + 4) = h[r][j][1]; }
;             else { u32x4 t; t.x = pkh2(h[r][j][0][0], h[r][j][0][1]); t.y = pkh2(h[r][j][0][2], h[r][j][0][3]); t.z = pkh2(h[r][j][1][0], h[r][j][1][1]); t.w = pkh2(h[r][j][1][2], h[r][j][1][3]);
;                 *(u32x4*)(hout + (size_t)(row0 + r) * DM + c) = t; } }
;     if (U) {
;         f32x4 gp[2][2], sc1[2][2], sh[2][2];
; #pragma unroll
;         for (int j = 0; j < 2; ++j)
; #pragma unroll
;             for (int k = 0; k < 2; ++k) { const int c = 8 * lane + 512 * j + 4 * k; gp[j][k] = *(const f32x4*)(gpre + c); sc1[j][k] = *(const f32x4*)(scale + (size_t)mrow * 9216 + c) + 1.0f; sh[j][k] = *(const f32x4*)(shift + (size_t)mrow * 9216 + c); }
; #pragma unroll
;         for (int r = 0; r < R; ++r) {
;             float ss = 0.f;
; #pragma unroll
;             for (int j = 0; j < 2; ++j)
; #pragma unroll
	v_lshlrev_b32_e32 v116, 16, v172
	v_and_b32_e32 v117, 0xffff0000, v172
	v_lshlrev_b32_e32 v118, 16, v173
	v_and_b32_e32 v119, 0xffff0000, v173
	v_lshlrev_b32_e32 v120, 16, v174
	v_and_b32_e32 v121, 0xffff0000, v174
	v_lshlrev_b32_e32 v122, 16, v175
	v_and_b32_e32 v123, 0xffff0000, v175
	v_lshlrev_b32_e32 v124, 16, v176
	v_and_b32_e32 v125, 0xffff0000, v176
	v_lshlrev_b32_e32 v126, 16, v177
	v_and_b32_e32 v127, 0xffff0000, v177
	v_lshlrev_b32_e32 v128, 16, v178
	v_and_b32_e32 v129, 0xffff0000, v178
	v_lshlrev_b32_e32 v130, 16, v179
	v_and_b32_e32 v131, 0xffff0000, v179
	v_cvt_f32_f16_e32 v198, v88
	v_cvt_f32_f16_sdwa v199, v88 dst_sel:DWORD dst_unused:UNUSED_PAD src0_sel:WORD_1
	v_cvt_f32_f16_e32 v200, v89
	v_cvt_f32_f16_sdwa v201, v89 dst_sel:DWORD dst_unused:UNUSED_PAD src0_sel:WORD_1
	v_cvt_f32_f16_e32 v202, v90
	v_cvt_f32_f16_sdwa v203, v90 dst_sel:DWORD dst_unused:UNUSED_PAD src0_sel:WORD_1
	v_cvt_f32_f16_e32 v204, v91
	v_cvt_f32_f16_sdwa v205, v91 dst_sel:DWORD dst_unused:UNUSED_PAD src0_sel:WORD_1
	v_cvt_f32_f16_e32 v206, v92
	v_cvt_f32_f16_sdwa v207, v92 dst_sel:DWORD dst_unused:UNUSED_PAD src0_sel:WORD_1
	v_cvt_f32_f16_e32 v208, v93
	v_cvt_f32_f16_sdwa v209, v93 dst_sel:DWORD dst_unused:UNUSED_PAD src0_sel:WORD_1
	v_cvt_f32_f16_e32 v210, v94
	v_cvt_f32_f16_sdwa v211, v94 dst_sel:DWORD dst_unused:UNUSED_PAD src0_sel:WORD_1
	v_cvt_f32_f16_e32 v212, v95
	v_cvt_f32_f16_sdwa v213, v95 dst_sel:DWORD dst_unused:UNUSED_PAD src0_sel:WORD_1
	global_load_dwordx4 v[88:91], v187, s[42:43] offset:2048
	global_load_dwordx4 v[92:95], v187, s[42:43] offset:3072
	global_load_dwordx4 v[172:175], v187, s[44:45] offset:2048
	global_load_dwordx4 v[176:179], v187, s[44:45] offset:3072
	v_pk_mul_f32 v[140:141], v[116:117], v[116:117]
	v_pk_fma_f32 v[140:141], v[118:119], v[118:119], v[140:141]
	v_pk_fma_f32 v[140:141], v[120:121], v[120:121], v[140:141]
	v_pk_fma_f32 v[140:141], v[122:123], v[122:123], v[140:141]
	v_pk_fma_f32 v[140:141], v[124:125], v[124:125], v[140:141]
	v_pk_fma_f32 v[140:141], v[126:127], v[126:127], v[140:141]
	v_pk_fma_f32 v[140:141], v[128:129], v[128:129], v[140:141]
	v_pk_fma_f32 v[140:141], v[130:131], v[130:131], v[140:141]
	v_add_f32_e32 v140, v140, v141
	s_nop 1
	v_add_f32_dpp v140, v140, v140 quad_perm:[1,0,3,2] row_mask:0xf bank_mask:0xf
	s_nop 1
	v_add_f32_dpp v140, v140, v140 quad_perm:[2,3,0,1] row_mask:0xf bank_mask:0xf
	s_nop 1
	v_add_f32_dpp v140, v140, v140 row_ror:4 row_mask:0xf bank_mask:0xf
	s_nop 1
	v_add_f32_dpp v140, v140, v140 row_ror:8 row_mask:0xf bank_mask:0xf
	s_nop 1
	v_add_f32_dpp v140, v140, v140 row_bcast:15 row_mask:0xa bank_mask:0xf
	s_nop 1
	v_add_f32_dpp v140, v140, v140 row_bcast:31 row_mask:0xc bank_mask:0xf
	s_nop 1
	v_fmamk_f32 v140, v140, 0x3a800000, v224
	v_rsq_f32_e32 v140, v140
	s_nop 0
	v_mul_f32_e32 v140, v144, v140
	s_nop 0
	v_readlane_b32 s4, v140, 63
	s_nop 1
	v_pk_mul_f32 v[116:117], v[116:117], s[4:5] op_sel_hi:[1,0]
	v_pk_mul_f32 v[118:119], v[118:119], s[4:5] op_sel_hi:[1,0]
	v_pk_mul_f32 v[120:121], v[120:121], s[4:5] op_sel_hi:[1,0]
	v_pk_mul_f32 v[122:123], v[122:123], s[4:5] op_sel_hi:[1,0]
	v_pk_mul_f32 v[124:125], v[124:125], s[4:5] op_sel_hi:[1,0]
	v_pk_mul_f32 v[126:127], v[126:127], s[4:5] op_sel_hi:[1,0]
	v_pk_mul_f32 v[128:129], v[128:129], s[4:5] op_sel_hi:[1,0]
	v_pk_mul_f32 v[130:131], v[130:131], s[4:5] op_sel_hi:[1,0]
	v_pk_fma_f32 v[198:199], v[0:1], v[116:117], v[198:199]
	v_pk_fma_f32 v[200:201], v[2:3], v[118:119], v[200:201]
	v_pk_fma_f32 v[202:203], v[4:5], v[120:121], v[202:203]
	v_pk_fma_f32 v[204:205], v[6:7], v[122:123], v[204:205]
	v_pk_fma_f32 v[206:207], v[8:9], v[124:125], v[206:207]
	v_pk_fma_f32 v[208:209], v[10:11], v[126:127], v[208:209]
	v_pk_fma_f32 v[210:211], v[12:13], v[128:129], v[210:211]
	v_pk_fma_f32 v[212:213], v[14:15], v[130:131], v[212:213]
	v_cvt_f16_f32_e32 v132, v198
	v_cvt_f16_f32_e32 v133, v200
	v_cvt_f16_f32_e32 v134, v202
	v_cvt_f16_f32_e32 v135, v204
	v_cvt_f16_f32_e32 v136, v206
	v_cvt_f16_f32_e32 v137, v208
	v_cvt_f16_f32_e32 v138, v210
	v_cvt_f16_f32_e32 v139, v212
	v_cvt_f16_f32_sdwa v132, v199 dst_sel:WORD_1 dst_unused:UNUSED_PRESERVE src0_sel:DWORD
	v_cvt_f16_f32_sdwa v133, v201 dst_sel:WORD_1 dst_unused:UNUSED_PRESERVE src0_sel:DWORD
	v_cvt_f16_f32_sdwa v134, v203 dst_sel:WORD_1 dst_unused:UNUSED_PRESERVE src0_sel:DWORD
	v_cvt_f16_f32_sdwa v135, v205 dst_sel:WORD_1 dst_unused:UNUSED_PRESERVE src0_sel:DWORD
	v_cvt_f16_f32_sdwa v136, v207 dst_sel:WORD_1 dst_unused:UNUSED_PRESERVE src0_sel:DWORD
	v_cvt_f16_f32_sdwa v137, v209 dst_sel:WORD_1 dst_unused:UNUSED_PRESERVE src0_sel:DWORD
	v_cvt_f16_f32_sdwa v138, v211 dst_sel:WORD_1 dst_unused:UNUSED_PRESERVE src0_sel:DWORD
	v_cvt_f16_f32_sdwa v139, v213 dst_sel:WORD_1 dst_unused:UNUSED_PRESERVE src0_sel:DWORD
	s_nop 0
	global_store_dwordx4 v186, v[132:135], s[42:43] offset:2048 sc1
	global_store_dwordx4 v186, v[136:139], s[42:43] offset:3072 sc1
	v_pk_mul_f32 v[140:141], v[198:199], v[198:199]
	v_pk_fma_f32 v[140:141], v[200:201], v[200:201], v[140:141]
	v_pk_fma_f32 v[140:141], v[202:203], v[202:203], v[140:141]
	v_pk_fma_f32 v[140:141], v[204:205], v[204:205], v[140:141]
	v_pk_fma_f32 v[140:141], v[206:207], v[206:207], v[140:141]
	v_pk_fma_f32 v[140:141], v[208:209], v[208:209], v[140:141]
	v_pk_fma_f32 v[140:141], v[210:211], v[210:211], v[140:141]
	v_pk_fma_f32 v[140:141], v[212:213], v[212:213], v[140:141]
	v_add_f32_e32 v140, v140, v141
	s_nop 1
	v_add_f32_dpp v140, v140, v140 quad_perm:[1,0,3,2] row_mask:0xf bank_mask:0xf
	s_nop 1
	v_add_f32_dpp v140, v140, v140 quad_perm:[2,3,0,1] row_mask:0xf bank_mask:0xf
	s_nop 1
	v_add_f32_dpp v140, v140, v140 row_ror:4 row_mask:0xf bank_mask:0xf
; template <int R, bool SRCB> ...
;     ...
;         for (int r = 0; r < R; ++r) {
;             f32x4 y[2][2]; float ss = 0.f;
; #pragma unroll
;             for (int j = 0; j < 2; ++j) { const u32x4 t = yr[r][j];
;                 y[j][0] = (f32x4){bf_lo(t.x), bf_hi(t.x), bf_lo(t.y), bf_hi(t.y)}; y[j][1] = (f32x4){bf_lo(t.z), bf_hi(t.z), bf_lo(t.w), bf_hi(t.w)};
;                 if (R == 1 && YP) {
; #pragma unroll
;                     for (int k = 0; k < 2; ++k) { const float* pp = YP + (size_t)(row0 - M_LAT) * DM + 8 * lane + 512 * j + 4 * k; f32x4 s = *(const f32x4*)pp;
; #pragma unroll
;                         for (int q = 1; q < pg8::NSL; ++q) s = s + *(const f32x4*)(pp + (size_t)q * 2048 * DM);
;                         y[j][k] = s; } }
; #pragma unroll
;                 for (int k = 0; k < 2; ++k) ss += (y[j][k][0] * y[j][k][0] + y[j][k][1] * y[j][k][1]) + (y[j][k][2] * y[j][k][2] + y[j][k][3] * y[j][k][3]); }
;             const float rr = __builtin_amdgcn_rsqf(wave_sum(ss) * (1.0f / DM) + 1e-6f) * w;
; #pragma unroll
;             for (int j = 0; j < 2; ++j)
; #pragma unroll
;                 for (int k = 0; k < 2; ++k) h[r][j][k] = h[r][j][k] + gg[j][k] * (y[j][k] * rr);
;         }
;     }
; #pragma unroll
;     for (int r = 0; r < R; ++r)
; #pragma unroll
;         for (int j = 0; j < 2; ++j) { const int c = 8 * lane + 512 * j;
;             if (final_out) { *(f32x4*)(final_out + (size_t)(row0 + r) * DM + c) = h[r][j][0]; *(f32x4*)(final_out + (size_t)(row0 + r) * DM + c + 4) = h[r][j][1]; }
;             else { u32x4 t; t.x = pkh2(h[r][j][0][0], h[r][j][0][1]); t.y = pkh2(h[r][j][0][2], h[r][j][0][3]); t.z = pkh2(h[r][j][1][0], h[r][j][1][1]); t.w = pkh2(h[r][j][1][2], h[r][j][1][3]);
;                 *(u32x4*)(hout + (size_t)(row0 + r) * DM + c) = t; } }
;     if (U) {
;         f32x4 gp[2][2], sc1[2][2], sh[2][2];
; #pragma unroll
;         for (int j = 0; j < 2; ++j)
; #pragma unroll
;             for (int k = 0; k < 2; ++k) { const int c = 8 * lane + 512 * j + 4 * k; gp[j][k] = *(const f32x4*)(gpre + c); sc1[j][k] = *(const f32x4*)(scale + (size_t)mrow * 9216 + c) + 1.0f; sh[j][k] = *(const f32x4*)(shift + (size_t)mrow * 9216 + c); }
; #pragma unroll
;         for (int r = 0; r < R; ++r) {
;             float ss = 0.f;
; #pragma unroll
;             for (int j = 0; j < 2; ++j)
; #pragma unroll
	s_nop 1
	v_add_f32_dpp v140, v140, v140 row_ror:8 row_mask:0xf bank_mask:0xf
	s_nop 1
	v_add_f32_dpp v140, v140, v140 row_bcast:15 row_mask:0xa bank_mask:0xf
	s_nop 1
	v_add_f32_dpp v140, v140, v140 row_bcast:31 row_mask:0xc bank_mask:0xf
	s_nop 1
	v_fmamk_f32 v140, v140, 0x3a800000, v224
	v_rsq_f32_e32 v140, v140
	s_nop 0
	v_readlane_b32 s6, v140, 63
	s_nop 1
	v_pk_mul_f32 v[198:199], v[198:199], s[6:7] op_sel_hi:[1,0]
	v_pk_mul_f32 v[200:201], v[200:201], s[6:7] op_sel_hi:[1,0]
	v_pk_mul_f32 v[202:203], v[202:203], s[6:7] op_sel_hi:[1,0]
	v_pk_mul_f32 v[204:205], v[204:205], s[6:7] op_sel_hi:[1,0]
	v_pk_mul_f32 v[206:207], v[206:207], s[6:7] op_sel_hi:[1,0]
	v_pk_mul_f32 v[208:209], v[208:209], s[6:7] op_sel_hi:[1,0]
	v_pk_mul_f32 v[210:211], v[210:211], s[6:7] op_sel_hi:[1,0]
	v_pk_mul_f32 v[212:213], v[212:213], s[6:7] op_sel_hi:[1,0]
	v_pk_mul_f32 v[198:199], v[16:17], v[198:199]
	v_pk_mul_f32 v[200:201], v[18:19], v[200:201]
	v_pk_mul_f32 v[202:203], v[20:21], v[202:203]
	v_pk_mul_f32 v[204:205], v[22:23], v[204:205]
	v_pk_mul_f32 v[206:207], v[24:25], v[206:207]
	v_pk_mul_f32 v[208:209], v[26:27], v[208:209]
	v_pk_mul_f32 v[210:211], v[28:29], v[210:211]
	v_pk_mul_f32 v[212:213], v[30:31], v[212:213]
	v_pk_fma_f32 v[198:199], v[32:33], v[198:199], v[48:49]
	v_pk_fma_f32 v[200:201], v[34:35], v[200:201], v[50:51]
	v_pk_fma_f32 v[202:203], v[36:37], v[202:203], v[52:53]
	v_pk_fma_f32 v[204:205], v[38:39], v[204:205], v[54:55]
	v_pk_fma_f32 v[206:207], v[40:41], v[206:207], v[56:57]
	v_pk_fma_f32 v[208:209], v[42:43], v[208:209], v[58:59]
	v_pk_fma_f32 v[210:211], v[44:45], v[210:211], v[60:61]
	v_pk_fma_f32 v[212:213], v[46:47], v[212:213], v[62:63]
	v_cvt_pk_bf16_f32 v230, v198, v199
	v_cvt_pk_bf16_f32 v231, v200, v201
	v_cvt_pk_bf16_f32 v232, v202, v203
	v_cvt_pk_bf16_f32 v233, v204, v205
	v_cvt_pk_bf16_f32 v234, v206, v207
	v_cvt_pk_bf16_f32 v235, v208, v209
	v_cvt_pk_bf16_f32 v236, v210, v211
	v_cvt_pk_bf16_f32 v237, v212, v213
	global_store_dwordx4 v186, v[230:233], s[44:45] offset:2048 sc1
	global_store_dwordx4 v186, v[234:237], s[44:45] offset:3072 sc1
	s_waitcnt vmcnt(28)
	v_lshlrev_b32_e32 v116, 16, v148
	v_and_b32_e32 v117, 0xffff0000, v148
	v_lshlrev_b32_e32 v118, 16, v149
	v_and_b32_e32 v119, 0xffff0000, v149
	v_lshlrev_b32_e32 v120, 16, v150
	v_and_b32_e32 v121, 0xffff0000, v150
	v_lshlrev_b32_e32 v122, 16, v151
	v_and_b32_e32 v123, 0xffff0000, v151
	v_lshlrev_b32_e32 v124, 16, v152
	v_and_b32_e32 v125, 0xffff0000, v152
	v_lshlrev_b32_e32 v126, 16, v153
	v_and_b32_e32 v127, 0xffff0000, v153
	v_lshlrev_b32_e32 v128, 16, v154
	v_and_b32_e32 v129, 0xffff0000, v154
	v_lshlrev_b32_e32 v130, 16, v155
	v_and_b32_e32 v131, 0xffff0000, v155
	v_cvt_f32_f16_e32 v198, v64
	v_cvt_f32_f16_sdwa v199, v64 dst_sel:DWORD dst_unused:UNUSED_PAD src0_sel:WORD_1
	v_cvt_f32_f16_e32 v200, v65
	v_cvt_f32_f16_sdwa v201, v65 dst_sel:DWORD dst_unused:UNUSED_PAD src0_sel:WORD_1
	v_cvt_f32_f16_e32 v202, v66
	v_cvt_f32_f16_sdwa v203, v66 dst_sel:DWORD dst_unused:UNUSED_PAD src0_sel:WORD_1
	v_cvt_f32_f16_e32 v204, v67
	v_cvt_f32_f16_sdwa v205, v67 dst_sel:DWORD dst_unused:UNUSED_PAD src0_sel:WORD_1
	v_cvt_f32_f16_e32 v206, v68
	v_cvt_f32_f16_sdwa v207, v68 dst_sel:DWORD dst_unused:UNUSED_PAD src0_sel:WORD_1
	v_cvt_f32_f16_e32 v208, v69
	v_cvt_f32_f16_sdwa v209, v69 dst_sel:DWORD dst_unused:UNUSED_PAD src0_sel:WORD_1
	v_cvt_f32_f16_e32 v210, v70
	v_cvt_f32_f16_sdwa v211, v70 dst_sel:DWORD dst_unused:UNUSED_PAD src0_sel:WORD_1
	v_cvt_f32_f16_e32 v212, v71
	v_cvt_f32_f16_sdwa v213, v71 dst_sel:DWORD dst_unused:UNUSED_PAD src0_sel:WORD_1
	v_pk_mul_f32 v[140:141], v[116:117], v[116:117]
	v_pk_fma_f32 v[140:141], v[118:119], v[118:119], v[140:141]
	v_pk_fma_f32 v[140:141], v[120:121], v[120:121], v[140:141]
	v_pk_fma_f32 v[140:141], v[122:123], v[122:123], v[140:141]
	v_pk_fma_f32 v[140:141], v[124:125], v[124:125], v[140:141]
	v_pk_fma_f32 v[140:141], v[126:127], v[126:127], v[140:141]
	v_pk_fma_f32 v[140:141], v[128:129], v[128:129], v[140:141]
	v_pk_fma_f32 v[140:141], v[130:131], v[130:131], v[140:141]
	v_add_f32_e32 v140, v140, v141
	s_nop 1
	v_add_f32_dpp v140, v140, v140 quad_perm:[1,0,3,2] row_mask:0xf bank_mask:0xf
	s_nop 1
	v_add_f32_dpp v140, v140, v140 quad_perm:[2,3,0,1] row_mask:0xf bank_mask:0xf
	s_nop 1
	v_add_f32_dpp v140, v140, v140 row_ror:4 row_mask:0xf bank_mask:0xf
	s_nop 1
	v_add_f32_dpp v140, v140, v140 row_ror:8 row_mask:0xf bank_mask:0xf
	s_nop 1
	v_add_f32_dpp v140, v140, v140 row_bcast:15 row_mask:0xa bank_mask:0xf
	s_nop 1
	v_add_f32_dpp v140, v140, v140 row_bcast:31 row_mask:0xc bank_mask:0xf
	s_nop 1
	v_fmamk_f32 v140, v140, 0x3a800000, v224
	v_rsq_f32_e32 v140, v140
	s_nop 0
	v_mul_f32_e32 v140, v144, v140
	s_nop 0
	v_readlane_b32 s4, v140, 63
	s_nop 1
	v_pk_mul_f32 v[116:117], v[116:117], s[4:5] op_sel_hi:[1,0]
	v_pk_mul_f32 v[118:119], v[118:119], s[4:5] op_sel_hi:[1,0]
	v_pk_mul_f32 v[120:121], v[120:121], s[4:5] op_sel_hi:[1,0]
	v_pk_mul_f32 v[122:123], v[122:123], s[4:5] op_sel_hi:[1,0]
	v_pk_mul_f32 v[124:125], v[124:125], s[4:5] op_sel_hi:[1,0]
	v_pk_mul_f32 v[126:127], v[126:127], s[4:5] op_sel_hi:[1,0]
	v_pk_mul_f32 v[128:129], v[128:129], s[4:5] op_sel_hi:[1,0]
	v_pk_mul_f32 v[130:131], v[130:131], s[4:5] op_sel_hi:[1,0]
	v_pk_fma_f32 v[198:199], v[0:1], v[116:117], v[198:199]
	v_pk_fma_f32 v[200:201], v[2:3], v[118:119], v[200:201]
	v_pk_fma_f32 v[202:203], v[4:5], v[120:121], v[202:203]
	v_pk_fma_f32 v[204:205], v[6:7], v[122:123], v[204:205]
	v_pk_fma_f32 v[206:207], v[8:9], v[124:125], v[206:207]
	v_pk_fma_f32 v[208:209], v[10:11], v[126:127], v[208:209]
	v_pk_fma_f32 v[210:211], v[12:13], v[128:129], v[210:211]
; template <int R, bool SRCB> ...
;     ...
;         for (int r = 0; r < R; ++r) {
;             f32x4 y[2][2]; float ss = 0.f;
; #pragma unroll
;             for (int j = 0; j < 2; ++j) { const u32x4 t = yr[r][j];
;                 y[j][0] = (f32x4){bf_lo(t.x), bf_hi(t.x), bf_lo(t.y), bf_hi(t.y)}; y[j][1] = (f32x4){bf_lo(t.z), bf_hi(t.z), bf_lo(t.w), bf_hi(t.w)};
;                 if (R == 1 && YP) {
; #pragma unroll
;                     for (int k = 0; k < 2; ++k) { const float* pp = YP + (size_t)(row0 - M_LAT) * DM + 8 * lane + 512 * j + 4 * k; f32x4 s = *(const f32x4*)pp;
; #pragma unroll
;                         for (int q = 1; q < pg8::NSL; ++q) s = s + *(const f32x4*)(pp + (size_t)q * 2048 * DM);
;                         y[j][k] = s; } }
; #pragma unroll
;                 for (int k = 0; k < 2; ++k) ss += (y[j][k][0] * y[j][k][0] + y[j][k][1] * y[j][k][1]) + (y[j][k][2] * y[j][k][2] + y[j][k][3] * y[j][k][3]); }
;             const float rr = __builtin_amdgcn_rsqf(wave_sum(ss) * (1.0f / DM) + 1e-6f) * w;
; #pragma unroll
;             for (int j = 0; j < 2; ++j)
; #pragma unroll
;                 for (int k = 0; k < 2; ++k) h[r][j][k] = h[r][j][k] + gg[j][k] * (y[j][k] * rr);
;         }
;     }
; #pragma unroll
;     for (int r = 0; r < R; ++r)
; #pragma unroll
;         for (int j = 0; j < 2; ++j) { const int c = 8 * lane + 512 * j;
;             if (final_out) { *(f32x4*)(final_out + (size_t)(row0 + r) * DM + c) = h[r][j][0]; *(f32x4*)(final_out + (size_t)(row0 + r) * DM + c + 4) = h[r][j][1]; }
;             else { u32x4 t; t.x = pkh2(h[r][j][0][0], h[r][j][0][1]); t.y = pkh2(h[r][j][0][2], h[r][j][0][3]); t.z = pkh2(h[r][j][1][0], h[r][j][1][1]); t.w = pkh2(h[r][j][1][2], h[r][j][1][3]);
;                 *(u32x4*)(hout + (size_t)(row0 + r) * DM + c) = t; } }
;     if (U) {
;         f32x4 gp[2][2], sc1[2][2], sh[2][2];
; #pragma unroll
;         for (int j = 0; j < 2; ++j)
; #pragma unroll
;             for (int k = 0; k < 2; ++k) { const int c = 8 * lane + 512 * j + 4 * k; gp[j][k] = *(const f32x4*)(gpre + c); sc1[j][k] = *(const f32x4*)(scale + (size_t)mrow * 9216 + c) + 1.0f; sh[j][k] = *(const f32x4*)(shift + (size_t)mrow * 9216 + c); }
; #pragma unroll
;         for (int r = 0; r < R; ++r) {
;             float ss = 0.f;
; #pragma unroll
;             for (int j = 0; j < 2; ++j)
; #pragma unroll
	v_pk_fma_f32 v[212:213], v[14:15], v[130:131], v[212:213]
	v_cvt_f16_f32_e32 v132, v198
	v_cvt_f16_f32_e32 v133, v200
	v_cvt_f16_f32_e32 v134, v202
	v_cvt_f16_f32_e32 v135, v204
	v_cvt_f16_f32_e32 v136, v206
	v_cvt_f16_f32_e32 v137, v208
	v_cvt_f16_f32_e32 v138, v210
	v_cvt_f16_f32_e32 v139, v212
	v_cvt_f16_f32_sdwa v132, v199 dst_sel:WORD_1 dst_unused:UNUSED_PRESERVE src0_sel:DWORD
	v_cvt_f16_f32_sdwa v133, v201 dst_sel:WORD_1 dst_unused:UNUSED_PRESERVE src0_sel:DWORD
	v_cvt_f16_f32_sdwa v134, v203 dst_sel:WORD_1 dst_unused:UNUSED_PRESERVE src0_sel:DWORD
	v_cvt_f16_f32_sdwa v135, v205 dst_sel:WORD_1 dst_unused:UNUSED_PRESERVE src0_sel:DWORD
	v_cvt_f16_f32_sdwa v136, v207 dst_sel:WORD_1 dst_unused:UNUSED_PRESERVE src0_sel:DWORD
	v_cvt_f16_f32_sdwa v137, v209 dst_sel:WORD_1 dst_unused:UNUSED_PRESERVE src0_sel:DWORD
	v_cvt_f16_f32_sdwa v138, v211 dst_sel:WORD_1 dst_unused:UNUSED_PRESERVE src0_sel:DWORD
	v_cvt_f16_f32_sdwa v139, v213 dst_sel:WORD_1 dst_unused:UNUSED_PRESERVE src0_sel:DWORD
	s_nop 0
	global_store_dwordx4 v187, v[132:135], s[42:43] offset:-4096 sc1
	global_store_dwordx4 v187, v[136:139], s[42:43] offset:-3072 sc1
	v_pk_mul_f32 v[140:141], v[198:199], v[198:199]
	v_pk_fma_f32 v[140:141], v[200:201], v[200:201], v[140:141]
	v_pk_fma_f32 v[140:141], v[202:203], v[202:203], v[140:141]
	v_pk_fma_f32 v[140:141], v[204:205], v[204:205], v[140:141]
	v_pk_fma_f32 v[140:141], v[206:207], v[206:207], v[140:141]
	v_pk_fma_f32 v[140:141], v[208:209], v[208:209], v[140:141]
	v_pk_fma_f32 v[140:141], v[210:211], v[210:211], v[140:141]
	v_pk_fma_f32 v[140:141], v[212:213], v[212:213], v[140:141]
	v_add_f32_e32 v140, v140, v141
	s_nop 1
	v_add_f32_dpp v140, v140, v140 quad_perm:[1,0,3,2] row_mask:0xf bank_mask:0xf
	s_nop 1
	v_add_f32_dpp v140, v140, v140 quad_perm:[2,3,0,1] row_mask:0xf bank_mask:0xf
	s_nop 1
	v_add_f32_dpp v140, v140, v140 row_ror:4 row_mask:0xf bank_mask:0xf
	s_nop 1
	v_add_f32_dpp v140, v140, v140 row_ror:8 row_mask:0xf bank_mask:0xf
	s_nop 1
	v_add_f32_dpp v140, v140, v140 row_bcast:15 row_mask:0xa bank_mask:0xf
	s_nop 1
	v_add_f32_dpp v140, v140, v140 row_bcast:31 row_mask:0xc bank_mask:0xf
	s_nop 1
	v_fmamk_f32 v140, v140, 0x3a800000, v224
	v_rsq_f32_e32 v140, v140
	s_nop 0
	v_readlane_b32 s6, v140, 63
	s_nop 1
	v_pk_mul_f32 v[198:199], v[198:199], s[6:7] op_sel_hi:[1,0]
	v_pk_mul_f32 v[200:201], v[200:201], s[6:7] op_sel_hi:[1,0]
	v_pk_mul_f32 v[202:203], v[202:203], s[6:7] op_sel_hi:[1,0]
	v_pk_mul_f32 v[204:205], v[204:205], s[6:7] op_sel_hi:[1,0]
	v_pk_mul_f32 v[206:207], v[206:207], s[6:7] op_sel_hi:[1,0]
	v_pk_mul_f32 v[208:209], v[208:209], s[6:7] op_sel_hi:[1,0]
	v_pk_mul_f32 v[210:211], v[210:211], s[6:7] op_sel_hi:[1,0]
	v_pk_mul_f32 v[212:213], v[212:213], s[6:7] op_sel_hi:[1,0]
	v_pk_mul_f32 v[198:199], v[16:17], v[198:199]
	v_pk_mul_f32 v[200:201], v[18:19], v[200:201]
	v_pk_mul_f32 v[202:203], v[20:21], v[202:203]
	v_pk_mul_f32 v[204:205], v[22:23], v[204:205]
	v_pk_mul_f32 v[206:207], v[24:25], v[206:207]
	v_pk_mul_f32 v[208:209], v[26:27], v[208:209]
	v_pk_mul_f32 v[210:211], v[28:29], v[210:211]
	v_pk_mul_f32 v[212:213], v[30:31], v[212:213]
	v_pk_fma_f32 v[198:199], v[32:33], v[198:199], v[48:49]
	v_pk_fma_f32 v[200:201], v[34:35], v[200:201], v[50:51]
	v_pk_fma_f32 v[202:203], v[36:37], v[202:203], v[52:53]
	v_pk_fma_f32 v[204:205], v[38:39], v[204:205], v[54:55]
	v_pk_fma_f32 v[206:207], v[40:41], v[206:207], v[56:57]
	v_pk_fma_f32 v[208:209], v[42:43], v[208:209], v[58:59]
	v_pk_fma_f32 v[210:211], v[44:45], v[210:211], v[60:61]
	v_pk_fma_f32 v[212:213], v[46:47], v[212:213], v[62:63]
	v_cvt_pk_bf16_f32 v230, v198, v199
	v_cvt_pk_bf16_f32 v231, v200, v201
	v_cvt_pk_bf16_f32 v232, v202, v203
	v_cvt_pk_bf16_f32 v233, v204, v205
	v_cvt_pk_bf16_f32 v234, v206, v207
	v_cvt_pk_bf16_f32 v235, v208, v209
	v_cvt_pk_bf16_f32 v236, v210, v211
	v_cvt_pk_bf16_f32 v237, v212, v213
	global_store_dwordx4 v187, v[230:233], s[44:45] offset:-4096 sc1
	global_store_dwordx4 v187, v[234:237], s[44:45] offset:-3072 sc1
	s_waitcnt vmcnt(24)
	v_lshlrev_b32_e32 v116, 16, v156
	v_and_b32_e32 v117, 0xffff0000, v156
	v_lshlrev_b32_e32 v118, 16, v157
	v_and_b32_e32 v119, 0xffff0000, v157
	v_lshlrev_b32_e32 v120, 16, v158
	v_and_b32_e32 v121, 0xffff0000, v158
	v_lshlrev_b32_e32 v122, 16, v159
	v_and_b32_e32 v123, 0xffff0000, v159
	v_lshlrev_b32_e32 v124, 16, v160
	v_and_b32_e32 v125, 0xffff0000, v160
	v_lshlrev_b32_e32 v126, 16, v161
	v_and_b32_e32 v127, 0xffff0000, v161
	v_lshlrev_b32_e32 v128, 16, v162
	v_and_b32_e32 v129, 0xffff0000, v162
	v_lshlrev_b32_e32 v130, 16, v163
	v_and_b32_e32 v131, 0xffff0000, v163
	v_cvt_f32_f16_e32 v198, v72
	v_cvt_f32_f16_sdwa v199, v72 dst_sel:DWORD dst_unused:UNUSED_PAD src0_sel:WORD_1
	v_cvt_f32_f16_e32 v200, v73
	v_cvt_f32_f16_sdwa v201, v73 dst_sel:DWORD dst_unused:UNUSED_PAD src0_sel:WORD_1
	v_cvt_f32_f16_e32 v202, v74
	v_cvt_f32_f16_sdwa v203, v74 dst_sel:DWORD dst_unused:UNUSED_PAD src0_sel:WORD_1
	v_cvt_f32_f16_e32 v204, v75
	v_cvt_f32_f16_sdwa v205, v75 dst_sel:DWORD dst_unused:UNUSED_PAD src0_sel:WORD_1
	v_cvt_f32_f16_e32 v206, v76
	v_cvt_f32_f16_sdwa v207, v76 dst_sel:DWORD dst_unused:UNUSED_PAD src0_sel:WORD_1
	v_cvt_f32_f16_e32 v208, v77
	v_cvt_f32_f16_sdwa v209, v77 dst_sel:DWORD dst_unused:UNUSED_PAD src0_sel:WORD_1
	v_cvt_f32_f16_e32 v210, v78
	v_cvt_f32_f16_sdwa v211, v78 dst_sel:DWORD dst_unused:UNUSED_PAD src0_sel:WORD_1
	v_cvt_f32_f16_e32 v212, v79
	v_cvt_f32_f16_sdwa v213, v79 dst_sel:DWORD dst_unused:UNUSED_PAD src0_sel:WORD_1
	v_pk_mul_f32 v[140:141], v[116:117], v[116:117]
	v_pk_fma_f32 v[140:141], v[118:119], v[118:119], v[140:141]
	v_pk_fma_f32 v[140:141], v[120:121], v[120:121], v[140:141]
; template <int R, bool SRCB> ...
;     ...
;         for (int r = 0; r < R; ++r) {
;             f32x4 y[2][2]; float ss = 0.f;
; #pragma unroll
;             for (int j = 0; j < 2; ++j) { const u32x4 t = yr[r][j];
;                 y[j][0] = (f32x4){bf_lo(t.x), bf_hi(t.x), bf_lo(t.y), bf_hi(t.y)}; y[j][1] = (f32x4){bf_lo(t.z), bf_hi(t.z), bf_lo(t.w), bf_hi(t.w)};
;                 if (R == 1 && YP) {
; #pragma unroll
;                     for (int k = 0; k < 2; ++k) { const float* pp = YP + (size_t)(row0 - M_LAT) * DM + 8 * lane + 512 * j + 4 * k; f32x4 s = *(const f32x4*)pp;
; #pragma unroll
;                         for (int q = 1; q < pg8::NSL; ++q) s = s + *(const f32x4*)(pp + (size_t)q * 2048 * DM);
;                         y[j][k] = s; } }
; #pragma unroll
;                 for (int k = 0; k < 2; ++k) ss += (y[j][k][0] * y[j][k][0] + y[j][k][1] * y[j][k][1]) + (y[j][k][2] * y[j][k][2] + y[j][k][3] * y[j][k][3]); }
;             const float rr = __builtin_amdgcn_rsqf(wave_sum(ss) * (1.0f / DM) + 1e-6f) * w;
; #pragma unroll
;             for (int j = 0; j < 2; ++j)
; #pragma unroll
;                 for (int k = 0; k < 2; ++k) h[r][j][k] = h[r][j][k] + gg[j][k] * (y[j][k] * rr);
;         }
;     }
; #pragma unroll
;     for (int r = 0; r < R; ++r)
; #pragma unroll
;         for (int j = 0; j < 2; ++j) { const int c = 8 * lane + 512 * j;
;             if (final_out) { *(f32x4*)(final_out + (size_t)(row0 + r) * DM + c) = h[r][j][0]; *(f32x4*)(final_out + (size_t)(row0 + r) * DM + c + 4) = h[r][j][1]; }
;             else { u32x4 t; t.x = pkh2(h[r][j][0][0], h[r][j][0][1]); t.y = pkh2(h[r][j][0][2], h[r][j][0][3]); t.z = pkh2(h[r][j][1][0], h[r][j][1][1]); t.w = pkh2(h[r][j][1][2], h[r][j][1][3]);
;                 *(u32x4*)(hout + (size_t)(row0 + r) * DM + c) = t; } }
;     if (U) {
;         f32x4 gp[2][2], sc1[2][2], sh[2][2];
; #pragma unroll
;         for (int j = 0; j < 2; ++j)
; #pragma unroll
;             for (int k = 0; k < 2; ++k) { const int c = 8 * lane + 512 * j + 4 * k; gp[j][k] = *(const f32x4*)(gpre + c); sc1[j][k] = *(const f32x4*)(scale + (size_t)mrow * 9216 + c) + 1.0f; sh[j][k] = *(const f32x4*)(shift + (size_t)mrow * 9216 + c); }
; #pragma unroll
;         for (int r = 0; r < R; ++r) {
;             float ss = 0.f;
; #pragma unroll
;             for (int j = 0; j < 2; ++j)
; #pragma unroll
	v_pk_fma_f32 v[140:141], v[122:123], v[122:123], v[140:141]
	v_pk_fma_f32 v[140:141], v[124:125], v[124:125], v[140:141]
	v_pk_fma_f32 v[140:141], v[126:127], v[126:127], v[140:141]
	v_pk_fma_f32 v[140:141], v[128:129], v[128:129], v[140:141]
	v_pk_fma_f32 v[140:141], v[130:131], v[130:131], v[140:141]
	v_add_f32_e32 v140, v140, v141
	s_nop 1
	v_add_f32_dpp v140, v140, v140 quad_perm:[1,0,3,2] row_mask:0xf bank_mask:0xf
	s_nop 1
	v_add_f32_dpp v140, v140, v140 quad_perm:[2,3,0,1] row_mask:0xf bank_mask:0xf
	s_nop 1
	v_add_f32_dpp v140, v140, v140 row_ror:4 row_mask:0xf bank_mask:0xf
	s_nop 1
	v_add_f32_dpp v140, v140, v140 row_ror:8 row_mask:0xf bank_mask:0xf
	s_nop 1
	v_add_f32_dpp v140, v140, v140 row_bcast:15 row_mask:0xa bank_mask:0xf
	s_nop 1
	v_add_f32_dpp v140, v140, v140 row_bcast:31 row_mask:0xc bank_mask:0xf
	s_nop 1
	v_fmamk_f32 v140, v140, 0x3a800000, v224
	v_rsq_f32_e32 v140, v140
	s_nop 0
	v_mul_f32_e32 v140, v144, v140
	s_nop 0
	v_readlane_b32 s4, v140, 63
	s_nop 1
	v_pk_mul_f32 v[116:117], v[116:117], s[4:5] op_sel_hi:[1,0]
	v_pk_mul_f32 v[118:119], v[118:119], s[4:5] op_sel_hi:[1,0]
	v_pk_mul_f32 v[120:121], v[120:121], s[4:5] op_sel_hi:[1,0]
	v_pk_mul_f32 v[122:123], v[122:123], s[4:5] op_sel_hi:[1,0]
	v_pk_mul_f32 v[124:125], v[124:125], s[4:5] op_sel_hi:[1,0]
	v_pk_mul_f32 v[126:127], v[126:127], s[4:5] op_sel_hi:[1,0]
	v_pk_mul_f32 v[128:129], v[128:129], s[4:5] op_sel_hi:[1,0]
	v_pk_mul_f32 v[130:131], v[130:131], s[4:5] op_sel_hi:[1,0]
	v_pk_fma_f32 v[198:199], v[0:1], v[116:117], v[198:199]
	v_pk_fma_f32 v[200:201], v[2:3], v[118:119], v[200:201]
	v_pk_fma_f32 v[202:203], v[4:5], v[120:121], v[202:203]
	v_pk_fma_f32 v[204:205], v[6:7], v[122:123], v[204:205]
	v_pk_fma_f32 v[206:207], v[8:9], v[124:125], v[206:207]
	v_pk_fma_f32 v[208:209], v[10:11], v[126:127], v[208:209]
	v_pk_fma_f32 v[210:211], v[12:13], v[128:129], v[210:211]
	v_pk_fma_f32 v[212:213], v[14:15], v[130:131], v[212:213]
	v_cvt_f16_f32_e32 v132, v198
	v_cvt_f16_f32_e32 v133, v200
	v_cvt_f16_f32_e32 v134, v202
	v_cvt_f16_f32_e32 v135, v204
	v_cvt_f16_f32_e32 v136, v206
	v_cvt_f16_f32_e32 v137, v208
	v_cvt_f16_f32_e32 v138, v210
	v_cvt_f16_f32_e32 v139, v212
	v_cvt_f16_f32_sdwa v132, v199 dst_sel:WORD_1 dst_unused:UNUSED_PRESERVE src0_sel:DWORD
	v_cvt_f16_f32_sdwa v133, v201 dst_sel:WORD_1 dst_unused:UNUSED_PRESERVE src0_sel:DWORD
	v_cvt_f16_f32_sdwa v134, v203 dst_sel:WORD_1 dst_unused:UNUSED_PRESERVE src0_sel:DWORD
	v_cvt_f16_f32_sdwa v135, v205 dst_sel:WORD_1 dst_unused:UNUSED_PRESERVE src0_sel:DWORD
	v_cvt_f16_f32_sdwa v136, v207 dst_sel:WORD_1 dst_unused:UNUSED_PRESERVE src0_sel:DWORD
	v_cvt_f16_f32_sdwa v137, v209 dst_sel:WORD_1 dst_unused:UNUSED_PRESERVE src0_sel:DWORD
	v_cvt_f16_f32_sdwa v138, v211 dst_sel:WORD_1 dst_unused:UNUSED_PRESERVE src0_sel:DWORD
	v_cvt_f16_f32_sdwa v139, v213 dst_sel:WORD_1 dst_unused:UNUSED_PRESERVE src0_sel:DWORD
	s_nop 0
	global_store_dwordx4 v187, v[132:135], s[42:43] offset:-2048 sc1
	global_store_dwordx4 v187, v[136:139], s[42:43] offset:-1024 sc1
	v_pk_mul_f32 v[140:141], v[198:199], v[198:199]
	v_pk_fma_f32 v[140:141], v[200:201], v[200:201], v[140:141]
	v_pk_fma_f32 v[140:141], v[202:203], v[202:203], v[140:141]
	v_pk_fma_f32 v[140:141], v[204:205], v[204:205], v[140:141]
	v_pk_fma_f32 v[140:141], v[206:207], v[206:207], v[140:141]
	v_pk_fma_f32 v[140:141], v[208:209], v[208:209], v[140:141]
	v_pk_fma_f32 v[140:141], v[210:211], v[210:211], v[140:141]
	v_pk_fma_f32 v[140:141], v[212:213], v[212:213], v[140:141]
	v_add_f32_e32 v140, v140, v141
	s_nop 1
	v_add_f32_dpp v140, v140, v140 quad_perm:[1,0,3,2] row_mask:0xf bank_mask:0xf
	s_nop 1
	v_add_f32_dpp v140, v140, v140 quad_perm:[2,3,0,1] row_mask:0xf bank_mask:0xf
	s_nop 1
	v_add_f32_dpp v140, v140, v140 row_ror:4 row_mask:0xf bank_mask:0xf
	s_nop 1
	v_add_f32_dpp v140, v140, v140 row_ror:8 row_mask:0xf bank_mask:0xf
	s_nop 1
	v_add_f32_dpp v140, v140, v140 row_bcast:15 row_mask:0xa bank_mask:0xf
	s_nop 1
	v_add_f32_dpp v140, v140, v140 row_bcast:31 row_mask:0xc bank_mask:0xf
	s_nop 1
	v_fmamk_f32 v140, v140, 0x3a800000, v224
	v_rsq_f32_e32 v140, v140
	s_nop 0
	v_readlane_b32 s6, v140, 63
	s_nop 1
	v_pk_mul_f32 v[198:199], v[198:199], s[6:7] op_sel_hi:[1,0]
	v_pk_mul_f32 v[200:201], v[200:201], s[6:7] op_sel_hi:[1,0]
	v_pk_mul_f32 v[202:203], v[202:203], s[6:7] op_sel_hi:[1,0]
	v_pk_mul_f32 v[204:205], v[204:205], s[6:7] op_sel_hi:[1,0]
	v_pk_mul_f32 v[206:207], v[206:207], s[6:7] op_sel_hi:[1,0]
	v_pk_mul_f32 v[208:209], v[208:209], s[6:7] op_sel_hi:[1,0]
	v_pk_mul_f32 v[210:211], v[210:211], s[6:7] op_sel_hi:[1,0]
	v_pk_mul_f32 v[212:213], v[212:213], s[6:7] op_sel_hi:[1,0]
	v_pk_mul_f32 v[198:199], v[16:17], v[198:199]
	v_pk_mul_f32 v[200:201], v[18:19], v[200:201]
	v_pk_mul_f32 v[202:203], v[20:21], v[202:203]
	v_pk_mul_f32 v[204:205], v[22:23], v[204:205]
	v_pk_mul_f32 v[206:207], v[24:25], v[206:207]
	v_pk_mul_f32 v[208:209], v[26:27], v[208:209]
	v_pk_mul_f32 v[210:211], v[28:29], v[210:211]
	v_pk_mul_f32 v[212:213], v[30:31], v[212:213]
	v_pk_fma_f32 v[198:199], v[32:33], v[198:199], v[48:49]
	v_pk_fma_f32 v[200:201], v[34:35], v[200:201], v[50:51]
	v_pk_fma_f32 v[202:203], v[36:37], v[202:203], v[52:53]
	v_pk_fma_f32 v[204:205], v[38:39], v[204:205], v[54:55]
	v_pk_fma_f32 v[206:207], v[40:41], v[206:207], v[56:57]
	v_pk_fma_f32 v[208:209], v[42:43], v[208:209], v[58:59]
	v_pk_fma_f32 v[210:211], v[44:45], v[210:211], v[60:61]
	v_pk_fma_f32 v[212:213], v[46:47], v[212:213], v[62:63]
	v_cvt_pk_bf16_f32 v230, v198, v199
	v_cvt_pk_bf16_f32 v231, v200, v201
	v_cvt_pk_bf16_f32 v232, v202, v203
	v_cvt_pk_bf16_f32 v233, v204, v205
	v_cvt_pk_bf16_f32 v234, v206, v207
	v_cvt_pk_bf16_f32 v235, v208, v209
	v_cvt_pk_bf16_f32 v236, v210, v211
	v_cvt_pk_bf16_f32 v237, v212, v213
	global_store_dwordx4 v187, v[230:233], s[44:45] offset:-2048 sc1
	global_store_dwordx4 v187, v[234:237], s[44:45] offset:-1024 sc1
	s_waitcnt vmcnt(20)
; template <int R, bool SRCB> ...
;     ...
;         for (int r = 0; r < R; ++r) {
;             f32x4 y[2][2]; float ss = 0.f;
; #pragma unroll
;             for (int j = 0; j < 2; ++j) { const u32x4 t = yr[r][j];
;                 y[j][0] = (f32x4){bf_lo(t.x), bf_hi(t.x), bf_lo(t.y), bf_hi(t.y)}; y[j][1] = (f32x4){bf_lo(t.z), bf_hi(t.z), bf_lo(t.w), bf_hi(t.w)};
;                 if (R == 1 && YP) {
; #pragma unroll
;                     for (int k = 0; k < 2; ++k) { const float* pp = YP + (size_t)(row0 - M_LAT) * DM + 8 * lane + 512 * j + 4 * k; f32x4 s = *(const f32x4*)pp;
; #pragma unroll
;                         for (int q = 1; q < pg8::NSL; ++q) s = s + *(const f32x4*)(pp + (size_t)q * 2048 * DM);
;                         y[j][k] = s; } }
; #pragma unroll
;                 for (int k = 0; k < 2; ++k) ss += (y[j][k][0] * y[j][k][0] + y[j][k][1] * y[j][k][1]) + (y[j][k][2] * y[j][k][2] + y[j][k][3] * y[j][k][3]); }
;             const float rr = __builtin_amdgcn_rsqf(wave_sum(ss) * (1.0f / DM) + 1e-6f) * w;
; #pragma unroll
;             for (int j = 0; j < 2; ++j)
; #pragma unroll
;                 for (int k = 0; k < 2; ++k) h[r][j][k] = h[r][j][k] + gg[j][k] * (y[j][k] * rr);
;         }
;     }
; #pragma unroll
;     for (int r = 0; r < R; ++r)
; #pragma unroll
;         for (int j = 0; j < 2; ++j) { const int c = 8 * lane + 512 * j;
;             if (final_out) { *(f32x4*)(final_out + (size_t)(row0 + r) * DM + c) = h[r][j][0]; *(f32x4*)(final_out + (size_t)(row0 + r) * DM + c + 4) = h[r][j][1]; }
;             else { u32x4 t; t.x = pkh2(h[r][j][0][0], h[r][j][0][1]); t.y = pkh2(h[r][j][0][2], h[r][j][0][3]); t.z = pkh2(h[r][j][1][0], h[r][j][1][1]); t.w = pkh2(h[r][j][1][2], h[r][j][1][3]);
;                 *(u32x4*)(hout + (size_t)(row0 + r) * DM + c) = t; } }
;     if (U) {
;         f32x4 gp[2][2], sc1[2][2], sh[2][2];
; #pragma unroll
;         for (int j = 0; j < 2; ++j)
; #pragma unroll
;             for (int k = 0; k < 2; ++k) { const int c = 8 * lane + 512 * j + 4 * k; gp[j][k] = *(const f32x4*)(gpre + c); sc1[j][k] = *(const f32x4*)(scale + (size_t)mrow * 9216 + c) + 1.0f; sh[j][k] = *(const f32x4*)(shift + (size_t)mrow * 9216 + c); }
; #pragma unroll
;         for (int r = 0; r < R; ++r) {
;             float ss = 0.f;
; #pragma unroll
;             for (int j = 0; j < 2; ++j)
; #pragma unroll
	v_lshlrev_b32_e32 v116, 16, v164
	v_and_b32_e32 v117, 0xffff0000, v164
	v_lshlrev_b32_e32 v118, 16, v165
	v_and_b32_e32 v119, 0xffff0000, v165
	v_lshlrev_b32_e32 v120, 16, v166
	v_and_b32_e32 v121, 0xffff0000, v166
	v_lshlrev_b32_e32 v122, 16, v167
	v_and_b32_e32 v123, 0xffff0000, v167
	v_lshlrev_b32_e32 v124, 16, v168
	v_and_b32_e32 v125, 0xffff0000, v168
	v_lshlrev_b32_e32 v126, 16, v169
	v_and_b32_e32 v127, 0xffff0000, v169
	v_lshlrev_b32_e32 v128, 16, v170
	v_and_b32_e32 v129, 0xffff0000, v170
	v_lshlrev_b32_e32 v130, 16, v171
	v_and_b32_e32 v131, 0xffff0000, v171
	v_cvt_f32_f16_e32 v198, v80
	v_cvt_f32_f16_sdwa v199, v80 dst_sel:DWORD dst_unused:UNUSED_PAD src0_sel:WORD_1
	v_cvt_f32_f16_e32 v200, v81
	v_cvt_f32_f16_sdwa v201, v81 dst_sel:DWORD dst_unused:UNUSED_PAD src0_sel:WORD_1
	v_cvt_f32_f16_e32 v202, v82
	v_cvt_f32_f16_sdwa v203, v82 dst_sel:DWORD dst_unused:UNUSED_PAD src0_sel:WORD_1
	v_cvt_f32_f16_e32 v204, v83
	v_cvt_f32_f16_sdwa v205, v83 dst_sel:DWORD dst_unused:UNUSED_PAD src0_sel:WORD_1
	v_cvt_f32_f16_e32 v206, v84
	v_cvt_f32_f16_sdwa v207, v84 dst_sel:DWORD dst_unused:UNUSED_PAD src0_sel:WORD_1
	v_cvt_f32_f16_e32 v208, v85
	v_cvt_f32_f16_sdwa v209, v85 dst_sel:DWORD dst_unused:UNUSED_PAD src0_sel:WORD_1
	v_cvt_f32_f16_e32 v210, v86
	v_cvt_f32_f16_sdwa v211, v86 dst_sel:DWORD dst_unused:UNUSED_PAD src0_sel:WORD_1
	v_cvt_f32_f16_e32 v212, v87
	v_cvt_f32_f16_sdwa v213, v87 dst_sel:DWORD dst_unused:UNUSED_PAD src0_sel:WORD_1
	v_pk_mul_f32 v[140:141], v[116:117], v[116:117]
	v_pk_fma_f32 v[140:141], v[118:119], v[118:119], v[140:141]
	v_pk_fma_f32 v[140:141], v[120:121], v[120:121], v[140:141]
	v_pk_fma_f32 v[140:141], v[122:123], v[122:123], v[140:141]
	v_pk_fma_f32 v[140:141], v[124:125], v[124:125], v[140:141]
	v_pk_fma_f32 v[140:141], v[126:127], v[126:127], v[140:141]
	v_pk_fma_f32 v[140:141], v[128:129], v[128:129], v[140:141]
	v_pk_fma_f32 v[140:141], v[130:131], v[130:131], v[140:141]
	v_add_f32_e32 v140, v140, v141
	s_nop 1
	v_add_f32_dpp v140, v140, v140 quad_perm:[1,0,3,2] row_mask:0xf bank_mask:0xf
	s_nop 1
	v_add_f32_dpp v140, v140, v140 quad_perm:[2,3,0,1] row_mask:0xf bank_mask:0xf
	s_nop 1
	v_add_f32_dpp v140, v140, v140 row_ror:4 row_mask:0xf bank_mask:0xf
	s_nop 1
	v_add_f32_dpp v140, v140, v140 row_ror:8 row_mask:0xf bank_mask:0xf
	s_nop 1
	v_add_f32_dpp v140, v140, v140 row_bcast:15 row_mask:0xa bank_mask:0xf
	s_nop 1
	v_add_f32_dpp v140, v140, v140 row_bcast:31 row_mask:0xc bank_mask:0xf
	s_nop 1
	v_fmamk_f32 v140, v140, 0x3a800000, v224
	v_rsq_f32_e32 v140, v140
	s_nop 0
	v_mul_f32_e32 v140, v144, v140
	s_nop 0
	v_readlane_b32 s4, v140, 63
	s_nop 1
	v_pk_mul_f32 v[116:117], v[116:117], s[4:5] op_sel_hi:[1,0]
	v_pk_mul_f32 v[118:119], v[118:119], s[4:5] op_sel_hi:[1,0]
	v_pk_mul_f32 v[120:121], v[120:121], s[4:5] op_sel_hi:[1,0]
	v_pk_mul_f32 v[122:123], v[122:123], s[4:5] op_sel_hi:[1,0]
	v_pk_mul_f32 v[124:125], v[124:125], s[4:5] op_sel_hi:[1,0]
	v_pk_mul_f32 v[126:127], v[126:127], s[4:5] op_sel_hi:[1,0]
	v_pk_mul_f32 v[128:129], v[128:129], s[4:5] op_sel_hi:[1,0]
	v_pk_mul_f32 v[130:131], v[130:131], s[4:5] op_sel_hi:[1,0]
	v_pk_fma_f32 v[198:199], v[0:1], v[116:117], v[198:199]
	v_pk_fma_f32 v[200:201], v[2:3], v[118:119], v[200:201]
	v_pk_fma_f32 v[202:203], v[4:5], v[120:121], v[202:203]
	v_pk_fma_f32 v[204:205], v[6:7], v[122:123], v[204:205]
	v_pk_fma_f32 v[206:207], v[8:9], v[124:125], v[206:207]
	v_pk_fma_f32 v[208:209], v[10:11], v[126:127], v[208:209]
	v_pk_fma_f32 v[210:211], v[12:13], v[128:129], v[210:211]
	v_pk_fma_f32 v[212:213], v[14:15], v[130:131], v[212:213]
	v_cvt_f16_f32_e32 v132, v198
	v_cvt_f16_f32_e32 v133, v200
	v_cvt_f16_f32_e32 v134, v202
	v_cvt_f16_f32_e32 v135, v204
	v_cvt_f16_f32_e32 v136, v206
	v_cvt_f16_f32_e32 v137, v208
	v_cvt_f16_f32_e32 v138, v210
	v_cvt_f16_f32_e32 v139, v212
	v_cvt_f16_f32_sdwa v132, v199 dst_sel:WORD_1 dst_unused:UNUSED_PRESERVE src0_sel:DWORD
	v_cvt_f16_f32_sdwa v133, v201 dst_sel:WORD_1 dst_unused:UNUSED_PRESERVE src0_sel:DWORD
	v_cvt_f16_f32_sdwa v134, v203 dst_sel:WORD_1 dst_unused:UNUSED_PRESERVE src0_sel:DWORD
	v_cvt_f16_f32_sdwa v135, v205 dst_sel:WORD_1 dst_unused:UNUSED_PRESERVE src0_sel:DWORD
	v_cvt_f16_f32_sdwa v136, v207 dst_sel:WORD_1 dst_unused:UNUSED_PRESERVE src0_sel:DWORD
	v_cvt_f16_f32_sdwa v137, v209 dst_sel:WORD_1 dst_unused:UNUSED_PRESERVE src0_sel:DWORD
	v_cvt_f16_f32_sdwa v138, v211 dst_sel:WORD_1 dst_unused:UNUSED_PRESERVE src0_sel:DWORD
	v_cvt_f16_f32_sdwa v139, v213 dst_sel:WORD_1 dst_unused:UNUSED_PRESERVE src0_sel:DWORD
	s_nop 0
	global_store_dwordx4 v187, v[132:135], s[42:43] offset:0 sc1
	global_store_dwordx4 v187, v[136:139], s[42:43] offset:1024 sc1
	v_pk_mul_f32 v[140:141], v[198:199], v[198:199]
	v_pk_fma_f32 v[140:141], v[200:201], v[200:201], v[140:141]
	v_pk_fma_f32 v[140:141], v[202:203], v[202:203], v[140:141]
	v_pk_fma_f32 v[140:141], v[204:205], v[204:205], v[140:141]
	v_pk_fma_f32 v[140:141], v[206:207], v[206:207], v[140:141]
	v_pk_fma_f32 v[140:141], v[208:209], v[208:209], v[140:141]
	v_pk_fma_f32 v[140:141], v[210:211], v[210:211], v[140:141]
	v_pk_fma_f32 v[140:141], v[212:213], v[212:213], v[140:141]
	v_add_f32_e32 v140, v140, v141
	s_nop 1
	v_add_f32_dpp v140, v140, v140 quad_perm:[1,0,3,2] row_mask:0xf bank_mask:0xf
	s_nop 1
	v_add_f32_dpp v140, v140, v140 quad_perm:[2,3,0,1] row_mask:0xf bank_mask:0xf
	s_nop 1
	v_add_f32_dpp v140, v140, v140 row_ror:4 row_mask:0xf bank_mask:0xf
	s_nop 1
	v_add_f32_dpp v140, v140, v140 row_ror:8 row_mask:0xf bank_mask:0xf
	s_nop 1
	v_add_f32_dpp v140, v140, v140 row_bcast:15 row_mask:0xa bank_mask:0xf
	s_nop 1
	v_add_f32_dpp v140, v140, v140 row_bcast:31 row_mask:0xc bank_mask:0xf
; template <int R, bool SRCB> ...
;     ...
;         for (int r = 0; r < R; ++r) {
;             f32x4 y[2][2]; float ss = 0.f;
; #pragma unroll
;             for (int j = 0; j < 2; ++j) { const u32x4 t = yr[r][j];
;                 y[j][0] = (f32x4){bf_lo(t.x), bf_hi(t.x), bf_lo(t.y), bf_hi(t.y)}; y[j][1] = (f32x4){bf_lo(t.z), bf_hi(t.z), bf_lo(t.w), bf_hi(t.w)};
;                 if (R == 1 && YP) {
; #pragma unroll
;                     for (int k = 0; k < 2; ++k) { const float* pp = YP + (size_t)(row0 - M_LAT) * DM + 8 * lane + 512 * j + 4 * k; f32x4 s = *(const f32x4*)pp;
; #pragma unroll
;                         for (int q = 1; q < pg8::NSL; ++q) s = s + *(const f32x4*)(pp + (size_t)q * 2048 * DM);
;                         y[j][k] = s; } }
; #pragma unroll
;                 for (int k = 0; k < 2; ++k) ss += (y[j][k][0] * y[j][k][0] + y[j][k][1] * y[j][k][1]) + (y[j][k][2] * y[j][k][2] + y[j][k][3] * y[j][k][3]); }
;             const float rr = __builtin_amdgcn_rsqf(wave_sum(ss) * (1.0f / DM) + 1e-6f) * w;
; #pragma unroll
;             for (int j = 0; j < 2; ++j)
; #pragma unroll
;                 for (int k = 0; k < 2; ++k) h[r][j][k] = h[r][j][k] + gg[j][k] * (y[j][k] * rr);
;         }
;     }
; #pragma unroll
;     for (int r = 0; r < R; ++r)
; #pragma unroll
;         for (int j = 0; j < 2; ++j) { const int c = 8 * lane + 512 * j;
;             if (final_out) { *(f32x4*)(final_out + (size_t)(row0 + r) * DM + c) = h[r][j][0]; *(f32x4*)(final_out + (size_t)(row0 + r) * DM + c + 4) = h[r][j][1]; }
;             else { u32x4 t; t.x = pkh2(h[r][j][0][0], h[r][j][0][1]); t.y = pkh2(h[r][j][0][2], h[r][j][0][3]); t.z = pkh2(h[r][j][1][0], h[r][j][1][1]); t.w = pkh2(h[r][j][1][2], h[r][j][1][3]);
;                 *(u32x4*)(hout + (size_t)(row0 + r) * DM + c) = t; } }
;     if (U) {
;         f32x4 gp[2][2], sc1[2][2], sh[2][2];
; #pragma unroll
;         for (int j = 0; j < 2; ++j)
; #pragma unroll
;             for (int k = 0; k < 2; ++k) { const int c = 8 * lane + 512 * j + 4 * k; gp[j][k] = *(const f32x4*)(gpre + c); sc1[j][k] = *(const f32x4*)(scale + (size_t)mrow * 9216 + c) + 1.0f; sh[j][k] = *(const f32x4*)(shift + (size_t)mrow * 9216 + c); }
; #pragma unroll
;         for (int r = 0; r < R; ++r) {
;             float ss = 0.f;
; #pragma unroll
;             for (int j = 0; j < 2; ++j)
; #pragma unroll
	s_nop 1
	v_fmamk_f32 v140, v140, 0x3a800000, v224
	v_rsq_f32_e32 v140, v140
	s_nop 0
	v_readlane_b32 s6, v140, 63
	s_nop 1
	v_pk_mul_f32 v[198:199], v[198:199], s[6:7] op_sel_hi:[1,0]
	v_pk_mul_f32 v[200:201], v[200:201], s[6:7] op_sel_hi:[1,0]
	v_pk_mul_f32 v[202:203], v[202:203], s[6:7] op_sel_hi:[1,0]
	v_pk_mul_f32 v[204:205], v[204:205], s[6:7] op_sel_hi:[1,0]
	v_pk_mul_f32 v[206:207], v[206:207], s[6:7] op_sel_hi:[1,0]
	v_pk_mul_f32 v[208:209], v[208:209], s[6:7] op_sel_hi:[1,0]
	v_pk_mul_f32 v[210:211], v[210:211], s[6:7] op_sel_hi:[1,0]
	v_pk_mul_f32 v[212:213], v[212:213], s[6:7] op_sel_hi:[1,0]
	v_pk_mul_f32 v[198:199], v[16:17], v[198:199]
	v_pk_mul_f32 v[200:201], v[18:19], v[200:201]
	v_pk_mul_f32 v[202:203], v[20:21], v[202:203]
	v_pk_mul_f32 v[204:205], v[22:23], v[204:205]
	v_pk_mul_f32 v[206:207], v[24:25], v[206:207]
	v_pk_mul_f32 v[208:209], v[26:27], v[208:209]
	v_pk_mul_f32 v[210:211], v[28:29], v[210:211]
	v_pk_mul_f32 v[212:213], v[30:31], v[212:213]
	v_pk_fma_f32 v[198:199], v[32:33], v[198:199], v[48:49]
	v_pk_fma_f32 v[200:201], v[34:35], v[200:201], v[50:51]
	v_pk_fma_f32 v[202:203], v[36:37], v[202:203], v[52:53]
	v_pk_fma_f32 v[204:205], v[38:39], v[204:205], v[54:55]
	v_pk_fma_f32 v[206:207], v[40:41], v[206:207], v[56:57]
	v_pk_fma_f32 v[208:209], v[42:43], v[208:209], v[58:59]
	v_pk_fma_f32 v[210:211], v[44:45], v[210:211], v[60:61]
	v_pk_fma_f32 v[212:213], v[46:47], v[212:213], v[62:63]
	v_cvt_pk_bf16_f32 v230, v198, v199
	v_cvt_pk_bf16_f32 v231, v200, v201
	v_cvt_pk_bf16_f32 v232, v202, v203
	v_cvt_pk_bf16_f32 v233, v204, v205
	v_cvt_pk_bf16_f32 v234, v206, v207
	v_cvt_pk_bf16_f32 v235, v208, v209
	v_cvt_pk_bf16_f32 v236, v210, v211
	v_cvt_pk_bf16_f32 v237, v212, v213
	global_store_dwordx4 v187, v[230:233], s[44:45] offset:0 sc1
	global_store_dwordx4 v187, v[234:237], s[44:45] offset:1024 sc1
	s_waitcnt vmcnt(16)
	v_lshlrev_b32_e32 v116, 16, v172
	v_and_b32_e32 v117, 0xffff0000, v172
	v_lshlrev_b32_e32 v118, 16, v173
	v_and_b32_e32 v119, 0xffff0000, v173
	v_lshlrev_b32_e32 v120, 16, v174
	v_and_b32_e32 v121, 0xffff0000, v174
	v_lshlrev_b32_e32 v122, 16, v175
	v_and_b32_e32 v123, 0xffff0000, v175
	v_lshlrev_b32_e32 v124, 16, v176
	v_and_b32_e32 v125, 0xffff0000, v176
	v_lshlrev_b32_e32 v126, 16, v177
	v_and_b32_e32 v127, 0xffff0000, v177
	v_lshlrev_b32_e32 v128, 16, v178
	v_and_b32_e32 v129, 0xffff0000, v178
	v_lshlrev_b32_e32 v130, 16, v179
	v_and_b32_e32 v131, 0xffff0000, v179
	v_cvt_f32_f16_e32 v198, v88
	v_cvt_f32_f16_sdwa v199, v88 dst_sel:DWORD dst_unused:UNUSED_PAD src0_sel:WORD_1
	v_cvt_f32_f16_e32 v200, v89
	v_cvt_f32_f16_sdwa v201, v89 dst_sel:DWORD dst_unused:UNUSED_PAD src0_sel:WORD_1
	v_cvt_f32_f16_e32 v202, v90
	v_cvt_f32_f16_sdwa v203, v90 dst_sel:DWORD dst_unused:UNUSED_PAD src0_sel:WORD_1
	v_cvt_f32_f16_e32 v204, v91
	v_cvt_f32_f16_sdwa v205, v91 dst_sel:DWORD dst_unused:UNUSED_PAD src0_sel:WORD_1
	v_cvt_f32_f16_e32 v206, v92
	v_cvt_f32_f16_sdwa v207, v92 dst_sel:DWORD dst_unused:UNUSED_PAD src0_sel:WORD_1
	v_cvt_f32_f16_e32 v208, v93
	v_cvt_f32_f16_sdwa v209, v93 dst_sel:DWORD dst_unused:UNUSED_PAD src0_sel:WORD_1
	v_cvt_f32_f16_e32 v210, v94
	v_cvt_f32_f16_sdwa v211, v94 dst_sel:DWORD dst_unused:UNUSED_PAD src0_sel:WORD_1
	v_cvt_f32_f16_e32 v212, v95
	v_cvt_f32_f16_sdwa v213, v95 dst_sel:DWORD dst_unused:UNUSED_PAD src0_sel:WORD_1
	v_pk_mul_f32 v[140:141], v[116:117], v[116:117]
	v_pk_fma_f32 v[140:141], v[118:119], v[118:119], v[140:141]
	v_pk_fma_f32 v[140:141], v[120:121], v[120:121], v[140:141]
	v_pk_fma_f32 v[140:141], v[122:123], v[122:123], v[140:141]
	v_pk_fma_f32 v[140:141], v[124:125], v[124:125], v[140:141]
	v_pk_fma_f32 v[140:141], v[126:127], v[126:127], v[140:141]
	v_pk_fma_f32 v[140:141], v[128:129], v[128:129], v[140:141]
	v_pk_fma_f32 v[140:141], v[130:131], v[130:131], v[140:141]
	v_add_f32_e32 v140, v140, v141
	s_nop 1
	v_add_f32_dpp v140, v140, v140 quad_perm:[1,0,3,2] row_mask:0xf bank_mask:0xf
	s_nop 1
	v_add_f32_dpp v140, v140, v140 quad_perm:[2,3,0,1] row_mask:0xf bank_mask:0xf
	s_nop 1
	v_add_f32_dpp v140, v140, v140 row_ror:4 row_mask:0xf bank_mask:0xf
	s_nop 1
	v_add_f32_dpp v140, v140, v140 row_ror:8 row_mask:0xf bank_mask:0xf
	s_nop 1
	v_add_f32_dpp v140, v140, v140 row_bcast:15 row_mask:0xa bank_mask:0xf
	s_nop 1
	v_add_f32_dpp v140, v140, v140 row_bcast:31 row_mask:0xc bank_mask:0xf
	s_nop 1
	v_fmamk_f32 v140, v140, 0x3a800000, v224
	v_rsq_f32_e32 v140, v140
	s_nop 0
	v_mul_f32_e32 v140, v144, v140
	s_nop 0
	v_readlane_b32 s4, v140, 63
	s_nop 1
	v_pk_mul_f32 v[116:117], v[116:117], s[4:5] op_sel_hi:[1,0]
	v_pk_mul_f32 v[118:119], v[118:119], s[4:5] op_sel_hi:[1,0]
	v_pk_mul_f32 v[120:121], v[120:121], s[4:5] op_sel_hi:[1,0]
	v_pk_mul_f32 v[122:123], v[122:123], s[4:5] op_sel_hi:[1,0]
; template <int R, bool SRCB> ...
;     ...
;         for (int r = 0; r < R; ++r) {
;             f32x4 y[2][2]; float ss = 0.f;
; #pragma unroll
;             for (int j = 0; j < 2; ++j) { const u32x4 t = yr[r][j];
;                 y[j][0] = (f32x4){bf_lo(t.x), bf_hi(t.x), bf_lo(t.y), bf_hi(t.y)}; y[j][1] = (f32x4){bf_lo(t.z), bf_hi(t.z), bf_lo(t.w), bf_hi(t.w)};
;                 if (R == 1 && YP) {
; #pragma unroll
;                     for (int k = 0; k < 2; ++k) { const float* pp = YP + (size_t)(row0 - M_LAT) * DM + 8 * lane + 512 * j + 4 * k; f32x4 s = *(const f32x4*)pp;
; #pragma unroll
;                         for (int q = 1; q < pg8::NSL; ++q) s = s + *(const f32x4*)(pp + (size_t)q * 2048 * DM);
;                         y[j][k] = s; } }
; #pragma unroll
;                 for (int k = 0; k < 2; ++k) ss += (y[j][k][0] * y[j][k][0] + y[j][k][1] * y[j][k][1]) + (y[j][k][2] * y[j][k][2] + y[j][k][3] * y[j][k][3]); }
;             const float rr = __builtin_amdgcn_rsqf(wave_sum(ss) * (1.0f / DM) + 1e-6f) * w;
; #pragma unroll
;             for (int j = 0; j < 2; ++j)
; #pragma unroll
;                 for (int k = 0; k < 2; ++k) h[r][j][k] = h[r][j][k] + gg[j][k] * (y[j][k] * rr);
;         }
;     }
; #pragma unroll
;     for (int r = 0; r < R; ++r)
; #pragma unroll
;         for (int j = 0; j < 2; ++j) { const int c = 8 * lane + 512 * j;
;             if (final_out) { *(f32x4*)(final_out + (size_t)(row0 + r) * DM + c) = h[r][j][0]; *(f32x4*)(final_out + (size_t)(row0 + r) * DM + c + 4) = h[r][j][1]; }
;             else { u32x4 t; t.x = pkh2(h[r][j][0][0], h[r][j][0][1]); t.y = pkh2(h[r][j][0][2], h[r][j][0][3]); t.z = pkh2(h[r][j][1][0], h[r][j][1][1]); t.w = pkh2(h[r][j][1][2], h[r][j][1][3]);
;                 *(u32x4*)(hout + (size_t)(row0 + r) * DM + c) = t; } }
;     if (U) {
;         f32x4 gp[2][2], sc1[2][2], sh[2][2];
; #pragma unroll
;         for (int j = 0; j < 2; ++j)
; #pragma unroll
;             for (int k = 0; k < 2; ++k) { const int c = 8 * lane + 512 * j + 4 * k; gp[j][k] = *(const f32x4*)(gpre + c); sc1[j][k] = *(const f32x4*)(scale + (size_t)mrow * 9216 + c) + 1.0f; sh[j][k] = *(const f32x4*)(shift + (size_t)mrow * 9216 + c); }
; #pragma unroll
;         for (int r = 0; r < R; ++r) {
;             float ss = 0.f;
; #pragma unroll
;             for (int j = 0; j < 2; ++j)
; #pragma unroll
	v_pk_mul_f32 v[124:125], v[124:125], s[4:5] op_sel_hi:[1,0]
	v_pk_mul_f32 v[126:127], v[126:127], s[4:5] op_sel_hi:[1,0]
	v_pk_mul_f32 v[128:129], v[128:129], s[4:5] op_sel_hi:[1,0]
	v_pk_mul_f32 v[130:131], v[130:131], s[4:5] op_sel_hi:[1,0]
	v_pk_fma_f32 v[198:199], v[0:1], v[116:117], v[198:199]
	v_pk_fma_f32 v[200:201], v[2:3], v[118:119], v[200:201]
	v_pk_fma_f32 v[202:203], v[4:5], v[120:121], v[202:203]
	v_pk_fma_f32 v[204:205], v[6:7], v[122:123], v[204:205]
	v_pk_fma_f32 v[206:207], v[8:9], v[124:125], v[206:207]
	v_pk_fma_f32 v[208:209], v[10:11], v[126:127], v[208:209]
	v_pk_fma_f32 v[210:211], v[12:13], v[128:129], v[210:211]
	v_pk_fma_f32 v[212:213], v[14:15], v[130:131], v[212:213]
	v_cvt_f16_f32_e32 v132, v198
	v_cvt_f16_f32_e32 v133, v200
	v_cvt_f16_f32_e32 v134, v202
	v_cvt_f16_f32_e32 v135, v204
	v_cvt_f16_f32_e32 v136, v206
	v_cvt_f16_f32_e32 v137, v208
	v_cvt_f16_f32_e32 v138, v210
	v_cvt_f16_f32_e32 v139, v212
	v_cvt_f16_f32_sdwa v132, v199 dst_sel:WORD_1 dst_unused:UNUSED_PRESERVE src0_sel:DWORD
	v_cvt_f16_f32_sdwa v133, v201 dst_sel:WORD_1 dst_unused:UNUSED_PRESERVE src0_sel:DWORD
	v_cvt_f16_f32_sdwa v134, v203 dst_sel:WORD_1 dst_unused:UNUSED_PRESERVE src0_sel:DWORD
	v_cvt_f16_f32_sdwa v135, v205 dst_sel:WORD_1 dst_unused:UNUSED_PRESERVE src0_sel:DWORD
	v_cvt_f16_f32_sdwa v136, v207 dst_sel:WORD_1 dst_unused:UNUSED_PRESERVE src0_sel:DWORD
	v_cvt_f16_f32_sdwa v137, v209 dst_sel:WORD_1 dst_unused:UNUSED_PRESERVE src0_sel:DWORD
	v_cvt_f16_f32_sdwa v138, v211 dst_sel:WORD_1 dst_unused:UNUSED_PRESERVE src0_sel:DWORD
	v_cvt_f16_f32_sdwa v139, v213 dst_sel:WORD_1 dst_unused:UNUSED_PRESERVE src0_sel:DWORD
	s_nop 0
	global_store_dwordx4 v187, v[132:135], s[42:43] offset:2048 sc1
	global_store_dwordx4 v187, v[136:139], s[42:43] offset:3072 sc1
	v_pk_mul_f32 v[140:141], v[198:199], v[198:199]
	v_pk_fma_f32 v[140:141], v[200:201], v[200:201], v[140:141]
	v_pk_fma_f32 v[140:141], v[202:203], v[202:203], v[140:141]
	v_pk_fma_f32 v[140:141], v[204:205], v[204:205], v[140:141]
	v_pk_fma_f32 v[140:141], v[206:207], v[206:207], v[140:141]
	v_pk_fma_f32 v[140:141], v[208:209], v[208:209], v[140:141]
	v_pk_fma_f32 v[140:141], v[210:211], v[210:211], v[140:141]
	v_pk_fma_f32 v[140:141], v[212:213], v[212:213], v[140:141]
	v_add_f32_e32 v140, v140, v141
	s_nop 1
	v_add_f32_dpp v140, v140, v140 quad_perm:[1,0,3,2] row_mask:0xf bank_mask:0xf
	s_nop 1
	v_add_f32_dpp v140, v140, v140 quad_perm:[2,3,0,1] row_mask:0xf bank_mask:0xf
	s_nop 1
	v_add_f32_dpp v140, v140, v140 row_ror:4 row_mask:0xf bank_mask:0xf
	s_nop 1
	v_add_f32_dpp v140, v140, v140 row_ror:8 row_mask:0xf bank_mask:0xf
	s_nop 1
	v_add_f32_dpp v140, v140, v140 row_bcast:15 row_mask:0xa bank_mask:0xf
	s_nop 1
	v_add_f32_dpp v140, v140, v140 row_bcast:31 row_mask:0xc bank_mask:0xf
	s_nop 1
	v_fmamk_f32 v140, v140, 0x3a800000, v224
	v_rsq_f32_e32 v140, v140
	s_nop 0
	v_readlane_b32 s6, v140, 63
	s_nop 1
	v_pk_mul_f32 v[198:199], v[198:199], s[6:7] op_sel_hi:[1,0]
	v_pk_mul_f32 v[200:201], v[200:201], s[6:7] op_sel_hi:[1,0]
	v_pk_mul_f32 v[202:203], v[202:203], s[6:7] op_sel_hi:[1,0]
	v_pk_mul_f32 v[204:205], v[204:205], s[6:7] op_sel_hi:[1,0]
	v_pk_mul_f32 v[206:207], v[206:207], s[6:7] op_sel_hi:[1,0]
	v_pk_mul_f32 v[208:209], v[208:209], s[6:7] op_sel_hi:[1,0]
	v_pk_mul_f32 v[210:211], v[210:211], s[6:7] op_sel_hi:[1,0]
	v_pk_mul_f32 v[212:213], v[212:213], s[6:7] op_sel_hi:[1,0]
	v_pk_mul_f32 v[198:199], v[16:17], v[198:199]
	v_pk_mul_f32 v[200:201], v[18:19], v[200:201]
	v_pk_mul_f32 v[202:203], v[20:21], v[202:203]
	v_pk_mul_f32 v[204:205], v[22:23], v[204:205]
	v_pk_mul_f32 v[206:207], v[24:25], v[206:207]
	v_pk_mul_f32 v[208:209], v[26:27], v[208:209]
	v_pk_mul_f32 v[210:211], v[28:29], v[210:211]
	v_pk_mul_f32 v[212:213], v[30:31], v[212:213]
	v_pk_fma_f32 v[198:199], v[32:33], v[198:199], v[48:49]
	v_pk_fma_f32 v[200:201], v[34:35], v[200:201], v[50:51]
	v_pk_fma_f32 v[202:203], v[36:37], v[202:203], v[52:53]
	v_pk_fma_f32 v[204:205], v[38:39], v[204:205], v[54:55]
	v_pk_fma_f32 v[206:207], v[40:41], v[206:207], v[56:57]
	v_pk_fma_f32 v[208:209], v[42:43], v[208:209], v[58:59]
	v_pk_fma_f32 v[210:211], v[44:45], v[210:211], v[60:61]
	v_pk_fma_f32 v[212:213], v[46:47], v[212:213], v[62:63]
	v_cvt_pk_bf16_f32 v230, v198, v199
	v_cvt_pk_bf16_f32 v231, v200, v201
	v_cvt_pk_bf16_f32 v232, v202, v203
	v_cvt_pk_bf16_f32 v233, v204, v205
	v_cvt_pk_bf16_f32 v234, v206, v207
	v_cvt_pk_bf16_f32 v235, v208, v209
	v_cvt_pk_bf16_f32 v236, v210, v211
	v_cvt_pk_bf16_f32 v237, v212, v213
	global_store_dwordx4 v187, v[230:233], s[44:45] offset:2048 sc1
	global_store_dwordx4 v187, v[234:237], s[44:45] offset:3072 sc1
	s_add_i32 s23, s23, s76
	s_cmpk_lt_i32 s23, 0x800
	s_cbranch_scc1 nrmx_chunk
	s_branch .LBB0_245
	s_nop 0
